# rename-safe N=1 handoff + snake MFMA operand order (one operand changes per step; last pair of each cluster unchanged)
# speedup vs baseline: 1.0051x; 1.0042x over previous
; #define PG8_STAGE(bufoff, gbase, voff) do { _Pragma("unroll") for (int _i = 0; _i < 2; ++_i) \
;         asm volatile("s_mov_b32 m0, %2\n\ts_nop 0\n\tglobal_load_lds_dwordx4 %0, %1" :: "v"((voff)[_i]), "s"((const char*)(gbase)), "s"(ldsbase + (unsigned)(bufoff) + ldsw + (unsigned)_i * 8192u) : "memory", "m0"); } while (0)
; #define PG8_LDA(dst, b, h) do { _Pragma("unroll") for (int m = 0; m < 4; ++m) _Pragma("unroll") for (int k = 0; k < 2; ++k) dst[m][k] = *(const PG8_LAS bf16x8*)(lds + PG8_SA(b, h) + aoff + m * 2048 + k * 1024); } while (0)
; #define PG8_WAIT_V(n) asm volatile("s_waitcnt vmcnt(" #n ")" ::: "memory")
; template <class Epi, class Sched, bool ALIGN_EPI = false, bool SP2 = false>
; __device__ __forceinline__ void gemm_phase(PG8_LAS unsigned char* lds, const Gemm g, const Sched& S, const Epi& E) {
;     ...
;             const bool last = (t == nt - 2);
;             const char* a1 = cA + (size_t)(t + 1) * kstep;
;             const char* a2 = last ? nA : cA + (size_t)(t + 2) * kstep; const char* b2 = last ? nB : cB + (size_t)(t + 2) * kstep;
;             const char* a3 = a2 + kstep; const char* b3 = b2 + kstep;
;             if (last && has_next) S.a_ready(nxt);
;             if constexpr (epi_has_mid<Epi>::value) { if (t == Epi::MID_T) E.mid(acc, cur, wr, wc, fr, fq); }
;             if constexpr (SP2) {
;             PG8_LDB(B0, 0, 0); PG8_LDB(B1, 0, 1); PG8_SCHED; PG8_LDA(At, 0, 0); PG8_STAGE(PG8_SA(1, 1), a1 + hstep, voffA);
;             PG8_WAIT_V(8); PG8_WAIT_L(0); PG8_BAR; PG8_MMA(0, 0, At, B0); PG8_MMA(0, 1, At, B1); PG8_BAR; PG8_SCHED;
;             PG8_LDA(At, 0, 1); PG8_STAGE(PG8_SB(0, 0), b2, voffB); PG8_STAGE(PG8_SB(0, 1), b2 + hstep, voffB); PG8_STAGE(PG8_SA(0, 0), a2, voffA);
;             PG8_WAIT_V(8); PG8_WAIT_L(0); PG8_BAR; PG8_MMA(1, 0, At, B0); PG8_MMA(1, 1, At, B1); PG8_BAR; PG8_SCHED;
;             PG8_LDB(B0, 1, 0); PG8_LDB(B1, 1, 1); PG8_SCHED; PG8_LDA(At, 1, 0); PG8_STAGE(PG8_SA(0, 1), a2 + hstep, voffA);
;             PG8_WAIT_V(8); PG8_WAIT_L(0); PG8_BAR; PG8_MMA(0, 0, At, B0); PG8_MMA(0, 1, At, B1); PG8_BAR; PG8_SCHED;
;             PG8_LDA(At, 1, 1); PG8_STAGE(PG8_SB(1, 0), b3, voffB); PG8_STAGE(PG8_SB(1, 1), b3 + hstep, voffB); PG8_STAGE(PG8_SA(1, 0), a3, voffA);
;             PG8_WAIT_V(8); PG8_WAIT_L(0); PG8_BAR; PG8_MMA(1, 0, At, B0); PG8_MMA(1, 1, At, B1); PG8_BAR; PG8_SCHED;
.LBB0_138:
	ds_read_b128 v[148:151], v142
	ds_read_b128 v[152:155], v142 offset:1024
	ds_read_b128 v[156:159], v142 offset:2048
	ds_read_b128 v[160:163], v142 offset:3072
	ds_read_b128 v[164:167], v143
	ds_read_b128 v[168:171], v143 offset:1024
	ds_read_b128 v[172:175], v143 offset:2048
	ds_read_b128 v[176:179], v143 offset:3072
	s_add_u32 s62, s66, 0x100
	s_addc_u32 s63, s67, 0
	s_cmp_eq_u32 s96, 60
	s_cselect_b32 s86, s92, s62
	s_cselect_b32 s87, s13, s63
	s_cselect_b32 s84, s93, s94
	s_cselect_b32 s85, s11, s95
	s_add_u32 s76, s86, 0x80
	s_addc_u32 s77, s87, 0
	ds_read_b128 v[180:183], v144
	ds_read_b128 v[184:187], v144 offset:1024
	ds_read_b128 v[188:191], v144 offset:2048
	ds_read_b128 v[192:195], v144 offset:3072
	ds_read_b128 v[196:199], v144 offset:4096
	ds_read_b128 v[200:203], v144 offset:5120
	ds_read_b128 v[204:207], v144 offset:6144
	ds_read_b128 v[208:211], v144 offset:7168
	s_add_u32 s66, s66, 0x100080
	s_addc_u32 s67, s67, 0
	s_mov_b32 m0, s83
	s_nop 0
	global_load_lds_dwordx4 v136, s[66:67]
	s_nop 0
	s_mov_b32 m0, s88
	s_nop 0
	global_load_lds_dwordx4 v138, s[66:67]
	s_waitcnt vmcnt(8)
	s_waitcnt lgkmcnt(0)
	s_barrier
	s_setprio 1
	s_waitcnt lgkmcnt(7)
	v_mfma_f32_16x16x32_bf16 v[126:129], v[148:151], v[180:183], v[126:129]
	v_mfma_f32_16x16x32_bf16 v[122:125], v[156:159], v[180:183], v[122:125]
	s_waitcnt lgkmcnt(5)
	v_mfma_f32_16x16x32_bf16 v[106:109], v[156:159], v[188:191], v[106:109]
	v_mfma_f32_16x16x32_bf16 v[110:113], v[148:151], v[188:191], v[110:113]
	s_waitcnt lgkmcnt(3)
	v_mfma_f32_16x16x32_bf16 v[94:97], v[148:151], v[196:199], v[94:97]
	v_mfma_f32_16x16x32_bf16 v[90:93], v[156:159], v[196:199], v[90:93]
	s_waitcnt lgkmcnt(1)
	v_mfma_f32_16x16x32_bf16 v[74:77], v[156:159], v[204:207], v[74:77]
	v_mfma_f32_16x16x32_bf16 v[78:81], v[148:151], v[204:207], v[78:81]
	v_mfma_f32_16x16x32_bf16 v[126:129], v[152:155], v[184:187], v[126:129]
	v_mfma_f32_16x16x32_bf16 v[122:125], v[160:163], v[184:187], v[122:125]
	v_mfma_f32_16x16x32_bf16 v[106:109], v[160:163], v[192:195], v[106:109]
	v_mfma_f32_16x16x32_bf16 v[110:113], v[152:155], v[192:195], v[110:113]
	v_mfma_f32_16x16x32_bf16 v[94:97], v[152:155], v[200:203], v[94:97]
	v_mfma_f32_16x16x32_bf16 v[90:93], v[160:163], v[200:203], v[90:93]
	s_waitcnt lgkmcnt(0)
	v_mfma_f32_16x16x32_bf16 v[74:77], v[160:163], v[208:211], v[74:77]
	v_mfma_f32_16x16x32_bf16 v[78:81], v[152:155], v[208:211], v[78:81]
	s_setprio 0
	s_setprio 1
	v_mfma_f32_16x16x32_bf16 v[118:121], v[164:167], v[180:183], v[118:121]
	v_mfma_f32_16x16x32_bf16 v[114:117], v[172:175], v[180:183], v[114:117]
	v_mfma_f32_16x16x32_bf16 v[98:101], v[172:175], v[188:191], v[98:101]
	v_mfma_f32_16x16x32_bf16 v[102:105], v[164:167], v[188:191], v[102:105]
	v_mfma_f32_16x16x32_bf16 v[86:89], v[164:167], v[196:199], v[86:89]
	v_mfma_f32_16x16x32_bf16 v[82:85], v[172:175], v[196:199], v[82:85]
	v_mfma_f32_16x16x32_bf16 v[66:69], v[172:175], v[204:207], v[66:69]
	v_mfma_f32_16x16x32_bf16 v[70:73], v[164:167], v[204:207], v[70:73]
	v_mfma_f32_16x16x32_bf16 v[118:121], v[168:171], v[184:187], v[118:121]
	v_mfma_f32_16x16x32_bf16 v[114:117], v[176:179], v[184:187], v[114:117]
	v_mfma_f32_16x16x32_bf16 v[98:101], v[176:179], v[192:195], v[98:101]
	v_mfma_f32_16x16x32_bf16 v[102:105], v[168:171], v[192:195], v[102:105]
	v_mfma_f32_16x16x32_bf16 v[86:89], v[168:171], v[200:203], v[86:89]
	v_mfma_f32_16x16x32_bf16 v[82:85], v[176:179], v[200:203], v[82:85]
	v_mfma_f32_16x16x32_bf16 v[70:73], v[168:171], v[208:211], v[70:73]
	s_setprio 2
	s_barrier
	v_mfma_f32_16x16x32_bf16 v[66:69], v[176:179], v[208:211], v[66:69]
	s_setprio 0
	ds_read_b128 v[180:183], v144 offset:16384
	ds_read_b128 v[184:187], v144 offset:17408
	ds_read_b128 v[188:191], v144 offset:18432
	ds_read_b128 v[192:195], v144 offset:19456
	ds_read_b128 v[196:199], v144 offset:20480
	ds_read_b128 v[200:203], v144 offset:21504
	ds_read_b128 v[204:207], v144 offset:22528
	ds_read_b128 v[252:255], v144 offset:23552
	s_mov_b32 m0, s55
	s_nop 0
	global_load_lds_dwordx4 v137, s[84:85]
	s_add_u32 s66, s84, 0x100000
	s_mov_b32 m0, s56
	s_nop 0
	global_load_lds_dwordx4 v139, s[84:85]
	s_addc_u32 s67, s85, 0
	s_mov_b32 m0, s57
	s_nop 0
	global_load_lds_dwordx4 v137, s[66:67]
	s_nop 0
	s_mov_b32 m0, s58
	s_nop 0
	global_load_lds_dwordx4 v139, s[66:67]
	s_nop 0
	s_mov_b32 m0, s54
	s_nop 0
	global_load_lds_dwordx4 v136, s[86:87]
	s_nop 0
	s_mov_b32 m0, s59
	s_nop 0
	global_load_lds_dwordx4 v138, s[86:87]
	s_waitcnt vmcnt(8)
	s_waitcnt lgkmcnt(0)
	s_barrier
; #define PG8_STAGE(bufoff, gbase, voff) do { _Pragma("unroll") for (int _i = 0; _i < 2; ++_i) \
;         asm volatile("s_mov_b32 m0, %2\n\ts_nop 0\n\tglobal_load_lds_dwordx4 %0, %1" :: "v"((voff)[_i]), "s"((const char*)(gbase)), "s"(ldsbase + (unsigned)(bufoff) + ldsw + (unsigned)_i * 8192u) : "memory", "m0"); } while (0)
; #define PG8_LDA(dst, b, h) do { _Pragma("unroll") for (int m = 0; m < 4; ++m) _Pragma("unroll") for (int k = 0; k < 2; ++k) dst[m][k] = *(const PG8_LAS bf16x8*)(lds + PG8_SA(b, h) + aoff + m * 2048 + k * 1024); } while (0)
; #define PG8_LDB(dst, b, h) do { _Pragma("unroll") for (int n = 0; n < 2; ++n) _Pragma("unroll") for (int k = 0; k < 2; ++k) dst[n][k] = *(const PG8_LAS bf16x8*)(lds + PG8_SB(b, h) + boff + n * 2048 + k * 1024); } while (0)
; #define PG8_MMA(ai, bj, At, Bt) do { __builtin_amdgcn_s_setprio(1); _Pragma("unroll") for (int m = 0; m < 4; ++m) _Pragma("unroll") for (int n = 0; n < 2; ++n) _Pragma("unroll") for (int k = 0; k < 2; ++k) \
;         acc[ai][bj][m][n] = __builtin_amdgcn_mfma_f32_16x16x32_bf16(Bt[n][k], At[m][k], acc[ai][bj][m][n], 0, 0, 0); __builtin_amdgcn_s_setprio(0); } while (0)
; #define PG8_WAIT_V(n) asm volatile("s_waitcnt vmcnt(" #n ")" ::: "memory")
; #define PG8_BAR __builtin_amdgcn_s_barrier()
; template <class Epi, class Sched, bool ALIGN_EPI = false, bool SP2 = false>
; __device__ __forceinline__ void gemm_phase(PG8_LAS unsigned char* lds, const Gemm g, const Sched& S, const Epi& E) {
;     ...
;             PG8_WAIT_V(8); PG8_WAIT_L(0); PG8_BAR; PG8_MMA(0, 0, At, B0); PG8_MMA(0, 1, At, B1); PG8_BAR; PG8_SCHED;
;             PG8_LDA(At, 0, 1); PG8_STAGE(PG8_SB(0, 0), b2, voffB); PG8_STAGE(PG8_SB(0, 1), b2 + hstep, voffB); PG8_STAGE(PG8_SA(0, 0), a2, voffA);
;             PG8_WAIT_V(8); PG8_WAIT_L(0); PG8_BAR; PG8_MMA(1, 0, At, B0); PG8_MMA(1, 1, At, B1); PG8_BAR; PG8_SCHED;
;             PG8_LDB(B0, 1, 0); PG8_LDB(B1, 1, 1); PG8_SCHED; PG8_LDA(At, 1, 0); PG8_STAGE(PG8_SA(0, 1), a2 + hstep, voffA);
;             PG8_WAIT_V(8); PG8_WAIT_L(0); PG8_BAR; PG8_MMA(0, 0, At, B0); PG8_MMA(0, 1, At, B1); PG8_BAR; PG8_SCHED;
;             PG8_LDA(At, 1, 1); PG8_STAGE(PG8_SB(1, 0), b3, voffB); PG8_STAGE(PG8_SB(1, 1), b3 + hstep, voffB); PG8_STAGE(PG8_SA(1, 0), a3, voffA);
;             PG8_WAIT_V(8); PG8_WAIT_L(0); PG8_BAR; PG8_MMA(1, 0, At, B0); PG8_MMA(1, 1, At, B1); PG8_BAR; PG8_SCHED;
	s_setprio 1
	s_waitcnt lgkmcnt(7)
	v_mfma_f32_16x16x32_bf16 v[62:65], v[148:151], v[180:183], v[62:65]
	v_mfma_f32_16x16x32_bf16 v[58:61], v[156:159], v[180:183], v[58:61]
	s_waitcnt lgkmcnt(5)
	v_mfma_f32_16x16x32_bf16 v[42:45], v[156:159], v[188:191], v[42:45]
	v_mfma_f32_16x16x32_bf16 v[46:49], v[148:151], v[188:191], v[46:49]
	s_waitcnt lgkmcnt(3)
	v_mfma_f32_16x16x32_bf16 v[30:33], v[148:151], v[196:199], v[30:33]
	v_mfma_f32_16x16x32_bf16 v[26:29], v[156:159], v[196:199], v[26:29]
	s_waitcnt lgkmcnt(1)
	v_mfma_f32_16x16x32_bf16 v[10:13], v[156:159], v[204:207], v[10:13]
	v_mfma_f32_16x16x32_bf16 v[14:17], v[148:151], v[204:207], v[14:17]
	v_mfma_f32_16x16x32_bf16 v[62:65], v[152:155], v[184:187], v[62:65]
	v_mfma_f32_16x16x32_bf16 v[58:61], v[160:163], v[184:187], v[58:61]
	v_mfma_f32_16x16x32_bf16 v[42:45], v[160:163], v[192:195], v[42:45]
	v_mfma_f32_16x16x32_bf16 v[46:49], v[152:155], v[192:195], v[46:49]
	v_mfma_f32_16x16x32_bf16 v[30:33], v[152:155], v[200:203], v[30:33]
	v_mfma_f32_16x16x32_bf16 v[26:29], v[160:163], v[200:203], v[26:29]
	s_waitcnt lgkmcnt(0)
	v_mfma_f32_16x16x32_bf16 v[10:13], v[160:163], v[252:255], v[10:13]
	v_mfma_f32_16x16x32_bf16 v[14:17], v[152:155], v[252:255], v[14:17]
	s_setprio 0
	s_setprio 1
	v_mfma_f32_16x16x32_bf16 v[54:57], v[164:167], v[180:183], v[54:57]
	v_mfma_f32_16x16x32_bf16 v[50:53], v[172:175], v[180:183], v[50:53]
	v_mfma_f32_16x16x32_bf16 v[34:37], v[172:175], v[188:191], v[34:37]
	v_mfma_f32_16x16x32_bf16 v[38:41], v[164:167], v[188:191], v[38:41]
	v_mfma_f32_16x16x32_bf16 v[22:25], v[164:167], v[196:199], v[22:25]
	v_mfma_f32_16x16x32_bf16 v[18:21], v[172:175], v[196:199], v[18:21]
	v_mfma_f32_16x16x32_bf16 v[2:5], v[172:175], v[204:207], v[2:5]
	v_mfma_f32_16x16x32_bf16 v[6:9], v[164:167], v[204:207], v[6:9]
	v_mfma_f32_16x16x32_bf16 v[54:57], v[168:171], v[184:187], v[54:57]
	v_mfma_f32_16x16x32_bf16 v[50:53], v[176:179], v[184:187], v[50:53]
	v_mfma_f32_16x16x32_bf16 v[34:37], v[176:179], v[192:195], v[34:37]
	v_mfma_f32_16x16x32_bf16 v[38:41], v[168:171], v[192:195], v[38:41]
	v_mfma_f32_16x16x32_bf16 v[22:25], v[168:171], v[200:203], v[22:25]
	v_mfma_f32_16x16x32_bf16 v[18:21], v[176:179], v[200:203], v[18:21]
	v_mfma_f32_16x16x32_bf16 v[6:9], v[168:171], v[252:255], v[6:9]
	s_setprio 2
	s_barrier
	v_mfma_f32_16x16x32_bf16 v[2:5], v[176:179], v[252:255], v[2:5]
	s_setprio 0
	ds_read_b128 v[148:151], v145
	ds_read_b128 v[152:155], v145 offset:1024
	ds_read_b128 v[156:159], v145 offset:2048
	ds_read_b128 v[160:163], v145 offset:3072
	ds_read_b128 v[164:167], v146
	ds_read_b128 v[168:171], v146 offset:1024
	ds_read_b128 v[172:175], v146 offset:2048
	ds_read_b128 v[248:251], v146 offset:3072
	ds_read_b128 v[180:183], v144 offset:32768
	ds_read_b128 v[184:187], v144 offset:33792
	ds_read_b128 v[188:191], v144 offset:34816
	ds_read_b128 v[192:195], v144 offset:35840
	ds_read_b128 v[196:199], v144 offset:36864
	ds_read_b128 v[200:203], v144 offset:37888
	ds_read_b128 v[204:207], v144 offset:38912
	ds_read_b128 v[208:211], v144 offset:39936
	s_add_u32 s66, s86, 0x100000
	s_addc_u32 s67, s87, 0
	s_mov_b32 m0, s60
	s_nop 0
	global_load_lds_dwordx4 v136, s[66:67]
	s_nop 0
	s_mov_b32 m0, s61
	s_nop 0
	global_load_lds_dwordx4 v138, s[66:67]
	s_waitcnt vmcnt(8)
	s_waitcnt lgkmcnt(0)
	s_barrier
	s_setprio 1
	s_waitcnt lgkmcnt(7)
	v_mfma_f32_16x16x32_bf16 v[126:129], v[148:151], v[180:183], v[126:129]
	v_mfma_f32_16x16x32_bf16 v[122:125], v[156:159], v[180:183], v[122:125]
	s_waitcnt lgkmcnt(5)
	v_mfma_f32_16x16x32_bf16 v[106:109], v[156:159], v[188:191], v[106:109]
	v_mfma_f32_16x16x32_bf16 v[110:113], v[148:151], v[188:191], v[110:113]
	s_waitcnt lgkmcnt(3)
	v_mfma_f32_16x16x32_bf16 v[94:97], v[148:151], v[196:199], v[94:97]
	v_mfma_f32_16x16x32_bf16 v[90:93], v[156:159], v[196:199], v[90:93]
	s_waitcnt lgkmcnt(1)
	v_mfma_f32_16x16x32_bf16 v[74:77], v[156:159], v[204:207], v[74:77]
	v_mfma_f32_16x16x32_bf16 v[78:81], v[148:151], v[204:207], v[78:81]
	v_mfma_f32_16x16x32_bf16 v[126:129], v[152:155], v[184:187], v[126:129]
	v_mfma_f32_16x16x32_bf16 v[122:125], v[160:163], v[184:187], v[122:125]
	v_mfma_f32_16x16x32_bf16 v[106:109], v[160:163], v[192:195], v[106:109]
	v_mfma_f32_16x16x32_bf16 v[110:113], v[152:155], v[192:195], v[110:113]
	v_mfma_f32_16x16x32_bf16 v[94:97], v[152:155], v[200:203], v[94:97]
	v_mfma_f32_16x16x32_bf16 v[90:93], v[160:163], v[200:203], v[90:93]
	s_waitcnt lgkmcnt(0)
	v_mfma_f32_16x16x32_bf16 v[74:77], v[160:163], v[208:211], v[74:77]
	v_mfma_f32_16x16x32_bf16 v[78:81], v[152:155], v[208:211], v[78:81]
	s_setprio 0
	s_setprio 1
	v_mfma_f32_16x16x32_bf16 v[118:121], v[164:167], v[180:183], v[118:121]
	v_mfma_f32_16x16x32_bf16 v[114:117], v[172:175], v[180:183], v[114:117]
	v_mfma_f32_16x16x32_bf16 v[98:101], v[172:175], v[188:191], v[98:101]
	v_mfma_f32_16x16x32_bf16 v[102:105], v[164:167], v[188:191], v[102:105]
	v_mfma_f32_16x16x32_bf16 v[86:89], v[164:167], v[196:199], v[86:89]
	v_mfma_f32_16x16x32_bf16 v[82:85], v[172:175], v[196:199], v[82:85]
	v_mfma_f32_16x16x32_bf16 v[66:69], v[172:175], v[204:207], v[66:69]
	v_mfma_f32_16x16x32_bf16 v[70:73], v[164:167], v[204:207], v[70:73]
	v_mfma_f32_16x16x32_bf16 v[118:121], v[168:171], v[184:187], v[118:121]
	v_mfma_f32_16x16x32_bf16 v[114:117], v[248:251], v[184:187], v[114:117]
	v_mfma_f32_16x16x32_bf16 v[98:101], v[248:251], v[192:195], v[98:101]
	v_mfma_f32_16x16x32_bf16 v[102:105], v[168:171], v[192:195], v[102:105]
	v_mfma_f32_16x16x32_bf16 v[86:89], v[168:171], v[200:203], v[86:89]
	v_mfma_f32_16x16x32_bf16 v[82:85], v[248:251], v[200:203], v[82:85]
	v_mfma_f32_16x16x32_bf16 v[70:73], v[168:171], v[208:211], v[70:73]
	s_setprio 2
	s_barrier
; __device__ __forceinline__ unsigned cvt_pk_bf16(float lo, float hi) { unsigned r; asm volatile("v_cvt_pk_bf16_f32 %0, %1, %2" : "=v"(r) : "v"(lo), "v"(hi)); return r; }
; __device__ __forceinline__ float silu_f(float x) { return x * sigmoid_f(x); }
; #define PG8_STAGE(bufoff, gbase, voff) do { _Pragma("unroll") for (int _i = 0; _i < 2; ++_i) \
;         asm volatile("s_mov_b32 m0, %2\n\ts_nop 0\n\tglobal_load_lds_dwordx4 %0, %1" :: "v"((voff)[_i]), "s"((const char*)(gbase)), "s"(ldsbase + (unsigned)(bufoff) + ldsw + (unsigned)_i * 8192u) : "memory", "m0"); } while (0)
; #define PG8_LDA(dst, b, h) do { _Pragma("unroll") for (int m = 0; m < 4; ++m) _Pragma("unroll") for (int k = 0; k < 2; ++k) dst[m][k] = *(const PG8_LAS bf16x8*)(lds + PG8_SA(b, h) + aoff + m * 2048 + k * 1024); } while (0)
; #define PG8_WAIT_V(n) asm volatile("s_waitcnt vmcnt(" #n ")" ::: "memory")
; #define PG8_WAIT_L(n) asm volatile("s_waitcnt lgkmcnt(" #n ")" ::: "memory")
; #define PG8_BAR __builtin_amdgcn_s_barrier()
; #define PG8_SCHED __builtin_amdgcn_sched_barrier(0)
;     __device__ __forceinline__ void operator()(const f32x4 (&acc)[2][2][4][2], const Unit& u, int wr, int wc, int fr, int fq) const {
;     ...
;         for (int ai = 0; ai < 2; ++ai)
; #pragma unroll
;             for (int m = 0; m < 4; ++m) { bf16_t* rowp = O + (size_t)(row0 + ai * HALF + m * 16) * ldc + col0;
;                 const f32x4 g0 = acc[ai][0][m][0], g1 = acc[ai][0][m][1], u0 = acc[ai][1][m][0], u1 = acc[ai][1][m][1];
;                 f32x4 v0, v1;
; #pragma unroll
;                 for (int j = 0; j < 4; ++j) { v0[j] = silu_f(g0[j]) * u0[j]; v1[j] = silu_f(g1[j]) * u1[j]; }
;                 u32x4 w; w.x = cvt_pk_bf16(v0[0], v0[1]); w.y = cvt_pk_bf16(v0[2], v0[3]); w.z = cvt_pk_bf16(v1[0], v1[1]); w.w = cvt_pk_bf16(v1[2], v1[3]);
; template <class Epi, class Sched, bool ALIGN_EPI = false, bool SP2 = false>
; __device__ __forceinline__ void gemm_phase(PG8_LAS unsigned char* lds, const Gemm g, const Sched& S, const Epi& E) {
;     ...
;         for (int t = 0; t < nt; t += 2) {
;     ...
;             PG8_LDA(At, 1, 1); PG8_STAGE(PG8_SB(1, 0), b3, voffB); PG8_STAGE(PG8_SB(1, 1), b3 + hstep, voffB); PG8_STAGE(PG8_SA(1, 0), a3, voffA);
;             PG8_WAIT_V(8); PG8_WAIT_L(0); PG8_BAR; PG8_MMA(1, 0, At, B0); PG8_MMA(1, 1, At, B1); PG8_BAR; PG8_SCHED;
	v_mfma_f32_16x16x32_bf16 v[66:69], v[248:251], v[208:211], v[66:69]
	s_setprio 0
	ds_read_b128 v[180:183], v144 offset:49152
	ds_read_b128 v[184:187], v144 offset:50176
	ds_read_b128 v[188:191], v144 offset:51200
	ds_read_b128 v[192:195], v144 offset:52224
	ds_read_b128 v[196:199], v144 offset:53248
	ds_read_b128 v[200:203], v144 offset:54272
	ds_read_b128 v[204:207], v144 offset:55296
	ds_read_b128 v[252:255], v144 offset:56320
	s_add_u32 s66, s84, 0x80
	s_addc_u32 s67, s85, 0
	s_mov_b32 m0, s64
	s_nop 0
	global_load_lds_dwordx4 v137, s[66:67]
	s_nop 0
	s_mov_b32 m0, s65
	s_nop 0
	global_load_lds_dwordx4 v139, s[66:67]
	s_add_u32 s66, s84, 0x100080
	s_addc_u32 s67, s85, 0
	s_mov_b32 m0, s70
	s_nop 0
	global_load_lds_dwordx4 v137, s[66:67]
	s_nop 0
	s_mov_b32 m0, s71
	s_nop 0
	global_load_lds_dwordx4 v139, s[66:67]
	s_nop 0
	s_mov_b32 m0, s68
	s_nop 0
	global_load_lds_dwordx4 v136, s[76:77]
	s_nop 0
	s_mov_b32 m0, s69
	s_nop 0
	global_load_lds_dwordx4 v138, s[76:77]
	s_waitcnt vmcnt(8)
	s_waitcnt lgkmcnt(0)
	s_barrier
	s_setprio 1
	s_waitcnt lgkmcnt(7)
	v_mfma_f32_16x16x32_bf16 v[62:65], v[148:151], v[180:183], v[62:65]
	v_mfma_f32_16x16x32_bf16 v[58:61], v[156:159], v[180:183], v[58:61]
	s_waitcnt lgkmcnt(5)
	v_mfma_f32_16x16x32_bf16 v[42:45], v[156:159], v[188:191], v[42:45]
	v_mfma_f32_16x16x32_bf16 v[46:49], v[148:151], v[188:191], v[46:49]
	s_waitcnt lgkmcnt(3)
	v_mfma_f32_16x16x32_bf16 v[30:33], v[148:151], v[196:199], v[30:33]
	v_mfma_f32_16x16x32_bf16 v[26:29], v[156:159], v[196:199], v[26:29]
	s_waitcnt lgkmcnt(1)
	v_mfma_f32_16x16x32_bf16 v[10:13], v[156:159], v[204:207], v[10:13]
	v_mfma_f32_16x16x32_bf16 v[14:17], v[148:151], v[204:207], v[14:17]
	v_mfma_f32_16x16x32_bf16 v[62:65], v[152:155], v[184:187], v[62:65]
	v_mfma_f32_16x16x32_bf16 v[58:61], v[160:163], v[184:187], v[58:61]
	v_mfma_f32_16x16x32_bf16 v[42:45], v[160:163], v[192:195], v[42:45]
	v_mfma_f32_16x16x32_bf16 v[46:49], v[152:155], v[192:195], v[46:49]
	v_mfma_f32_16x16x32_bf16 v[30:33], v[152:155], v[200:203], v[30:33]
	v_mfma_f32_16x16x32_bf16 v[26:29], v[160:163], v[200:203], v[26:29]
	s_waitcnt lgkmcnt(0)
	v_mfma_f32_16x16x32_bf16 v[10:13], v[160:163], v[252:255], v[10:13]
	v_mfma_f32_16x16x32_bf16 v[14:17], v[152:155], v[252:255], v[14:17]
	s_setprio 0
	s_setprio 1
	v_mfma_f32_16x16x32_bf16 v[54:57], v[164:167], v[180:183], v[54:57]
	v_mfma_f32_16x16x32_bf16 v[50:53], v[172:175], v[180:183], v[50:53]
	v_mfma_f32_16x16x32_bf16 v[34:37], v[172:175], v[188:191], v[34:37]
	v_mfma_f32_16x16x32_bf16 v[38:41], v[164:167], v[188:191], v[38:41]
	v_mfma_f32_16x16x32_bf16 v[22:25], v[164:167], v[196:199], v[22:25]
	v_mfma_f32_16x16x32_bf16 v[18:21], v[172:175], v[196:199], v[18:21]
	v_mfma_f32_16x16x32_bf16 v[2:5], v[172:175], v[204:207], v[2:5]
	v_mfma_f32_16x16x32_bf16 v[6:9], v[164:167], v[204:207], v[6:9]
	v_mfma_f32_16x16x32_bf16 v[54:57], v[168:171], v[184:187], v[54:57]
	v_mfma_f32_16x16x32_bf16 v[50:53], v[248:251], v[184:187], v[50:53]
	v_mfma_f32_16x16x32_bf16 v[34:37], v[248:251], v[192:195], v[34:37]
	v_mfma_f32_16x16x32_bf16 v[38:41], v[168:171], v[192:195], v[38:41]
	v_mfma_f32_16x16x32_bf16 v[22:25], v[168:171], v[200:203], v[22:25]
	v_mfma_f32_16x16x32_bf16 v[18:21], v[248:251], v[200:203], v[18:21]
	v_mfma_f32_16x16x32_bf16 v[6:9], v[168:171], v[252:255], v[6:9]
	s_setprio 2
	s_barrier
	v_mfma_f32_16x16x32_bf16 v[2:5], v[248:251], v[252:255], v[2:5]
	s_setprio 0
	s_add_i32 s96, s96, 2
	s_add_u32 s94, s94, 0x100
	s_addc_u32 s95, s95, 0
	s_cmp_gt_u32 s96, 61
	s_mov_b64 s[66:67], s[62:63]
	s_cbranch_scc0 .LBB0_138
	v_mul_f32_e32 v134, 0xbfb8aa3b, v126
	v_exp_f32_e32 v150, v134
	v_mul_f32_e32 v134, 0xbfb8aa3b, v122
	v_exp_f32_e32 v151, v134
	v_lshl_or_b32 v148, s91, 7, v141
	v_add_f32_e32 v150, 1.0, v150
	v_rcp_f32_e32 v152, v150
	v_add_f32_e32 v150, 1.0, v151
	v_rcp_f32_e32 v153, v150
	v_lshl_add_u32 v147, s82, 8, v140
	v_mul_f32_e32 v126, v126, v152
	v_mul_f32_e32 v118, v126, v118
	v_mul_f32_e32 v126, 0xbfb8aa3b, v127
	v_exp_f32_e32 v126, v126
	v_mul_f32_e32 v152, 0xbfb8aa3b, v123
	v_exp_f32_e32 v152, v152
	v_mul_f32_e32 v122, v122, v153
	v_mul_f32_e32 v122, v122, v114
	v_add_f32_e32 v114, 1.0, v126
	v_rcp_f32_e32 v114, v114
	v_add_f32_e32 v126, 1.0, v152
	v_mul_f32_e32 v152, 0xbfb8aa3b, v128
	v_rcp_f32_e32 v126, v126
	v_exp_f32_e32 v152, v152
	v_mul_f32_e32 v114, v127, v114
	v_mul_f32_e32 v119, v114, v119
	v_mul_f32_e32 v114, v123, v126
	v_add_f32_e32 v123, 1.0, v152
	v_rcp_f32_e32 v123, v123
	v_mul_f32_e32 v126, 0xbfb8aa3b, v124
	v_exp_f32_e32 v126, v126
	v_mul_f32_e32 v127, v114, v115
	v_mul_f32_e32 v114, v128, v123
	v_mul_f32_e32 v115, 0xbfb8aa3b, v129
	v_mul_f32_e32 v123, v114, v120
	v_exp_f32_e32 v115, v115
	v_mul_f32_e32 v120, 0xbfb8aa3b, v125
	v_exp_f32_e32 v120, v120
	v_add_f32_e32 v114, 1.0, v126
	v_rcp_f32_e32 v114, v114
	v_add_f32_e32 v115, 1.0, v115
	v_rcp_f32_e32 v115, v115
	v_add_f32_e32 v120, 1.0, v120
	v_rcp_f32_e32 v120, v120
	v_mul_f32_e32 v114, v124, v114
	v_mul_f32_e32 v124, v114, v116
	v_mul_f32_e32 v114, v129, v115
	v_ashrrev_i32_e32 v149, 31, v148
	v_mov_b64_e32 v[134:135], s[72:73]
	v_mul_f32_e32 v126, v114, v121
	v_mul_f32_e32 v114, v125, v120
	v_mad_i64_i32 v[150:151], s[62:63], v147, s90, v[134:135]
	v_mul_f32_e32 v125, v114, v117
	v_lshlrev_b64 v[114:115], 1, v[148:149]
	v_lshl_add_u64 v[120:121], v[150:151], 0, v[114:115]
	v_cvt_pk_bf16_f32 v116, v118, v119
	v_cvt_pk_bf16_f32 v117, v123, v126
	v_cvt_pk_bf16_f32 v118, v122, v127
	v_cvt_pk_bf16_f32 v119, v124, v125
	global_store_dwordx4 v[120:121], v[116:119], off
	s_and_b64 vcc, exec, s[0:1]
	s_mov_b32 s91, s10
	v_mul_f32_e32 v116, 0xbfb8aa3b, v110
	v_exp_f32_e32 v116, v116
; __device__ __forceinline__ unsigned cvt_pk_bf16(float lo, float hi) { unsigned r; asm volatile("v_cvt_pk_bf16_f32 %0, %1, %2" : "=v"(r) : "v"(lo), "v"(hi)); return r; }
; __device__ __forceinline__ float silu_f(float x) { return x * sigmoid_f(x); }
;     __device__ __forceinline__ void operator()(const f32x4 (&acc)[2][2][4][2], const Unit& u, int wr, int wc, int fr, int fq) const {
;     ...
;         for (int ai = 0; ai < 2; ++ai)
; #pragma unroll
;             for (int m = 0; m < 4; ++m) { bf16_t* rowp = O + (size_t)(row0 + ai * HALF + m * 16) * ldc + col0;
;                 const f32x4 g0 = acc[ai][0][m][0], g1 = acc[ai][0][m][1], u0 = acc[ai][1][m][0], u1 = acc[ai][1][m][1];
;                 f32x4 v0, v1;
; #pragma unroll
;                 for (int j = 0; j < 4; ++j) { v0[j] = silu_f(g0[j]) * u0[j]; v1[j] = silu_f(g1[j]) * u1[j]; }
;                 u32x4 w; w.x = cvt_pk_bf16(v0[0], v0[1]); w.y = cvt_pk_bf16(v0[2], v0[3]); w.z = cvt_pk_bf16(v1[0], v1[1]); w.w = cvt_pk_bf16(v1[2], v1[3]);
;                 *(u32x4*)rowp = w; }
	v_mul_f32_e32 v117, 0xbfb8aa3b, v106
	v_exp_f32_e32 v117, v117
	v_or_b32_e32 v118, 16, v147
	v_add_f32_e32 v116, 1.0, v116
	v_rcp_f32_e32 v119, v116
	v_add_f32_e32 v116, 1.0, v117
	v_rcp_f32_e32 v120, v116
	v_mad_i64_i32 v[116:117], s[62:63], v118, s90, v[134:135]
	v_mul_f32_e32 v110, v110, v119
	v_mul_f32_e32 v110, v110, v102
	v_mul_f32_e32 v102, v106, v120
	v_mul_f32_e32 v106, 0xbfb8aa3b, v111
	v_exp_f32_e32 v106, v106
	v_mul_f32_e32 v118, 0xbfb8aa3b, v107
	v_mul_f32_e32 v119, v102, v98
	v_exp_f32_e32 v118, v118
	v_add_f32_e32 v98, 1.0, v106
	v_rcp_f32_e32 v98, v98
	v_mul_f32_e32 v106, 0xbfb8aa3b, v112
	v_exp_f32_e32 v106, v106
	v_add_f32_e32 v102, 1.0, v118
	v_mul_f32_e32 v98, v111, v98
	v_rcp_f32_e32 v102, v102
	v_mul_f32_e32 v98, v98, v103
	v_add_f32_e32 v103, 1.0, v106
	v_rcp_f32_e32 v103, v103
	v_mul_f32_e32 v102, v107, v102
	v_mul_f32_e32 v106, 0xbfb8aa3b, v108
	v_mul_f32_e32 v107, v102, v99
	v_mul_f32_e32 v99, v112, v103
	v_exp_f32_e32 v106, v106
	v_mul_f32_e32 v99, v99, v104
	v_mul_f32_e32 v103, 0xbfb8aa3b, v113
	v_mul_f32_e32 v104, 0xbfb8aa3b, v109
	v_exp_f32_e32 v103, v103
	v_exp_f32_e32 v104, v104
	v_add_f32_e32 v102, 1.0, v106
	v_rcp_f32_e32 v102, v102
	v_add_f32_e32 v103, 1.0, v103
	v_add_f32_e32 v104, 1.0, v104
	v_rcp_f32_e32 v103, v103
	v_rcp_f32_e32 v104, v104
	v_mul_f32_e32 v102, v108, v102
	v_mul_f32_e32 v106, v102, v100
	v_mul_f32_e32 v100, v113, v103
	v_mul_f32_e32 v102, v109, v104
	v_mul_f32_e32 v100, v100, v105
	v_mul_f32_e32 v101, v102, v101
	v_lshl_add_u64 v[102:103], v[116:117], 0, v[114:115]
	v_cvt_pk_bf16_f32 v98, v110, v98
	v_cvt_pk_bf16_f32 v99, v99, v100
	v_cvt_pk_bf16_f32 v100, v119, v107
	v_cvt_pk_bf16_f32 v101, v106, v101
	global_store_dwordx4 v[102:103], v[98:101], off
	s_mov_b32 s82, s12
	s_mov_b64 s[66:67], s[14:15]
	v_mul_f32_e32 v98, 0xbfb8aa3b, v94
	v_exp_f32_e32 v98, v98
	v_mul_f32_e32 v99, 0xbfb8aa3b, v90
	v_exp_f32_e32 v99, v99
	v_or_b32_e32 v100, 32, v147
	v_add_f32_e32 v98, 1.0, v98
	v_rcp_f32_e32 v101, v98
	v_add_f32_e32 v98, 1.0, v99
	v_rcp_f32_e32 v102, v98
	v_mad_i64_i32 v[98:99], s[62:63], v100, s90, v[134:135]
	v_mul_f32_e32 v94, v94, v101
	v_mul_f32_e32 v94, v94, v86
	v_mul_f32_e32 v86, v90, v102
	v_mul_f32_e32 v90, 0xbfb8aa3b, v95
	v_exp_f32_e32 v90, v90
	v_mul_f32_e32 v100, 0xbfb8aa3b, v91
	v_mul_f32_e32 v101, v86, v82
	v_exp_f32_e32 v100, v100
	v_add_f32_e32 v82, 1.0, v90
	v_rcp_f32_e32 v82, v82
	v_mul_f32_e32 v90, 0xbfb8aa3b, v96
	v_exp_f32_e32 v90, v90
	v_add_f32_e32 v86, 1.0, v100
	v_mul_f32_e32 v82, v95, v82
	v_rcp_f32_e32 v86, v86
	v_mul_f32_e32 v82, v82, v87
	v_add_f32_e32 v87, 1.0, v90
	v_rcp_f32_e32 v87, v87
	v_mul_f32_e32 v86, v91, v86
	v_mul_f32_e32 v90, 0xbfb8aa3b, v92
	v_mul_f32_e32 v91, v86, v83
	v_mul_f32_e32 v83, v96, v87
	v_exp_f32_e32 v90, v90
	v_mul_f32_e32 v83, v83, v88
	v_mul_f32_e32 v87, 0xbfb8aa3b, v97
	v_mul_f32_e32 v88, 0xbfb8aa3b, v93
	v_exp_f32_e32 v87, v87
	v_exp_f32_e32 v88, v88
	v_add_f32_e32 v86, 1.0, v90
	v_rcp_f32_e32 v86, v86
	v_add_f32_e32 v87, 1.0, v87
	v_add_f32_e32 v88, 1.0, v88
	v_rcp_f32_e32 v87, v87
	v_rcp_f32_e32 v88, v88
	v_mul_f32_e32 v86, v92, v86
	v_mul_f32_e32 v90, v86, v84
	v_mul_f32_e32 v84, v97, v87
	v_mul_f32_e32 v86, v93, v88
	v_mul_f32_e32 v84, v84, v89
	v_mul_f32_e32 v85, v86, v85
	v_lshl_add_u64 v[86:87], v[98:99], 0, v[114:115]
	v_cvt_pk_bf16_f32 v82, v94, v82
	v_cvt_pk_bf16_f32 v83, v83, v84
	v_cvt_pk_bf16_f32 v84, v101, v91
	v_cvt_pk_bf16_f32 v85, v90, v85
	global_store_dwordx4 v[86:87], v[82:85], off
	s_nop 1
	v_mul_f32_e32 v82, 0xbfb8aa3b, v78
	v_exp_f32_e32 v82, v82
	v_mul_f32_e32 v83, 0xbfb8aa3b, v74
	v_exp_f32_e32 v83, v83
	v_or_b32_e32 v84, 48, v147
	v_add_f32_e32 v82, 1.0, v82
	v_rcp_f32_e32 v85, v82
	v_add_f32_e32 v82, 1.0, v83
	v_rcp_f32_e32 v86, v82
	v_mad_i64_i32 v[82:83], s[62:63], v84, s90, v[134:135]
	v_mul_f32_e32 v78, v78, v85
	v_mul_f32_e32 v78, v78, v70
	v_mul_f32_e32 v70, v74, v86
	v_mul_f32_e32 v74, 0xbfb8aa3b, v79
	v_exp_f32_e32 v74, v74
	v_mul_f32_e32 v84, 0xbfb8aa3b, v75
	v_mul_f32_e32 v85, v70, v66
	v_exp_f32_e32 v84, v84
	v_add_f32_e32 v66, 1.0, v74
	v_rcp_f32_e32 v66, v66
	v_mul_f32_e32 v74, 0xbfb8aa3b, v80
	v_exp_f32_e32 v74, v74
	v_add_f32_e32 v70, 1.0, v84
	v_mul_f32_e32 v66, v79, v66
	v_rcp_f32_e32 v70, v70
	v_mul_f32_e32 v66, v66, v71
	v_add_f32_e32 v71, 1.0, v74
	v_rcp_f32_e32 v71, v71
	v_mul_f32_e32 v70, v75, v70
	v_mul_f32_e32 v74, 0xbfb8aa3b, v76
	v_mul_f32_e32 v75, v70, v67
	v_mul_f32_e32 v67, v80, v71
	v_exp_f32_e32 v74, v74
	v_mul_f32_e32 v67, v67, v72
	v_mul_f32_e32 v71, 0xbfb8aa3b, v81
	v_mul_f32_e32 v72, 0xbfb8aa3b, v77
	v_exp_f32_e32 v71, v71
	v_exp_f32_e32 v72, v72
	v_add_f32_e32 v70, 1.0, v74
	v_rcp_f32_e32 v70, v70
	v_add_f32_e32 v71, 1.0, v71
	v_add_f32_e32 v72, 1.0, v72
	v_rcp_f32_e32 v71, v71
	v_rcp_f32_e32 v72, v72
	v_mul_f32_e32 v70, v76, v70
	v_mul_f32_e32 v74, v70, v68
	v_mul_f32_e32 v68, v81, v71
	v_mul_f32_e32 v70, v77, v72
	v_mul_f32_e32 v68, v68, v73
	v_mul_f32_e32 v69, v70, v69
	v_lshl_add_u64 v[70:71], v[82:83], 0, v[114:115]
	v_cvt_pk_bf16_f32 v66, v78, v66
	v_cvt_pk_bf16_f32 v67, v67, v68
	v_cvt_pk_bf16_f32 v68, v85, v75
	v_cvt_pk_bf16_f32 v69, v74, v69
	global_store_dwordx4 v[70:71], v[66:69], off
	s_nop 1
	v_mul_f32_e32 v66, 0xbfb8aa3b, v62
	v_exp_f32_e32 v66, v66
	v_mul_f32_e32 v67, 0xbfb8aa3b, v58
	v_exp_f32_e32 v67, v67
	v_add_u32_e32 v68, 0x80, v147
	v_add_f32_e32 v66, 1.0, v66
	v_rcp_f32_e32 v69, v66
	v_add_f32_e32 v66, 1.0, v67
	v_rcp_f32_e32 v70, v66
	v_mad_i64_i32 v[66:67], s[62:63], v68, s90, v[134:135]
	v_mul_f32_e32 v62, v62, v69
	v_mul_f32_e32 v62, v62, v54
	v_mul_f32_e32 v54, v58, v70
	v_mul_f32_e32 v58, 0xbfb8aa3b, v63
	v_exp_f32_e32 v58, v58
; __device__ __forceinline__ unsigned cvt_pk_bf16(float lo, float hi) { unsigned r; asm volatile("v_cvt_pk_bf16_f32 %0, %1, %2" : "=v"(r) : "v"(lo), "v"(hi)); return r; }
; __device__ __forceinline__ float silu_f(float x) { return x * sigmoid_f(x); }
; #define PG8_WAIT_V(n) asm volatile("s_waitcnt vmcnt(" #n ")" ::: "memory")
; #define PG8_BAR __builtin_amdgcn_s_barrier()
;     __device__ __forceinline__ void operator()(const f32x4 (&acc)[2][2][4][2], const Unit& u, int wr, int wc, int fr, int fq) const {
;     ...
;         for (int ai = 0; ai < 2; ++ai)
; #pragma unroll
;             for (int m = 0; m < 4; ++m) { bf16_t* rowp = O + (size_t)(row0 + ai * HALF + m * 16) * ldc + col0;
;                 const f32x4 g0 = acc[ai][0][m][0], g1 = acc[ai][0][m][1], u0 = acc[ai][1][m][0], u1 = acc[ai][1][m][1];
;                 f32x4 v0, v1;
; #pragma unroll
;                 for (int j = 0; j < 4; ++j) { v0[j] = silu_f(g0[j]) * u0[j]; v1[j] = silu_f(g1[j]) * u1[j]; }
;                 u32x4 w; w.x = cvt_pk_bf16(v0[0], v0[1]); w.y = cvt_pk_bf16(v0[2], v0[3]); w.z = cvt_pk_bf16(v1[0], v1[1]); w.w = cvt_pk_bf16(v1[2], v1[3]);
;                 *(u32x4*)rowp = w; }
; template <class Epi, class Sched, bool ALIGN_EPI = false, bool SP2 = false>
; __device__ __forceinline__ void gemm_phase(PG8_LAS unsigned char* lds, const Gemm g, const Sched& S, const Epi& E) {
;     ...
;         if (!has_next) break;
; #pragma unroll
;         for (int a = 0; a < 2; ++a)
; #pragma unroll
;             for (int b = 0; b < 2; ++b)
; #pragma unroll
;                 for (int m = 0; m < 4; ++m)
; #pragma unroll
;                     for (int n = 0; n < 2; ++n) acc[a][b][m][n] = (f32x4){0.f, 0.f, 0.f, 0.f};
;         cur = nxt; cA = nA; cB = nB; ++ui;
;         if constexpr (ALIGN_EPI) { if (wr == 1) PG8_BAR; }
;     }
;     PG8_WAIT_V(0);
;     if constexpr (!ALIGN_EPI) { if (wr == 0) PG8_BAR; }
;     PG8_BAR;
	v_mul_f32_e32 v68, 0xbfb8aa3b, v59
	v_mul_f32_e32 v69, v54, v50
	v_exp_f32_e32 v68, v68
	v_add_f32_e32 v50, 1.0, v58
	v_rcp_f32_e32 v50, v50
	v_mul_f32_e32 v58, 0xbfb8aa3b, v64
	v_exp_f32_e32 v58, v58
	v_add_f32_e32 v54, 1.0, v68
	v_mul_f32_e32 v50, v63, v50
	v_rcp_f32_e32 v54, v54
	v_mul_f32_e32 v50, v50, v55
	v_add_f32_e32 v55, 1.0, v58
	v_rcp_f32_e32 v55, v55
	v_mul_f32_e32 v54, v59, v54
	v_mul_f32_e32 v58, 0xbfb8aa3b, v60
	v_mul_f32_e32 v59, v54, v51
	v_mul_f32_e32 v51, v64, v55
	v_exp_f32_e32 v58, v58
	v_mul_f32_e32 v51, v51, v56
	v_mul_f32_e32 v55, 0xbfb8aa3b, v65
	v_mul_f32_e32 v56, 0xbfb8aa3b, v61
	v_exp_f32_e32 v55, v55
	v_exp_f32_e32 v56, v56
	v_add_f32_e32 v54, 1.0, v58
	v_rcp_f32_e32 v54, v54
	v_add_f32_e32 v55, 1.0, v55
	v_add_f32_e32 v56, 1.0, v56
	v_rcp_f32_e32 v55, v55
	v_rcp_f32_e32 v56, v56
	v_mul_f32_e32 v54, v60, v54
	v_mul_f32_e32 v58, v54, v52
	v_mul_f32_e32 v52, v65, v55
	v_mul_f32_e32 v54, v61, v56
	v_mul_f32_e32 v52, v52, v57
	v_mul_f32_e32 v53, v54, v53
	v_lshl_add_u64 v[54:55], v[66:67], 0, v[114:115]
	v_cvt_pk_bf16_f32 v50, v62, v50
	v_cvt_pk_bf16_f32 v51, v51, v52
	v_cvt_pk_bf16_f32 v52, v69, v59
	v_cvt_pk_bf16_f32 v53, v58, v53
	global_store_dwordx4 v[54:55], v[50:53], off
	s_nop 1
	v_mul_f32_e32 v50, 0xbfb8aa3b, v46
	v_exp_f32_e32 v50, v50
	v_mul_f32_e32 v51, 0xbfb8aa3b, v42
	v_exp_f32_e32 v51, v51
	v_add_u32_e32 v52, 0x90, v147
	v_add_f32_e32 v50, 1.0, v50
	v_rcp_f32_e32 v53, v50
	v_add_f32_e32 v50, 1.0, v51
	v_rcp_f32_e32 v54, v50
	v_mad_i64_i32 v[50:51], s[62:63], v52, s90, v[134:135]
	v_mul_f32_e32 v46, v46, v53
	v_mul_f32_e32 v46, v46, v38
	v_mul_f32_e32 v38, v42, v54
	v_mul_f32_e32 v42, 0xbfb8aa3b, v47
	v_exp_f32_e32 v42, v42
	v_mul_f32_e32 v52, 0xbfb8aa3b, v43
	v_mul_f32_e32 v53, v38, v34
	v_exp_f32_e32 v52, v52
	v_add_f32_e32 v34, 1.0, v42
	v_rcp_f32_e32 v34, v34
	v_mul_f32_e32 v42, 0xbfb8aa3b, v48
	v_exp_f32_e32 v42, v42
	v_add_f32_e32 v38, 1.0, v52
	v_mul_f32_e32 v34, v47, v34
	v_rcp_f32_e32 v38, v38
	v_mul_f32_e32 v34, v34, v39
	v_add_f32_e32 v39, 1.0, v42
	v_rcp_f32_e32 v39, v39
	v_mul_f32_e32 v38, v43, v38
	v_mul_f32_e32 v42, 0xbfb8aa3b, v44
	v_mul_f32_e32 v43, v38, v35
	v_mul_f32_e32 v35, v48, v39
	v_exp_f32_e32 v42, v42
	v_mul_f32_e32 v35, v35, v40
	v_mul_f32_e32 v39, 0xbfb8aa3b, v49
	v_mul_f32_e32 v40, 0xbfb8aa3b, v45
	v_exp_f32_e32 v39, v39
	v_exp_f32_e32 v40, v40
	v_add_f32_e32 v38, 1.0, v42
	v_rcp_f32_e32 v38, v38
	v_add_f32_e32 v39, 1.0, v39
	v_add_f32_e32 v40, 1.0, v40
	v_rcp_f32_e32 v39, v39
	v_rcp_f32_e32 v40, v40
	v_mul_f32_e32 v38, v44, v38
	v_mul_f32_e32 v42, v38, v36
	v_mul_f32_e32 v36, v49, v39
	v_mul_f32_e32 v38, v45, v40
	v_mul_f32_e32 v36, v36, v41
	v_mul_f32_e32 v37, v38, v37
	v_lshl_add_u64 v[38:39], v[50:51], 0, v[114:115]
	v_cvt_pk_bf16_f32 v34, v46, v34
	v_cvt_pk_bf16_f32 v35, v35, v36
	v_cvt_pk_bf16_f32 v36, v53, v43
	v_cvt_pk_bf16_f32 v37, v42, v37
	global_store_dwordx4 v[38:39], v[34:37], off
	s_nop 1
	v_mul_f32_e32 v34, 0xbfb8aa3b, v30
	v_exp_f32_e32 v34, v34
	v_mul_f32_e32 v35, 0xbfb8aa3b, v26
	v_exp_f32_e32 v35, v35
	v_add_u32_e32 v36, 0xa0, v147
	v_add_f32_e32 v34, 1.0, v34
	v_rcp_f32_e32 v37, v34
	v_add_f32_e32 v34, 1.0, v35
	v_rcp_f32_e32 v38, v34
	v_mad_i64_i32 v[34:35], s[62:63], v36, s90, v[134:135]
	v_mul_f32_e32 v30, v30, v37
	v_mul_f32_e32 v30, v30, v22
	v_mul_f32_e32 v22, v26, v38
	v_mul_f32_e32 v26, 0xbfb8aa3b, v31
	v_exp_f32_e32 v26, v26
	v_mul_f32_e32 v36, 0xbfb8aa3b, v27
	v_mul_f32_e32 v37, v22, v18
	v_exp_f32_e32 v36, v36
	v_add_f32_e32 v18, 1.0, v26
	v_rcp_f32_e32 v18, v18
	v_mul_f32_e32 v26, 0xbfb8aa3b, v32
	v_exp_f32_e32 v26, v26
	v_add_f32_e32 v22, 1.0, v36
	v_mul_f32_e32 v18, v31, v18
	v_rcp_f32_e32 v22, v22
	v_mul_f32_e32 v18, v18, v23
	v_add_f32_e32 v23, 1.0, v26
	v_rcp_f32_e32 v23, v23
	v_mul_f32_e32 v22, v27, v22
	v_mul_f32_e32 v26, 0xbfb8aa3b, v28
	v_mul_f32_e32 v27, v22, v19
	v_mul_f32_e32 v19, v32, v23
	v_exp_f32_e32 v26, v26
	v_mul_f32_e32 v19, v19, v24
	v_mul_f32_e32 v23, 0xbfb8aa3b, v33
	v_mul_f32_e32 v24, 0xbfb8aa3b, v29
	v_exp_f32_e32 v23, v23
	v_exp_f32_e32 v24, v24
	v_add_f32_e32 v22, 1.0, v26
	v_rcp_f32_e32 v22, v22
	v_add_f32_e32 v23, 1.0, v23
	v_add_f32_e32 v24, 1.0, v24
	v_rcp_f32_e32 v23, v23
	v_rcp_f32_e32 v24, v24
	v_mul_f32_e32 v22, v28, v22
	v_mul_f32_e32 v26, v22, v20
	v_mul_f32_e32 v20, v33, v23
	v_mul_f32_e32 v22, v29, v24
	v_mul_f32_e32 v20, v20, v25
	v_mul_f32_e32 v21, v22, v21
	v_lshl_add_u64 v[22:23], v[34:35], 0, v[114:115]
	v_cvt_pk_bf16_f32 v18, v30, v18
	v_cvt_pk_bf16_f32 v19, v19, v20
	v_cvt_pk_bf16_f32 v20, v37, v27
	v_cvt_pk_bf16_f32 v21, v26, v21
	global_store_dwordx4 v[22:23], v[18:21], off
	s_nop 1
	v_mul_f32_e32 v18, 0xbfb8aa3b, v14
	v_exp_f32_e32 v18, v18
	v_mul_f32_e32 v19, 0xbfb8aa3b, v10
	v_exp_f32_e32 v19, v19
	v_add_u32_e32 v20, 0xb0, v147
	v_add_f32_e32 v18, 1.0, v18
	v_rcp_f32_e32 v21, v18
	v_add_f32_e32 v18, 1.0, v19
	v_rcp_f32_e32 v22, v18
	v_mad_i64_i32 v[18:19], s[62:63], v20, s90, v[134:135]
	v_mul_f32_e32 v14, v14, v21
	v_mul_f32_e32 v14, v14, v6
	v_mul_f32_e32 v6, v10, v22
	v_mul_f32_e32 v10, 0xbfb8aa3b, v15
	v_exp_f32_e32 v10, v10
	v_mul_f32_e32 v20, 0xbfb8aa3b, v11
	v_mul_f32_e32 v21, v6, v2
	v_exp_f32_e32 v20, v20
	v_add_f32_e32 v2, 1.0, v10
	v_rcp_f32_e32 v2, v2
	v_mul_f32_e32 v10, 0xbfb8aa3b, v16
	v_exp_f32_e32 v10, v10
	v_add_f32_e32 v6, 1.0, v20
	v_mul_f32_e32 v2, v15, v2
	v_rcp_f32_e32 v6, v6
	v_mul_f32_e32 v2, v2, v7
	v_add_f32_e32 v7, 1.0, v10
	v_rcp_f32_e32 v7, v7
	v_mul_f32_e32 v6, v11, v6
	v_mul_f32_e32 v10, 0xbfb8aa3b, v12
	v_mul_f32_e32 v11, v6, v3
	v_mul_f32_e32 v3, v16, v7
	v_exp_f32_e32 v10, v10
	v_mul_f32_e32 v3, v3, v8
	v_mul_f32_e32 v7, 0xbfb8aa3b, v17
	v_mul_f32_e32 v8, 0xbfb8aa3b, v13
	v_exp_f32_e32 v7, v7
	v_exp_f32_e32 v8, v8
	v_add_f32_e32 v6, 1.0, v10
	v_rcp_f32_e32 v6, v6
	v_add_f32_e32 v7, 1.0, v7
	v_add_f32_e32 v8, 1.0, v8
	v_rcp_f32_e32 v7, v7
	v_rcp_f32_e32 v8, v8
	v_mul_f32_e32 v6, v12, v6
	v_mul_f32_e32 v10, v6, v4
	v_mul_f32_e32 v4, v17, v7
	v_mul_f32_e32 v6, v13, v8
	v_mul_f32_e32 v4, v4, v9
	v_mul_f32_e32 v5, v6, v5
	v_lshl_add_u64 v[6:7], v[18:19], 0, v[114:115]
	s_mov_b64 s[62:63], s[16:17]
	v_cvt_pk_bf16_f32 v2, v14, v2
	v_cvt_pk_bf16_f32 v3, v3, v4
	v_cvt_pk_bf16_f32 v4, v21, v11
	v_cvt_pk_bf16_f32 v5, v10, v5
	global_store_dwordx4 v[6:7], v[2:5], off
	s_cbranch_vccz .LBB0_135
	s_waitcnt vmcnt(0)
	s_cmpk_gt_u32 s3, 0xff
	s_cbranch_scc1 .LBB0_142
	s_barrier

; #define PG8_STAGE(bufoff, gbase, voff) do { _Pragma("unroll") for (int _i = 0; _i < 2; ++_i) \
;         asm volatile("s_mov_b32 m0, %2\n\ts_nop 0\n\tglobal_load_lds_dwordx4 %0, %1" :: "v"((voff)[_i]), "s"((const char*)(gbase)), "s"(ldsbase + (unsigned)(bufoff) + ldsw + (unsigned)_i * 8192u) : "memory", "m0"); } while (0)
; #define PG8_LDA(dst, b, h) do { _Pragma("unroll") for (int m = 0; m < 4; ++m) _Pragma("unroll") for (int k = 0; k < 2; ++k) dst[m][k] = *(const PG8_LAS bf16x8*)(lds + PG8_SA(b, h) + aoff + m * 2048 + k * 1024); } while (0)
; #define PG8_WAIT_V(n) asm volatile("s_waitcnt vmcnt(" #n ")" ::: "memory")
; #define PG8_WAIT_L(n) asm volatile("s_waitcnt lgkmcnt(" #n ")" ::: "memory")
; template <class Epi, class Sched, bool ALIGN_EPI = false, bool SP2 = false>
; __device__ __forceinline__ void gemm_phase(PG8_LAS unsigned char* lds, const Gemm g, const Sched& S, const Epi& E) {
;     ...
;             const char* a1 = cA + (size_t)(t + 1) * kstep;
;             const char* a2 = last ? nA : cA + (size_t)(t + 2) * kstep; const char* b2 = last ? nB : cB + (size_t)(t + 2) * kstep;
;             const char* a3 = a2 + kstep; const char* b3 = b2 + kstep;
;             if (last && has_next) S.a_ready(nxt);
;             if constexpr (epi_has_mid<Epi>::value) { if (t == Epi::MID_T) E.mid(acc, cur, wr, wc, fr, fq); }
;             if constexpr (SP2) {
;             PG8_LDB(B0, 0, 0); PG8_LDB(B1, 0, 1); PG8_SCHED; PG8_LDA(At, 0, 0); PG8_STAGE(PG8_SA(1, 1), a1 + hstep, voffA);
;             PG8_WAIT_V(8); PG8_WAIT_L(0); PG8_BAR; PG8_MMA(0, 0, At, B0); PG8_MMA(0, 1, At, B1); PG8_BAR; PG8_SCHED;
;             PG8_LDA(At, 0, 1); PG8_STAGE(PG8_SB(0, 0), b2, voffB); PG8_STAGE(PG8_SB(0, 1), b2 + hstep, voffB); PG8_STAGE(PG8_SA(0, 0), a2, voffA);
;             PG8_WAIT_V(8); PG8_WAIT_L(0); PG8_BAR; PG8_MMA(1, 0, At, B0); PG8_MMA(1, 1, At, B1); PG8_BAR; PG8_SCHED;
;             PG8_LDB(B0, 1, 0); PG8_LDB(B1, 1, 1); PG8_SCHED; PG8_LDA(At, 1, 0); PG8_STAGE(PG8_SA(0, 1), a2 + hstep, voffA);
;             PG8_WAIT_V(8); PG8_WAIT_L(0); PG8_BAR; PG8_MMA(0, 0, At, B0); PG8_MMA(0, 1, At, B1); PG8_BAR; PG8_SCHED;
;             PG8_LDA(At, 1, 1); PG8_STAGE(PG8_SB(1, 0), b3, voffB); PG8_STAGE(PG8_SB(1, 1), b3 + hstep, voffB); PG8_STAGE(PG8_SA(1, 0), a3, voffA);
;             PG8_WAIT_V(8); PG8_WAIT_L(0); PG8_BAR; PG8_MMA(1, 0, At, B0); PG8_MMA(1, 1, At, B1); PG8_BAR; PG8_SCHED;
.LBB0_234:
	ds_read_b128 v[134:137], v145
	ds_read_b128 v[152:155], v145 offset:1024
	ds_read_b128 v[156:159], v145 offset:2048
	ds_read_b128 v[160:163], v145 offset:3072
	ds_read_b128 v[164:167], v146
	ds_read_b128 v[168:171], v146 offset:1024
	ds_read_b128 v[172:175], v146 offset:2048
	ds_read_b128 v[176:179], v146 offset:3072
	s_cmpk_eq_i32 s57, 0xa8
	s_cselect_b32 s76, s4, s53
	s_cselect_b32 s77, s5, s54
	s_cselect_b32 s66, s46, s55
	s_cselect_b32 s67, s47, s56
	s_add_u32 s62, s76, 0x80
	s_addc_u32 s63, s77, 0
	ds_read_b128 v[180:183], v147
	ds_read_b128 v[184:187], v147 offset:1024
	ds_read_b128 v[188:191], v147 offset:2048
	ds_read_b128 v[192:195], v147 offset:3072
	ds_read_b128 v[196:199], v147 offset:4096
	ds_read_b128 v[200:203], v147 offset:5120
	ds_read_b128 v[204:207], v147 offset:6144
	ds_read_b128 v[208:211], v147 offset:7168
	s_mov_b32 m0, s94
	s_nop 0
	global_load_lds_dwordx4 v1, s[50:51]
	s_nop 0
	s_mov_b32 m0, s95
	s_nop 0
	global_load_lds_dwordx4 v141, s[50:51]
	s_waitcnt vmcnt(8)
	s_waitcnt lgkmcnt(0)
	s_barrier
	s_setprio 1
	s_waitcnt lgkmcnt(7)
	v_mfma_f32_16x16x32_bf16 v[126:129], v[134:137], v[180:183], v[126:129]
	v_mfma_f32_16x16x32_bf16 v[122:125], v[156:159], v[180:183], v[122:125]
	s_waitcnt lgkmcnt(5)
	v_mfma_f32_16x16x32_bf16 v[106:109], v[156:159], v[188:191], v[106:109]
	v_mfma_f32_16x16x32_bf16 v[110:113], v[134:137], v[188:191], v[110:113]
	s_waitcnt lgkmcnt(3)
	v_mfma_f32_16x16x32_bf16 v[94:97], v[134:137], v[196:199], v[94:97]
	v_mfma_f32_16x16x32_bf16 v[90:93], v[156:159], v[196:199], v[90:93]
	s_waitcnt lgkmcnt(1)
	v_mfma_f32_16x16x32_bf16 v[74:77], v[156:159], v[204:207], v[74:77]
	v_mfma_f32_16x16x32_bf16 v[78:81], v[134:137], v[204:207], v[78:81]
	v_mfma_f32_16x16x32_bf16 v[126:129], v[152:155], v[184:187], v[126:129]
	v_mfma_f32_16x16x32_bf16 v[122:125], v[160:163], v[184:187], v[122:125]
	v_mfma_f32_16x16x32_bf16 v[106:109], v[160:163], v[192:195], v[106:109]
	v_mfma_f32_16x16x32_bf16 v[110:113], v[152:155], v[192:195], v[110:113]
	v_mfma_f32_16x16x32_bf16 v[94:97], v[152:155], v[200:203], v[94:97]
	v_mfma_f32_16x16x32_bf16 v[90:93], v[160:163], v[200:203], v[90:93]
	s_waitcnt lgkmcnt(0)
	v_mfma_f32_16x16x32_bf16 v[74:77], v[160:163], v[208:211], v[74:77]
	v_mfma_f32_16x16x32_bf16 v[78:81], v[152:155], v[208:211], v[78:81]
	s_setprio 0
	s_setprio 1
	v_mfma_f32_16x16x32_bf16 v[118:121], v[164:167], v[180:183], v[118:121]
	v_mfma_f32_16x16x32_bf16 v[114:117], v[172:175], v[180:183], v[114:117]
	v_mfma_f32_16x16x32_bf16 v[98:101], v[172:175], v[188:191], v[98:101]
	v_mfma_f32_16x16x32_bf16 v[102:105], v[164:167], v[188:191], v[102:105]
	v_mfma_f32_16x16x32_bf16 v[86:89], v[164:167], v[196:199], v[86:89]
	v_mfma_f32_16x16x32_bf16 v[82:85], v[172:175], v[196:199], v[82:85]
	v_mfma_f32_16x16x32_bf16 v[66:69], v[172:175], v[204:207], v[66:69]
	v_mfma_f32_16x16x32_bf16 v[70:73], v[164:167], v[204:207], v[70:73]
	v_mfma_f32_16x16x32_bf16 v[118:121], v[168:171], v[184:187], v[118:121]
	v_mfma_f32_16x16x32_bf16 v[114:117], v[176:179], v[184:187], v[114:117]
	v_mfma_f32_16x16x32_bf16 v[98:101], v[176:179], v[192:195], v[98:101]
	v_mfma_f32_16x16x32_bf16 v[102:105], v[168:171], v[192:195], v[102:105]
	v_mfma_f32_16x16x32_bf16 v[86:89], v[168:171], v[200:203], v[86:89]
	v_mfma_f32_16x16x32_bf16 v[82:85], v[176:179], v[200:203], v[82:85]
	v_mfma_f32_16x16x32_bf16 v[70:73], v[168:171], v[208:211], v[70:73]
	s_setprio 2
	s_barrier
	v_mfma_f32_16x16x32_bf16 v[66:69], v[176:179], v[208:211], v[66:69]
	s_setprio 0
	ds_read_b128 v[180:183], v147 offset:16384
	ds_read_b128 v[184:187], v147 offset:17408
	ds_read_b128 v[188:191], v147 offset:18432
	ds_read_b128 v[192:195], v147 offset:19456
	ds_read_b128 v[196:199], v147 offset:20480
	ds_read_b128 v[200:203], v147 offset:21504
	ds_read_b128 v[204:207], v147 offset:22528
	ds_read_b128 v[252:255], v147 offset:23552
	s_mov_b32 m0, s64
	s_nop 0
	global_load_lds_dwordx4 v140, s[66:67]
	s_add_u32 s58, s66, 0x2b0000
	s_mov_b32 m0, s65
	s_nop 0
	global_load_lds_dwordx4 v142, s[66:67]
	s_addc_u32 s59, s67, 0
	s_mov_b32 m0, s82
	s_nop 0
	global_load_lds_dwordx4 v140, s[58:59]
	s_nop 0
	s_mov_b32 m0, s83
	s_nop 0
	global_load_lds_dwordx4 v142, s[58:59]
	s_nop 0
	s_mov_b32 m0, s35
	s_nop 0
	global_load_lds_dwordx4 v1, s[76:77]
	s_nop 0
	s_mov_b32 m0, s84
	s_nop 0
	global_load_lds_dwordx4 v141, s[76:77]
	s_waitcnt vmcnt(8)
	s_waitcnt lgkmcnt(0)
	s_barrier
	s_setprio 1
	s_waitcnt lgkmcnt(7)
	v_mfma_f32_16x16x32_bf16 v[62:65], v[134:137], v[180:183], v[62:65]
	v_mfma_f32_16x16x32_bf16 v[58:61], v[156:159], v[180:183], v[58:61]
	s_waitcnt lgkmcnt(5)
	v_mfma_f32_16x16x32_bf16 v[42:45], v[156:159], v[188:191], v[42:45]
	v_mfma_f32_16x16x32_bf16 v[46:49], v[134:137], v[188:191], v[46:49]
	s_waitcnt lgkmcnt(3)
	v_mfma_f32_16x16x32_bf16 v[30:33], v[134:137], v[196:199], v[30:33]
	v_mfma_f32_16x16x32_bf16 v[26:29], v[156:159], v[196:199], v[26:29]
	s_waitcnt lgkmcnt(1)
	v_mfma_f32_16x16x32_bf16 v[10:13], v[156:159], v[204:207], v[10:13]
	v_mfma_f32_16x16x32_bf16 v[14:17], v[134:137], v[204:207], v[14:17]
	v_mfma_f32_16x16x32_bf16 v[62:65], v[152:155], v[184:187], v[62:65]
	v_mfma_f32_16x16x32_bf16 v[58:61], v[160:163], v[184:187], v[58:61]
	v_mfma_f32_16x16x32_bf16 v[42:45], v[160:163], v[192:195], v[42:45]
	v_mfma_f32_16x16x32_bf16 v[46:49], v[152:155], v[192:195], v[46:49]
	v_mfma_f32_16x16x32_bf16 v[30:33], v[152:155], v[200:203], v[30:33]
	v_mfma_f32_16x16x32_bf16 v[26:29], v[160:163], v[200:203], v[26:29]
	s_waitcnt lgkmcnt(0)
	v_mfma_f32_16x16x32_bf16 v[10:13], v[160:163], v[252:255], v[10:13]
	v_mfma_f32_16x16x32_bf16 v[14:17], v[152:155], v[252:255], v[14:17]
	s_setprio 0
	s_setprio 1
	v_mfma_f32_16x16x32_bf16 v[54:57], v[164:167], v[180:183], v[54:57]
	v_mfma_f32_16x16x32_bf16 v[50:53], v[172:175], v[180:183], v[50:53]
	v_mfma_f32_16x16x32_bf16 v[34:37], v[172:175], v[188:191], v[34:37]
	v_mfma_f32_16x16x32_bf16 v[38:41], v[164:167], v[188:191], v[38:41]
	v_mfma_f32_16x16x32_bf16 v[22:25], v[164:167], v[196:199], v[22:25]
	v_mfma_f32_16x16x32_bf16 v[18:21], v[172:175], v[196:199], v[18:21]
	v_mfma_f32_16x16x32_bf16 v[2:5], v[172:175], v[204:207], v[2:5]
	v_mfma_f32_16x16x32_bf16 v[6:9], v[164:167], v[204:207], v[6:9]
	v_mfma_f32_16x16x32_bf16 v[54:57], v[168:171], v[184:187], v[54:57]
	v_mfma_f32_16x16x32_bf16 v[50:53], v[176:179], v[184:187], v[50:53]
	v_mfma_f32_16x16x32_bf16 v[34:37], v[176:179], v[192:195], v[34:37]
	v_mfma_f32_16x16x32_bf16 v[38:41], v[168:171], v[192:195], v[38:41]
	v_mfma_f32_16x16x32_bf16 v[22:25], v[168:171], v[200:203], v[22:25]
	v_mfma_f32_16x16x32_bf16 v[18:21], v[176:179], v[200:203], v[18:21]
	v_mfma_f32_16x16x32_bf16 v[6:9], v[168:171], v[252:255], v[6:9]
	s_setprio 2
	s_barrier
; #define PG8_STAGE(bufoff, gbase, voff) do { _Pragma("unroll") for (int _i = 0; _i < 2; ++_i) \
;         asm volatile("s_mov_b32 m0, %2\n\ts_nop 0\n\tglobal_load_lds_dwordx4 %0, %1" :: "v"((voff)[_i]), "s"((const char*)(gbase)), "s"(ldsbase + (unsigned)(bufoff) + ldsw + (unsigned)_i * 8192u) : "memory", "m0"); } while (0)
; #define PG8_LDA(dst, b, h) do { _Pragma("unroll") for (int m = 0; m < 4; ++m) _Pragma("unroll") for (int k = 0; k < 2; ++k) dst[m][k] = *(const PG8_LAS bf16x8*)(lds + PG8_SA(b, h) + aoff + m * 2048 + k * 1024); } while (0)
; #define PG8_LDB(dst, b, h) do { _Pragma("unroll") for (int n = 0; n < 2; ++n) _Pragma("unroll") for (int k = 0; k < 2; ++k) dst[n][k] = *(const PG8_LAS bf16x8*)(lds + PG8_SB(b, h) + boff + n * 2048 + k * 1024); } while (0)
; #define PG8_MMA(ai, bj, At, Bt) do { __builtin_amdgcn_s_setprio(1); _Pragma("unroll") for (int m = 0; m < 4; ++m) _Pragma("unroll") for (int n = 0; n < 2; ++n) _Pragma("unroll") for (int k = 0; k < 2; ++k) \
;         acc[ai][bj][m][n] = __builtin_amdgcn_mfma_f32_16x16x32_bf16(Bt[n][k], At[m][k], acc[ai][bj][m][n], 0, 0, 0); __builtin_amdgcn_s_setprio(0); } while (0)
; #define PG8_WAIT_V(n) asm volatile("s_waitcnt vmcnt(" #n ")" ::: "memory")
; #define PG8_WAIT_L(n) asm volatile("s_waitcnt lgkmcnt(" #n ")" ::: "memory")
; #define PG8_BAR __builtin_amdgcn_s_barrier()
; #define PG8_SCHED __builtin_amdgcn_sched_barrier(0)
; template <class Epi, class Sched, bool ALIGN_EPI = false, bool SP2 = false>
; __device__ __forceinline__ void gemm_phase(PG8_LAS unsigned char* lds, const Gemm g, const Sched& S, const Epi& E) {
;     ...
;             PG8_WAIT_V(8); PG8_WAIT_L(0); PG8_BAR; PG8_MMA(1, 0, At, B0); PG8_MMA(1, 1, At, B1); PG8_BAR; PG8_SCHED;
;             PG8_LDB(B0, 1, 0); PG8_LDB(B1, 1, 1); PG8_SCHED; PG8_LDA(At, 1, 0); PG8_STAGE(PG8_SA(0, 1), a2 + hstep, voffA);
;             PG8_WAIT_V(8); PG8_WAIT_L(0); PG8_BAR; PG8_MMA(0, 0, At, B0); PG8_MMA(0, 1, At, B1); PG8_BAR; PG8_SCHED;
	v_mfma_f32_16x16x32_bf16 v[2:5], v[176:179], v[252:255], v[2:5]
	s_setprio 0
	ds_read_b128 v[134:137], v148
	ds_read_b128 v[152:155], v148 offset:1024
	ds_read_b128 v[156:159], v148 offset:2048
	ds_read_b128 v[160:163], v148 offset:3072
	ds_read_b128 v[164:167], v149
	ds_read_b128 v[168:171], v149 offset:1024
	ds_read_b128 v[172:175], v149 offset:2048
	ds_read_b128 v[248:251], v149 offset:3072
	ds_read_b128 v[180:183], v147 offset:32768
	ds_read_b128 v[184:187], v147 offset:33792
	ds_read_b128 v[188:191], v147 offset:34816
	ds_read_b128 v[192:195], v147 offset:35840
	ds_read_b128 v[196:199], v147 offset:36864
	ds_read_b128 v[200:203], v147 offset:37888
	ds_read_b128 v[204:207], v147 offset:38912
	ds_read_b128 v[208:211], v147 offset:39936
	s_add_u32 s58, s76, 0x2b0000
	s_addc_u32 s59, s77, 0
	s_mov_b32 m0, s85
	s_nop 0
	global_load_lds_dwordx4 v1, s[58:59]
	s_nop 0
	s_mov_b32 m0, s86
	s_nop 0
	global_load_lds_dwordx4 v141, s[58:59]
	s_waitcnt vmcnt(8)
	s_waitcnt lgkmcnt(0)
	s_barrier
	s_setprio 1
	s_waitcnt lgkmcnt(7)
	v_mfma_f32_16x16x32_bf16 v[126:129], v[134:137], v[180:183], v[126:129]
	v_mfma_f32_16x16x32_bf16 v[122:125], v[156:159], v[180:183], v[122:125]
	s_waitcnt lgkmcnt(5)
	v_mfma_f32_16x16x32_bf16 v[106:109], v[156:159], v[188:191], v[106:109]
	v_mfma_f32_16x16x32_bf16 v[110:113], v[134:137], v[188:191], v[110:113]
	s_waitcnt lgkmcnt(3)
	v_mfma_f32_16x16x32_bf16 v[94:97], v[134:137], v[196:199], v[94:97]
	v_mfma_f32_16x16x32_bf16 v[90:93], v[156:159], v[196:199], v[90:93]
	s_waitcnt lgkmcnt(1)
	v_mfma_f32_16x16x32_bf16 v[74:77], v[156:159], v[204:207], v[74:77]
	v_mfma_f32_16x16x32_bf16 v[78:81], v[134:137], v[204:207], v[78:81]
	v_mfma_f32_16x16x32_bf16 v[126:129], v[152:155], v[184:187], v[126:129]
	v_mfma_f32_16x16x32_bf16 v[122:125], v[160:163], v[184:187], v[122:125]
	v_mfma_f32_16x16x32_bf16 v[106:109], v[160:163], v[192:195], v[106:109]
	v_mfma_f32_16x16x32_bf16 v[110:113], v[152:155], v[192:195], v[110:113]
	v_mfma_f32_16x16x32_bf16 v[94:97], v[152:155], v[200:203], v[94:97]
	v_mfma_f32_16x16x32_bf16 v[90:93], v[160:163], v[200:203], v[90:93]
	s_waitcnt lgkmcnt(0)
	v_mfma_f32_16x16x32_bf16 v[74:77], v[160:163], v[208:211], v[74:77]
	v_mfma_f32_16x16x32_bf16 v[78:81], v[152:155], v[208:211], v[78:81]
	s_setprio 0
	s_setprio 1
	v_mfma_f32_16x16x32_bf16 v[118:121], v[164:167], v[180:183], v[118:121]
	v_mfma_f32_16x16x32_bf16 v[114:117], v[172:175], v[180:183], v[114:117]
	v_mfma_f32_16x16x32_bf16 v[98:101], v[172:175], v[188:191], v[98:101]
	v_mfma_f32_16x16x32_bf16 v[102:105], v[164:167], v[188:191], v[102:105]
	v_mfma_f32_16x16x32_bf16 v[86:89], v[164:167], v[196:199], v[86:89]
	v_mfma_f32_16x16x32_bf16 v[82:85], v[172:175], v[196:199], v[82:85]
	v_mfma_f32_16x16x32_bf16 v[66:69], v[172:175], v[204:207], v[66:69]
	v_mfma_f32_16x16x32_bf16 v[70:73], v[164:167], v[204:207], v[70:73]
	v_mfma_f32_16x16x32_bf16 v[118:121], v[168:171], v[184:187], v[118:121]
	v_mfma_f32_16x16x32_bf16 v[114:117], v[248:251], v[184:187], v[114:117]
	v_mfma_f32_16x16x32_bf16 v[98:101], v[248:251], v[192:195], v[98:101]
	v_mfma_f32_16x16x32_bf16 v[102:105], v[168:171], v[192:195], v[102:105]
	v_mfma_f32_16x16x32_bf16 v[86:89], v[168:171], v[200:203], v[86:89]
	v_mfma_f32_16x16x32_bf16 v[82:85], v[248:251], v[200:203], v[82:85]
	v_mfma_f32_16x16x32_bf16 v[70:73], v[168:171], v[208:211], v[70:73]
	s_setprio 2
	s_barrier
; #define PG8_STAGE(bufoff, gbase, voff) do { _Pragma("unroll") for (int _i = 0; _i < 2; ++_i) \
;         asm volatile("s_mov_b32 m0, %2\n\ts_nop 0\n\tglobal_load_lds_dwordx4 %0, %1" :: "v"((voff)[_i]), "s"((const char*)(gbase)), "s"(ldsbase + (unsigned)(bufoff) + ldsw + (unsigned)_i * 8192u) : "memory", "m0"); } while (0)
; #define PG8_LDA(dst, b, h) do { _Pragma("unroll") for (int m = 0; m < 4; ++m) _Pragma("unroll") for (int k = 0; k < 2; ++k) dst[m][k] = *(const PG8_LAS bf16x8*)(lds + PG8_SA(b, h) + aoff + m * 2048 + k * 1024); } while (0)
; #define PG8_MMA(ai, bj, At, Bt) do { __builtin_amdgcn_s_setprio(1); _Pragma("unroll") for (int m = 0; m < 4; ++m) _Pragma("unroll") for (int n = 0; n < 2; ++n) _Pragma("unroll") for (int k = 0; k < 2; ++k) \
;         acc[ai][bj][m][n] = __builtin_amdgcn_mfma_f32_16x16x32_bf16(Bt[n][k], At[m][k], acc[ai][bj][m][n], 0, 0, 0); __builtin_amdgcn_s_setprio(0); } while (0)
; #define PG8_WAIT_V(n) asm volatile("s_waitcnt vmcnt(" #n ")" ::: "memory")
; #define PG8_WAIT_L(n) asm volatile("s_waitcnt lgkmcnt(" #n ")" ::: "memory")
; #define PG8_BAR __builtin_amdgcn_s_barrier()
; #define PG8_SCHED __builtin_amdgcn_sched_barrier(0)
; template <class Epi, class Sched, bool ALIGN_EPI = false, bool SP2 = false>
; __device__ __forceinline__ void gemm_phase(PG8_LAS unsigned char* lds, const Gemm g, const Sched& S, const Epi& E) {
;     ...
;             PG8_LDA(At, 1, 1); PG8_STAGE(PG8_SB(1, 0), b3, voffB); PG8_STAGE(PG8_SB(1, 1), b3 + hstep, voffB); PG8_STAGE(PG8_SA(1, 0), a3, voffA);
;             PG8_WAIT_V(8); PG8_WAIT_L(0); PG8_BAR; PG8_MMA(1, 0, At, B0); PG8_MMA(1, 1, At, B1); PG8_BAR; PG8_SCHED;
;     ...
;         if constexpr (ALIGN_EPI) { if (wr == 0) PG8_BAR; }
	v_mfma_f32_16x16x32_bf16 v[66:69], v[248:251], v[208:211], v[66:69]
	s_setprio 0
	ds_read_b128 v[180:183], v147 offset:49152
	ds_read_b128 v[184:187], v147 offset:50176
	ds_read_b128 v[188:191], v147 offset:51200
	ds_read_b128 v[192:195], v147 offset:52224
	ds_read_b128 v[196:199], v147 offset:53248
	ds_read_b128 v[200:203], v147 offset:54272
	ds_read_b128 v[204:207], v147 offset:55296
	ds_read_b128 v[252:255], v147 offset:56320
	s_add_u32 s58, s66, 0x80
	s_addc_u32 s59, s67, 0
	s_mov_b32 m0, s88
	s_nop 0
	global_load_lds_dwordx4 v140, s[58:59]
	s_nop 0
	s_mov_b32 m0, s89
	s_nop 0
	global_load_lds_dwordx4 v142, s[58:59]
	s_add_u32 s58, s66, 0x2b0080
	s_addc_u32 s59, s67, 0
	s_mov_b32 m0, s92
	s_nop 0
	global_load_lds_dwordx4 v140, s[58:59]
	s_nop 0
	s_mov_b32 m0, s93
	s_nop 0
	global_load_lds_dwordx4 v142, s[58:59]
	s_nop 0
	s_mov_b32 m0, s90
	s_nop 0
	global_load_lds_dwordx4 v1, s[62:63]
	s_nop 0
	s_mov_b32 m0, s91
	s_nop 0
	global_load_lds_dwordx4 v141, s[62:63]
	s_waitcnt vmcnt(8)
	s_waitcnt lgkmcnt(0)
	s_barrier
	s_setprio 1
	s_waitcnt lgkmcnt(7)
	v_mfma_f32_16x16x32_bf16 v[62:65], v[134:137], v[180:183], v[62:65]
	v_mfma_f32_16x16x32_bf16 v[58:61], v[156:159], v[180:183], v[58:61]
	s_waitcnt lgkmcnt(5)
	v_mfma_f32_16x16x32_bf16 v[42:45], v[156:159], v[188:191], v[42:45]
	v_mfma_f32_16x16x32_bf16 v[46:49], v[134:137], v[188:191], v[46:49]
	s_waitcnt lgkmcnt(3)
	v_mfma_f32_16x16x32_bf16 v[30:33], v[134:137], v[196:199], v[30:33]
	v_mfma_f32_16x16x32_bf16 v[26:29], v[156:159], v[196:199], v[26:29]
	s_waitcnt lgkmcnt(1)
	v_mfma_f32_16x16x32_bf16 v[10:13], v[156:159], v[204:207], v[10:13]
	v_mfma_f32_16x16x32_bf16 v[14:17], v[134:137], v[204:207], v[14:17]
	v_mfma_f32_16x16x32_bf16 v[62:65], v[152:155], v[184:187], v[62:65]
	v_mfma_f32_16x16x32_bf16 v[58:61], v[160:163], v[184:187], v[58:61]
	v_mfma_f32_16x16x32_bf16 v[42:45], v[160:163], v[192:195], v[42:45]
	v_mfma_f32_16x16x32_bf16 v[46:49], v[152:155], v[192:195], v[46:49]
	v_mfma_f32_16x16x32_bf16 v[30:33], v[152:155], v[200:203], v[30:33]
	v_mfma_f32_16x16x32_bf16 v[26:29], v[160:163], v[200:203], v[26:29]
	s_waitcnt lgkmcnt(0)
	v_mfma_f32_16x16x32_bf16 v[10:13], v[160:163], v[252:255], v[10:13]
	v_mfma_f32_16x16x32_bf16 v[14:17], v[152:155], v[252:255], v[14:17]
	s_setprio 0
	s_setprio 1
	v_mfma_f32_16x16x32_bf16 v[54:57], v[164:167], v[180:183], v[54:57]
	v_mfma_f32_16x16x32_bf16 v[50:53], v[172:175], v[180:183], v[50:53]
	v_mfma_f32_16x16x32_bf16 v[34:37], v[172:175], v[188:191], v[34:37]
	v_mfma_f32_16x16x32_bf16 v[38:41], v[164:167], v[188:191], v[38:41]
	v_mfma_f32_16x16x32_bf16 v[22:25], v[164:167], v[196:199], v[22:25]
	v_mfma_f32_16x16x32_bf16 v[18:21], v[172:175], v[196:199], v[18:21]
	v_mfma_f32_16x16x32_bf16 v[2:5], v[172:175], v[204:207], v[2:5]
	v_mfma_f32_16x16x32_bf16 v[6:9], v[164:167], v[204:207], v[6:9]
	v_mfma_f32_16x16x32_bf16 v[54:57], v[168:171], v[184:187], v[54:57]
	v_mfma_f32_16x16x32_bf16 v[50:53], v[248:251], v[184:187], v[50:53]
	v_mfma_f32_16x16x32_bf16 v[34:37], v[248:251], v[192:195], v[34:37]
	v_mfma_f32_16x16x32_bf16 v[38:41], v[168:171], v[192:195], v[38:41]
	v_mfma_f32_16x16x32_bf16 v[22:25], v[168:171], v[200:203], v[22:25]
	v_mfma_f32_16x16x32_bf16 v[18:21], v[248:251], v[200:203], v[18:21]
	v_mfma_f32_16x16x32_bf16 v[6:9], v[168:171], v[252:255], v[6:9]
	s_setprio 2
	s_barrier
	v_mfma_f32_16x16x32_bf16 v[2:5], v[248:251], v[252:255], v[2:5]
	s_setprio 0
	s_add_i32 s57, s57, 2
	s_add_u32 s53, s53, 0x100
	s_addc_u32 s54, s54, 0
	s_add_u32 s55, s55, 0x100
	s_addc_u32 s56, s56, 0
	s_add_u32 s50, s50, 0x100
	s_addc_u32 s51, s51, 0
	s_cmpk_gt_u32 s57, 0xa9
	s_cbranch_scc0 .LBB0_234
	s_and_b64 vcc, exec, s[16:17]
	s_cbranch_vccz .LBB0_237
	s_barrier

; #define PG8_STAGE(bufoff, gbase, voff) do { _Pragma("unroll") for (int _i = 0; _i < 2; ++_i) \
;         asm volatile("s_mov_b32 m0, %2\n\ts_nop 0\n\tglobal_load_lds_dwordx4 %0, %1" :: "v"((voff)[_i]), "s"((const char*)(gbase)), "s"(ldsbase + (unsigned)(bufoff) + ldsw + (unsigned)_i * 8192u) : "memory", "m0"); } while (0)
; #define PG8_LDA(dst, b, h) do { _Pragma("unroll") for (int m = 0; m < 4; ++m) _Pragma("unroll") for (int k = 0; k < 2; ++k) dst[m][k] = *(const PG8_LAS bf16x8*)(lds + PG8_SA(b, h) + aoff + m * 2048 + k * 1024); } while (0)
; #define PG8_LDB(dst, b, h) do { _Pragma("unroll") for (int n = 0; n < 2; ++n) _Pragma("unroll") for (int k = 0; k < 2; ++k) dst[n][k] = *(const PG8_LAS bf16x8*)(lds + PG8_SB(b, h) + boff + n * 2048 + k * 1024); } while (0)
; #define PG8_MMA(ai, bj, At, Bt) do { __builtin_amdgcn_s_setprio(1); _Pragma("unroll") for (int m = 0; m < 4; ++m) _Pragma("unroll") for (int n = 0; n < 2; ++n) _Pragma("unroll") for (int k = 0; k < 2; ++k) \
;         acc[ai][bj][m][n] = __builtin_amdgcn_mfma_f32_16x16x32_bf16(Bt[n][k], At[m][k], acc[ai][bj][m][n], 0, 0, 0); __builtin_amdgcn_s_setprio(0); } while (0)
; template <class Epi, class Sched, bool ALIGN_EPI = false, bool SP2 = false>
; __device__ __forceinline__ void gemm_phase(PG8_LAS unsigned char* lds, const Gemm g, const Sched& S, const Epi& E) {
;     ...
;             const bool last = (t == nt - 2);
;             const char* a1 = cA + (size_t)(t + 1) * kstep;
;             const char* a2 = last ? nA : cA + (size_t)(t + 2) * kstep; const char* b2 = last ? nB : cB + (size_t)(t + 2) * kstep;
;             const char* a3 = a2 + kstep; const char* b3 = b2 + kstep;
;             if (last && has_next) S.a_ready(nxt);
;             if constexpr (epi_has_mid<Epi>::value) { if (t == Epi::MID_T) E.mid(acc, cur, wr, wc, fr, fq); }
;             if constexpr (SP2) {
;             PG8_LDB(B0, 0, 0); PG8_LDB(B1, 0, 1); PG8_SCHED; PG8_LDA(At, 0, 0); PG8_STAGE(PG8_SA(1, 1), a1 + hstep, voffA);
;             PG8_WAIT_V(8); PG8_WAIT_L(0); PG8_BAR; PG8_MMA(0, 0, At, B0); PG8_MMA(0, 1, At, B1); PG8_BAR; PG8_SCHED;
;             PG8_LDA(At, 0, 1); PG8_STAGE(PG8_SB(0, 0), b2, voffB); PG8_STAGE(PG8_SB(0, 1), b2 + hstep, voffB); PG8_STAGE(PG8_SA(0, 0), a2, voffA);
;             PG8_WAIT_V(8); PG8_WAIT_L(0); PG8_BAR; PG8_MMA(1, 0, At, B0); PG8_MMA(1, 1, At, B1); PG8_BAR; PG8_SCHED;
.LBB0_325:
	v_add_u32_e32 v138, 0x10000, v151
	ds_read_b128 v[154:157], v138
	ds_read_b128 v[158:161], v138 offset:1024
	ds_read_b128 v[162:165], v138 offset:2048
	ds_read_b128 v[166:169], v138 offset:3072
	v_add_u32_e32 v138, 0x14000, v151
	s_add_u32 s8, s82, 0x100
	ds_read_b128 v[170:173], v138
	ds_read_b128 v[174:177], v138 offset:1024
	ds_read_b128 v[178:181], v138 offset:2048
	ds_read_b128 v[182:185], v138 offset:3072
	s_addc_u32 s9, s83, 0
	s_and_b64 s[60:61], s[62:63], exec
	s_cselect_b32 s84, s54, s8
	s_cselect_b32 s85, s19, s9
	s_cselect_b32 s63, s17, s57
	s_cselect_b32 s62, s55, s56
	s_add_u32 s66, s84, 0x80
	s_addc_u32 s67, s85, 0
	s_add_u32 s76, s62, 0x80
	s_addc_u32 s77, s63, 0
	ds_read_b128 v[186:189], v152
	ds_read_b128 v[190:193], v152 offset:1024
	ds_read_b128 v[194:197], v152 offset:2048
	ds_read_b128 v[198:201], v152 offset:3072
	ds_read_b128 v[202:205], v152 offset:4096
	ds_read_b128 v[206:209], v152 offset:5120
	ds_read_b128 v[210:213], v152 offset:6144
	ds_read_b128 v[214:217], v152 offset:7168
	s_add_u32 s60, s82, 0x100080
	s_addc_u32 s61, s83, 0
	s_mov_b32 m0, s97
	s_nop 0
	global_load_lds_dwordx4 v141, s[60:61]
	s_nop 0
	s_mov_b32 m0, s70
	s_nop 0
	global_load_lds_dwordx4 v143, s[60:61]
	s_waitcnt vmcnt(8)
	s_waitcnt lgkmcnt(0)
	s_barrier
	s_setprio 1
	s_waitcnt lgkmcnt(7)
	v_mfma_f32_16x16x32_bf16 v[126:129], v[154:157], v[186:189], v[126:129]
	v_mfma_f32_16x16x32_bf16 v[122:125], v[162:165], v[186:189], v[122:125]
	s_waitcnt lgkmcnt(5)
	v_mfma_f32_16x16x32_bf16 v[106:109], v[162:165], v[194:197], v[106:109]
	v_mfma_f32_16x16x32_bf16 v[110:113], v[154:157], v[194:197], v[110:113]
	s_waitcnt lgkmcnt(3)
	v_mfma_f32_16x16x32_bf16 v[94:97], v[154:157], v[202:205], v[94:97]
	v_mfma_f32_16x16x32_bf16 v[90:93], v[162:165], v[202:205], v[90:93]
	s_waitcnt lgkmcnt(1)
	v_mfma_f32_16x16x32_bf16 v[74:77], v[162:165], v[210:213], v[74:77]
	v_mfma_f32_16x16x32_bf16 v[78:81], v[154:157], v[210:213], v[78:81]
	v_mfma_f32_16x16x32_bf16 v[126:129], v[158:161], v[190:193], v[126:129]
	v_mfma_f32_16x16x32_bf16 v[122:125], v[166:169], v[190:193], v[122:125]
	v_mfma_f32_16x16x32_bf16 v[106:109], v[166:169], v[198:201], v[106:109]
	v_mfma_f32_16x16x32_bf16 v[110:113], v[158:161], v[198:201], v[110:113]
	v_mfma_f32_16x16x32_bf16 v[94:97], v[158:161], v[206:209], v[94:97]
	v_mfma_f32_16x16x32_bf16 v[90:93], v[166:169], v[206:209], v[90:93]
	s_waitcnt lgkmcnt(0)
	v_mfma_f32_16x16x32_bf16 v[74:77], v[166:169], v[214:217], v[74:77]
	v_mfma_f32_16x16x32_bf16 v[78:81], v[158:161], v[214:217], v[78:81]
	s_setprio 0
	s_setprio 1
	v_mfma_f32_16x16x32_bf16 v[118:121], v[170:173], v[186:189], v[118:121]
	v_mfma_f32_16x16x32_bf16 v[114:117], v[178:181], v[186:189], v[114:117]
	v_mfma_f32_16x16x32_bf16 v[98:101], v[178:181], v[194:197], v[98:101]
	v_mfma_f32_16x16x32_bf16 v[102:105], v[170:173], v[194:197], v[102:105]
	v_mfma_f32_16x16x32_bf16 v[86:89], v[170:173], v[202:205], v[86:89]
	v_mfma_f32_16x16x32_bf16 v[82:85], v[178:181], v[202:205], v[82:85]
	v_mfma_f32_16x16x32_bf16 v[66:69], v[178:181], v[210:213], v[66:69]
	v_mfma_f32_16x16x32_bf16 v[70:73], v[170:173], v[210:213], v[70:73]
	v_mfma_f32_16x16x32_bf16 v[118:121], v[174:177], v[190:193], v[118:121]
	v_mfma_f32_16x16x32_bf16 v[114:117], v[182:185], v[190:193], v[114:117]
	v_mfma_f32_16x16x32_bf16 v[98:101], v[182:185], v[198:201], v[98:101]
	v_mfma_f32_16x16x32_bf16 v[102:105], v[174:177], v[198:201], v[102:105]
	v_mfma_f32_16x16x32_bf16 v[86:89], v[174:177], v[206:209], v[86:89]
	v_mfma_f32_16x16x32_bf16 v[82:85], v[182:185], v[206:209], v[82:85]
	v_mfma_f32_16x16x32_bf16 v[70:73], v[174:177], v[214:217], v[70:73]
	s_setprio 2
	s_barrier
	v_mfma_f32_16x16x32_bf16 v[66:69], v[182:185], v[214:217], v[66:69]
	s_setprio 0
	ds_read_b128 v[186:189], v152 offset:16384
	ds_read_b128 v[190:193], v152 offset:17408
	ds_read_b128 v[194:197], v152 offset:18432
	ds_read_b128 v[198:201], v152 offset:19456
	ds_read_b128 v[202:205], v152 offset:20480
	ds_read_b128 v[206:209], v152 offset:21504
	ds_read_b128 v[210:213], v152 offset:22528
	ds_read_b128 v[252:255], v152 offset:23552
	s_mov_b32 m0, s68
	s_nop 0
	global_load_lds_dwordx4 v142, s[62:63]
	s_add_u32 s60, s62, 0x100000
	s_mov_b32 m0, s69
	s_nop 0
	global_load_lds_dwordx4 v144, s[62:63]
	s_addc_u32 s61, s63, 0
	s_mov_b32 m0, s81
	s_nop 0
	global_load_lds_dwordx4 v142, s[60:61]
	s_nop 0
	s_mov_b32 m0, s86
	s_nop 0
	global_load_lds_dwordx4 v144, s[60:61]
	s_nop 0
	s_mov_b32 m0, s65
	s_nop 0
	global_load_lds_dwordx4 v141, s[84:85]
	s_nop 0
	s_mov_b32 m0, s87
	s_nop 0
	global_load_lds_dwordx4 v143, s[84:85]
	s_waitcnt vmcnt(8)
	s_waitcnt lgkmcnt(0)
	s_barrier
; #define PG8_STAGE(bufoff, gbase, voff) do { _Pragma("unroll") for (int _i = 0; _i < 2; ++_i) \
;         asm volatile("s_mov_b32 m0, %2\n\ts_nop 0\n\tglobal_load_lds_dwordx4 %0, %1" :: "v"((voff)[_i]), "s"((const char*)(gbase)), "s"(ldsbase + (unsigned)(bufoff) + ldsw + (unsigned)_i * 8192u) : "memory", "m0"); } while (0)
; #define PG8_LDA(dst, b, h) do { _Pragma("unroll") for (int m = 0; m < 4; ++m) _Pragma("unroll") for (int k = 0; k < 2; ++k) dst[m][k] = *(const PG8_LAS bf16x8*)(lds + PG8_SA(b, h) + aoff + m * 2048 + k * 1024); } while (0)
; #define PG8_LDB(dst, b, h) do { _Pragma("unroll") for (int n = 0; n < 2; ++n) _Pragma("unroll") for (int k = 0; k < 2; ++k) dst[n][k] = *(const PG8_LAS bf16x8*)(lds + PG8_SB(b, h) + boff + n * 2048 + k * 1024); } while (0)
; #define PG8_MMA(ai, bj, At, Bt) do { __builtin_amdgcn_s_setprio(1); _Pragma("unroll") for (int m = 0; m < 4; ++m) _Pragma("unroll") for (int n = 0; n < 2; ++n) _Pragma("unroll") for (int k = 0; k < 2; ++k) \
;         acc[ai][bj][m][n] = __builtin_amdgcn_mfma_f32_16x16x32_bf16(Bt[n][k], At[m][k], acc[ai][bj][m][n], 0, 0, 0); __builtin_amdgcn_s_setprio(0); } while (0)
; #define PG8_WAIT_V(n) asm volatile("s_waitcnt vmcnt(" #n ")" ::: "memory")
; #define PG8_WAIT_L(n) asm volatile("s_waitcnt lgkmcnt(" #n ")" ::: "memory")
; #define PG8_BAR __builtin_amdgcn_s_barrier()
; #define PG8_SCHED __builtin_amdgcn_sched_barrier(0)
; template <class Epi, class Sched, bool ALIGN_EPI = false, bool SP2 = false>
; __device__ __forceinline__ void gemm_phase(PG8_LAS unsigned char* lds, const Gemm g, const Sched& S, const Epi& E) {
;     ...
;             PG8_WAIT_V(8); PG8_WAIT_L(0); PG8_BAR; PG8_MMA(1, 0, At, B0); PG8_MMA(1, 1, At, B1); PG8_BAR; PG8_SCHED;
;             PG8_LDB(B0, 1, 0); PG8_LDB(B1, 1, 1); PG8_SCHED; PG8_LDA(At, 1, 0); PG8_STAGE(PG8_SA(0, 1), a2 + hstep, voffA);
;             PG8_WAIT_V(8); PG8_WAIT_L(0); PG8_BAR; PG8_MMA(0, 0, At, B0); PG8_MMA(0, 1, At, B1); PG8_BAR; PG8_SCHED;
	s_setprio 1
	s_waitcnt lgkmcnt(7)
	v_mfma_f32_16x16x32_bf16 v[62:65], v[154:157], v[186:189], v[62:65]
	v_mfma_f32_16x16x32_bf16 v[58:61], v[162:165], v[186:189], v[58:61]
	s_waitcnt lgkmcnt(5)
	v_mfma_f32_16x16x32_bf16 v[42:45], v[162:165], v[194:197], v[42:45]
	v_mfma_f32_16x16x32_bf16 v[46:49], v[154:157], v[194:197], v[46:49]
	s_waitcnt lgkmcnt(3)
	v_mfma_f32_16x16x32_bf16 v[30:33], v[154:157], v[202:205], v[30:33]
	v_mfma_f32_16x16x32_bf16 v[26:29], v[162:165], v[202:205], v[26:29]
	s_waitcnt lgkmcnt(1)
	v_mfma_f32_16x16x32_bf16 v[10:13], v[162:165], v[210:213], v[10:13]
	v_mfma_f32_16x16x32_bf16 v[14:17], v[154:157], v[210:213], v[14:17]
	v_mfma_f32_16x16x32_bf16 v[62:65], v[158:161], v[190:193], v[62:65]
	v_mfma_f32_16x16x32_bf16 v[58:61], v[166:169], v[190:193], v[58:61]
	v_mfma_f32_16x16x32_bf16 v[42:45], v[166:169], v[198:201], v[42:45]
	v_mfma_f32_16x16x32_bf16 v[46:49], v[158:161], v[198:201], v[46:49]
	v_mfma_f32_16x16x32_bf16 v[30:33], v[158:161], v[206:209], v[30:33]
	v_mfma_f32_16x16x32_bf16 v[26:29], v[166:169], v[206:209], v[26:29]
	s_waitcnt lgkmcnt(0)
	v_mfma_f32_16x16x32_bf16 v[10:13], v[166:169], v[252:255], v[10:13]
	v_mfma_f32_16x16x32_bf16 v[14:17], v[158:161], v[252:255], v[14:17]
	s_setprio 0
	s_setprio 1
	v_mfma_f32_16x16x32_bf16 v[54:57], v[170:173], v[186:189], v[54:57]
	v_mfma_f32_16x16x32_bf16 v[50:53], v[178:181], v[186:189], v[50:53]
	v_mfma_f32_16x16x32_bf16 v[34:37], v[178:181], v[194:197], v[34:37]
	v_mfma_f32_16x16x32_bf16 v[38:41], v[170:173], v[194:197], v[38:41]
	v_mfma_f32_16x16x32_bf16 v[22:25], v[170:173], v[202:205], v[22:25]
	v_mfma_f32_16x16x32_bf16 v[18:21], v[178:181], v[202:205], v[18:21]
	v_mfma_f32_16x16x32_bf16 v[2:5], v[178:181], v[210:213], v[2:5]
	v_mfma_f32_16x16x32_bf16 v[6:9], v[170:173], v[210:213], v[6:9]
	v_mfma_f32_16x16x32_bf16 v[54:57], v[174:177], v[190:193], v[54:57]
	v_mfma_f32_16x16x32_bf16 v[50:53], v[182:185], v[190:193], v[50:53]
	v_mfma_f32_16x16x32_bf16 v[34:37], v[182:185], v[198:201], v[34:37]
	v_mfma_f32_16x16x32_bf16 v[38:41], v[174:177], v[198:201], v[38:41]
	v_mfma_f32_16x16x32_bf16 v[22:25], v[174:177], v[206:209], v[22:25]
	v_mfma_f32_16x16x32_bf16 v[18:21], v[182:185], v[206:209], v[18:21]
	v_mfma_f32_16x16x32_bf16 v[6:9], v[174:177], v[252:255], v[6:9]
	s_setprio 2
	s_barrier
	v_mfma_f32_16x16x32_bf16 v[2:5], v[182:185], v[252:255], v[2:5]
	s_setprio 0
	v_add_u32_e32 v138, 0x18000, v151
	ds_read_b128 v[154:157], v138
	ds_read_b128 v[158:161], v138 offset:1024
	ds_read_b128 v[162:165], v138 offset:2048
	ds_read_b128 v[166:169], v138 offset:3072
	v_add_u32_e32 v138, 0x1c000, v151
	ds_read_b128 v[170:173], v138
	ds_read_b128 v[174:177], v138 offset:1024
	ds_read_b128 v[178:181], v138 offset:2048
	ds_read_b128 v[248:251], v138 offset:3072
	ds_read_b128 v[186:189], v152 offset:32768
	ds_read_b128 v[190:193], v152 offset:33792
	ds_read_b128 v[194:197], v152 offset:34816
	ds_read_b128 v[198:201], v152 offset:35840
	ds_read_b128 v[202:205], v152 offset:36864
	ds_read_b128 v[206:209], v152 offset:37888
	ds_read_b128 v[210:213], v152 offset:38912
	ds_read_b128 v[214:217], v152 offset:39936
	s_add_u32 s60, s84, 0x100000
	s_addc_u32 s61, s85, 0
	s_mov_b32 m0, s88
	s_nop 0
	global_load_lds_dwordx4 v141, s[60:61]
	s_nop 0
	s_mov_b32 m0, s89
	s_nop 0
	global_load_lds_dwordx4 v143, s[60:61]
	s_waitcnt vmcnt(8)
	s_waitcnt lgkmcnt(0)
	s_barrier
	s_setprio 1
	s_waitcnt lgkmcnt(7)
	v_mfma_f32_16x16x32_bf16 v[126:129], v[154:157], v[186:189], v[126:129]
	v_mfma_f32_16x16x32_bf16 v[122:125], v[162:165], v[186:189], v[122:125]
	s_waitcnt lgkmcnt(5)
	v_mfma_f32_16x16x32_bf16 v[106:109], v[162:165], v[194:197], v[106:109]
	v_mfma_f32_16x16x32_bf16 v[110:113], v[154:157], v[194:197], v[110:113]
	s_waitcnt lgkmcnt(3)
	v_mfma_f32_16x16x32_bf16 v[94:97], v[154:157], v[202:205], v[94:97]
	v_mfma_f32_16x16x32_bf16 v[90:93], v[162:165], v[202:205], v[90:93]
	s_waitcnt lgkmcnt(1)
	v_mfma_f32_16x16x32_bf16 v[74:77], v[162:165], v[210:213], v[74:77]
	v_mfma_f32_16x16x32_bf16 v[78:81], v[154:157], v[210:213], v[78:81]
	v_mfma_f32_16x16x32_bf16 v[126:129], v[158:161], v[190:193], v[126:129]
	v_mfma_f32_16x16x32_bf16 v[122:125], v[166:169], v[190:193], v[122:125]
	v_mfma_f32_16x16x32_bf16 v[106:109], v[166:169], v[198:201], v[106:109]
	v_mfma_f32_16x16x32_bf16 v[110:113], v[158:161], v[198:201], v[110:113]
	v_mfma_f32_16x16x32_bf16 v[94:97], v[158:161], v[206:209], v[94:97]
	v_mfma_f32_16x16x32_bf16 v[90:93], v[166:169], v[206:209], v[90:93]
	s_waitcnt lgkmcnt(0)
	v_mfma_f32_16x16x32_bf16 v[74:77], v[166:169], v[214:217], v[74:77]
	v_mfma_f32_16x16x32_bf16 v[78:81], v[158:161], v[214:217], v[78:81]
	s_setprio 0
	s_setprio 1
	v_mfma_f32_16x16x32_bf16 v[118:121], v[170:173], v[186:189], v[118:121]
	v_mfma_f32_16x16x32_bf16 v[114:117], v[178:181], v[186:189], v[114:117]
	v_mfma_f32_16x16x32_bf16 v[98:101], v[178:181], v[194:197], v[98:101]
	v_mfma_f32_16x16x32_bf16 v[102:105], v[170:173], v[194:197], v[102:105]
	v_mfma_f32_16x16x32_bf16 v[86:89], v[170:173], v[202:205], v[86:89]
	v_mfma_f32_16x16x32_bf16 v[82:85], v[178:181], v[202:205], v[82:85]
	v_mfma_f32_16x16x32_bf16 v[66:69], v[178:181], v[210:213], v[66:69]
	v_mfma_f32_16x16x32_bf16 v[70:73], v[170:173], v[210:213], v[70:73]
	v_mfma_f32_16x16x32_bf16 v[118:121], v[174:177], v[190:193], v[118:121]
	v_mfma_f32_16x16x32_bf16 v[114:117], v[248:251], v[190:193], v[114:117]
	v_mfma_f32_16x16x32_bf16 v[98:101], v[248:251], v[198:201], v[98:101]
	v_mfma_f32_16x16x32_bf16 v[102:105], v[174:177], v[198:201], v[102:105]
	v_mfma_f32_16x16x32_bf16 v[86:89], v[174:177], v[206:209], v[86:89]
	v_mfma_f32_16x16x32_bf16 v[82:85], v[248:251], v[206:209], v[82:85]
	v_mfma_f32_16x16x32_bf16 v[70:73], v[174:177], v[214:217], v[70:73]
	s_setprio 2
	s_barrier
; #define PG8_STAGE(bufoff, gbase, voff) do { _Pragma("unroll") for (int _i = 0; _i < 2; ++_i) \
;         asm volatile("s_mov_b32 m0, %2\n\ts_nop 0\n\tglobal_load_lds_dwordx4 %0, %1" :: "v"((voff)[_i]), "s"((const char*)(gbase)), "s"(ldsbase + (unsigned)(bufoff) + ldsw + (unsigned)_i * 8192u) : "memory", "m0"); } while (0)
; #define PG8_LDA(dst, b, h) do { _Pragma("unroll") for (int m = 0; m < 4; ++m) _Pragma("unroll") for (int k = 0; k < 2; ++k) dst[m][k] = *(const PG8_LAS bf16x8*)(lds + PG8_SA(b, h) + aoff + m * 2048 + k * 1024); } while (0)
; #define PG8_MMA(ai, bj, At, Bt) do { __builtin_amdgcn_s_setprio(1); _Pragma("unroll") for (int m = 0; m < 4; ++m) _Pragma("unroll") for (int n = 0; n < 2; ++n) _Pragma("unroll") for (int k = 0; k < 2; ++k) \
;         acc[ai][bj][m][n] = __builtin_amdgcn_mfma_f32_16x16x32_bf16(Bt[n][k], At[m][k], acc[ai][bj][m][n], 0, 0, 0); __builtin_amdgcn_s_setprio(0); } while (0)
; #define PG8_WAIT_V(n) asm volatile("s_waitcnt vmcnt(" #n ")" ::: "memory")
; #define PG8_WAIT_L(n) asm volatile("s_waitcnt lgkmcnt(" #n ")" ::: "memory")
; #define PG8_BAR __builtin_amdgcn_s_barrier()
; #define PG8_SCHED __builtin_amdgcn_sched_barrier(0)
; template <class Epi, class Sched, bool ALIGN_EPI = false, bool SP2 = false>
; __device__ __forceinline__ void gemm_phase(PG8_LAS unsigned char* lds, const Gemm g, const Sched& S, const Epi& E) {
;     ...
;             PG8_LDA(At, 1, 1); PG8_STAGE(PG8_SB(1, 0), b3, voffB); PG8_STAGE(PG8_SB(1, 1), b3 + hstep, voffB); PG8_STAGE(PG8_SA(1, 0), a3, voffA);
;             PG8_WAIT_V(8); PG8_WAIT_L(0); PG8_BAR; PG8_MMA(1, 0, At, B0); PG8_MMA(1, 1, At, B1); PG8_BAR; PG8_SCHED;
	v_mfma_f32_16x16x32_bf16 v[66:69], v[248:251], v[214:217], v[66:69]
	s_setprio 0
	ds_read_b128 v[186:189], v152 offset:49152
	ds_read_b128 v[190:193], v152 offset:50176
	ds_read_b128 v[194:197], v152 offset:51200
	ds_read_b128 v[198:201], v152 offset:52224
	ds_read_b128 v[202:205], v152 offset:53248
	ds_read_b128 v[206:209], v152 offset:54272
	ds_read_b128 v[210:213], v152 offset:55296
	ds_read_b128 v[252:255], v152 offset:56320
	s_mov_b32 m0, s90
	s_nop 0
	global_load_lds_dwordx4 v142, s[76:77]
	s_add_u32 s60, s62, 0x100080
	s_mov_b32 m0, s91
	s_nop 0
	global_load_lds_dwordx4 v144, s[76:77]
	s_addc_u32 s61, s63, 0
	s_mov_b32 m0, s95
	s_nop 0
	global_load_lds_dwordx4 v142, s[60:61]
	s_nop 0
	s_mov_b32 m0, s96
	s_nop 0
	global_load_lds_dwordx4 v144, s[60:61]
	s_nop 0
	s_mov_b32 m0, s92
	s_nop 0
	global_load_lds_dwordx4 v141, s[66:67]
	s_nop 0
	s_mov_b32 m0, s94
	s_nop 0
	global_load_lds_dwordx4 v143, s[66:67]
	s_waitcnt vmcnt(8)
	s_waitcnt lgkmcnt(0)
	s_barrier
	s_setprio 1
	s_waitcnt lgkmcnt(7)
	v_mfma_f32_16x16x32_bf16 v[62:65], v[154:157], v[186:189], v[62:65]
	v_mfma_f32_16x16x32_bf16 v[58:61], v[162:165], v[186:189], v[58:61]
	s_waitcnt lgkmcnt(5)
	v_mfma_f32_16x16x32_bf16 v[42:45], v[162:165], v[194:197], v[42:45]
	v_mfma_f32_16x16x32_bf16 v[46:49], v[154:157], v[194:197], v[46:49]
	s_waitcnt lgkmcnt(3)
	v_mfma_f32_16x16x32_bf16 v[30:33], v[154:157], v[202:205], v[30:33]
	v_mfma_f32_16x16x32_bf16 v[26:29], v[162:165], v[202:205], v[26:29]
	s_waitcnt lgkmcnt(1)
	v_mfma_f32_16x16x32_bf16 v[10:13], v[162:165], v[210:213], v[10:13]
	v_mfma_f32_16x16x32_bf16 v[14:17], v[154:157], v[210:213], v[14:17]
	v_mfma_f32_16x16x32_bf16 v[62:65], v[158:161], v[190:193], v[62:65]
	v_mfma_f32_16x16x32_bf16 v[58:61], v[166:169], v[190:193], v[58:61]
	v_mfma_f32_16x16x32_bf16 v[42:45], v[166:169], v[198:201], v[42:45]
	v_mfma_f32_16x16x32_bf16 v[46:49], v[158:161], v[198:201], v[46:49]
	v_mfma_f32_16x16x32_bf16 v[30:33], v[158:161], v[206:209], v[30:33]
	v_mfma_f32_16x16x32_bf16 v[26:29], v[166:169], v[206:209], v[26:29]
	s_waitcnt lgkmcnt(0)
	v_mfma_f32_16x16x32_bf16 v[10:13], v[166:169], v[252:255], v[10:13]
	v_mfma_f32_16x16x32_bf16 v[14:17], v[158:161], v[252:255], v[14:17]
	s_setprio 0
	s_setprio 1
	v_mfma_f32_16x16x32_bf16 v[54:57], v[170:173], v[186:189], v[54:57]
	v_mfma_f32_16x16x32_bf16 v[50:53], v[178:181], v[186:189], v[50:53]
	v_mfma_f32_16x16x32_bf16 v[34:37], v[178:181], v[194:197], v[34:37]
	v_mfma_f32_16x16x32_bf16 v[38:41], v[170:173], v[194:197], v[38:41]
	v_mfma_f32_16x16x32_bf16 v[22:25], v[170:173], v[202:205], v[22:25]
	v_mfma_f32_16x16x32_bf16 v[18:21], v[178:181], v[202:205], v[18:21]
	v_mfma_f32_16x16x32_bf16 v[2:5], v[178:181], v[210:213], v[2:5]
	v_mfma_f32_16x16x32_bf16 v[6:9], v[170:173], v[210:213], v[6:9]
	v_mfma_f32_16x16x32_bf16 v[54:57], v[174:177], v[190:193], v[54:57]
	v_mfma_f32_16x16x32_bf16 v[50:53], v[248:251], v[190:193], v[50:53]
	v_mfma_f32_16x16x32_bf16 v[34:37], v[248:251], v[198:201], v[34:37]
	v_mfma_f32_16x16x32_bf16 v[38:41], v[174:177], v[198:201], v[38:41]
	v_mfma_f32_16x16x32_bf16 v[22:25], v[174:177], v[206:209], v[22:25]
	v_mfma_f32_16x16x32_bf16 v[18:21], v[248:251], v[206:209], v[18:21]
	v_mfma_f32_16x16x32_bf16 v[6:9], v[174:177], v[252:255], v[6:9]
	s_setprio 2
	s_barrier
	v_mfma_f32_16x16x32_bf16 v[2:5], v[248:251], v[252:255], v[2:5]
	s_setprio 0
	s_add_i32 s58, s58, 2
	s_add_u32 s56, s56, 0x100
	s_addc_u32 s57, s57, 0
	s_cmp_gt_u32 s58, 61
	s_cbranch_scc1 .LBB0_316
	s_mov_b64 s[82:83], s[8:9]
	s_branch .LBB0_320

; #define PG8_STAGE(bufoff, gbase, voff) do { _Pragma("unroll") for (int _i = 0; _i < 2; ++_i) \
;         asm volatile("s_mov_b32 m0, %2\n\ts_nop 0\n\tglobal_load_lds_dwordx4 %0, %1" :: "v"((voff)[_i]), "s"((const char*)(gbase)), "s"(ldsbase + (unsigned)(bufoff) + ldsw + (unsigned)_i * 8192u) : "memory", "m0"); } while (0)
; #define PG8_LDA(dst, b, h) do { _Pragma("unroll") for (int m = 0; m < 4; ++m) _Pragma("unroll") for (int k = 0; k < 2; ++k) dst[m][k] = *(const PG8_LAS bf16x8*)(lds + PG8_SA(b, h) + aoff + m * 2048 + k * 1024); } while (0)
; #define PG8_LDB(dst, b, h) do { _Pragma("unroll") for (int n = 0; n < 2; ++n) _Pragma("unroll") for (int k = 0; k < 2; ++k) dst[n][k] = *(const PG8_LAS bf16x8*)(lds + PG8_SB(b, h) + boff + n * 2048 + k * 1024); } while (0)
; #define PG8_MMA(ai, bj, At, Bt) do { __builtin_amdgcn_s_setprio(1); _Pragma("unroll") for (int m = 0; m < 4; ++m) _Pragma("unroll") for (int n = 0; n < 2; ++n) _Pragma("unroll") for (int k = 0; k < 2; ++k) \
;         acc[ai][bj][m][n] = __builtin_amdgcn_mfma_f32_16x16x32_bf16(Bt[n][k], At[m][k], acc[ai][bj][m][n], 0, 0, 0); __builtin_amdgcn_s_setprio(0); } while (0)
; template <class Epi, class Sched, bool ALIGN_EPI = false, bool SP2 = false>
; __device__ __forceinline__ void gemm_phase(PG8_LAS unsigned char* lds, const Gemm g, const Sched& S, const Epi& E) {
;     ...
;             const bool last = (t == nt - 2);
;             const char* a1 = cA + (size_t)(t + 1) * kstep;
;             const char* a2 = last ? nA : cA + (size_t)(t + 2) * kstep; const char* b2 = last ? nB : cB + (size_t)(t + 2) * kstep;
;             const char* a3 = a2 + kstep; const char* b3 = b2 + kstep;
;             if (last && has_next) S.a_ready(nxt);
;             if constexpr (epi_has_mid<Epi>::value) { if (t == Epi::MID_T) E.mid(acc, cur, wr, wc, fr, fq); }
;             if constexpr (SP2) {
;             PG8_LDB(B0, 0, 0); PG8_LDB(B1, 0, 1); PG8_SCHED; PG8_LDA(At, 0, 0); PG8_STAGE(PG8_SA(1, 1), a1 + hstep, voffA);
;             PG8_WAIT_V(8); PG8_WAIT_L(0); PG8_BAR; PG8_MMA(0, 0, At, B0); PG8_MMA(0, 1, At, B1); PG8_BAR; PG8_SCHED;
;             PG8_LDA(At, 0, 1); PG8_STAGE(PG8_SB(0, 0), b2, voffB); PG8_STAGE(PG8_SB(0, 1), b2 + hstep, voffB); PG8_STAGE(PG8_SA(0, 0), a2, voffA);
;             PG8_WAIT_V(8); PG8_WAIT_L(0); PG8_BAR; PG8_MMA(1, 0, At, B0); PG8_MMA(1, 1, At, B1); PG8_BAR; PG8_SCHED;
.LBB0_620:
	v_add_u32_e32 v3, 0x10000, v199
	ds_read_b128 v[134:137], v3
	ds_read_b128 v[138:141], v3 offset:1024
	ds_read_b128 v[142:145], v3 offset:2048
	ds_read_b128 v[146:149], v3 offset:3072
	v_add_u32_e32 v3, 0x14000, v199
	s_add_u32 s44, s42, 0x100
	ds_read_b128 v[158:161], v3
	ds_read_b128 v[162:165], v3 offset:1024
	ds_read_b128 v[166:169], v3 offset:2048
	ds_read_b128 v[170:173], v3 offset:3072
	s_addc_u32 s45, s43, 0
	s_cmp_eq_u32 s92, 60
	s_cselect_b32 s56, s88, s44
	s_cselect_b32 s57, s23, s45
	s_cselect_b32 s47, s19, s91
	s_cselect_b32 s46, s89, s90
	s_add_u32 s50, s56, 0x80
	s_addc_u32 s51, s57, 0
	s_add_u32 s54, s46, 0x80
	s_addc_u32 s55, s47, 0
	ds_read_b128 v[174:177], v200
	ds_read_b128 v[178:181], v200 offset:1024
	ds_read_b128 v[182:185], v200 offset:2048
	ds_read_b128 v[186:189], v200 offset:3072
	ds_read_b128 v[190:193], v200 offset:4096
	ds_read_b128 v[202:205], v200 offset:5120
	ds_read_b128 v[206:209], v200 offset:6144
	ds_read_b128 v[210:213], v200 offset:7168
	s_add_u32 s42, s42, 0x100080
	s_addc_u32 s43, s43, 0
	s_mov_b32 m0, s85
	s_nop 0
	global_load_lds_dwordx4 v1, s[42:43]
	s_nop 0
	s_mov_b32 m0, s86
	s_nop 0
	global_load_lds_dwordx4 v195, s[42:43]
	s_waitcnt vmcnt(8)
	s_waitcnt lgkmcnt(0)
	s_barrier
	s_setprio 1
	s_waitcnt lgkmcnt(7)
	v_mfma_f32_16x16x32_bf16 v[130:133], v[134:137], v[174:177], v[130:133]
	v_mfma_f32_16x16x32_bf16 v[126:129], v[142:145], v[174:177], v[126:129]
	s_waitcnt lgkmcnt(5)
	v_mfma_f32_16x16x32_bf16 v[118:121], v[142:145], v[182:185], v[118:121]
	v_mfma_f32_16x16x32_bf16 v[122:125], v[134:137], v[182:185], v[122:125]
	s_waitcnt lgkmcnt(3)
	v_mfma_f32_16x16x32_bf16 v[114:117], v[134:137], v[190:193], v[114:117]
	v_mfma_f32_16x16x32_bf16 v[110:113], v[142:145], v[190:193], v[110:113]
	s_waitcnt lgkmcnt(1)
	v_mfma_f32_16x16x32_bf16 v[102:105], v[142:145], v[206:209], v[102:105]
	v_mfma_f32_16x16x32_bf16 v[106:109], v[134:137], v[206:209], v[106:109]
	v_mfma_f32_16x16x32_bf16 v[130:133], v[138:141], v[178:181], v[130:133]
	v_mfma_f32_16x16x32_bf16 v[126:129], v[146:149], v[178:181], v[126:129]
	v_mfma_f32_16x16x32_bf16 v[118:121], v[146:149], v[186:189], v[118:121]
	v_mfma_f32_16x16x32_bf16 v[122:125], v[138:141], v[186:189], v[122:125]
	v_mfma_f32_16x16x32_bf16 v[114:117], v[138:141], v[202:205], v[114:117]
	v_mfma_f32_16x16x32_bf16 v[110:113], v[146:149], v[202:205], v[110:113]
	s_waitcnt lgkmcnt(0)
	v_mfma_f32_16x16x32_bf16 v[102:105], v[146:149], v[210:213], v[102:105]
	v_mfma_f32_16x16x32_bf16 v[106:109], v[138:141], v[210:213], v[106:109]
	s_setprio 0
	s_setprio 1
	v_mfma_f32_16x16x32_bf16 v[66:69], v[158:161], v[174:177], v[66:69]
	v_mfma_f32_16x16x32_bf16 v[62:65], v[166:169], v[174:177], v[62:65]
	v_mfma_f32_16x16x32_bf16 v[54:57], v[166:169], v[182:185], v[54:57]
	v_mfma_f32_16x16x32_bf16 v[58:61], v[158:161], v[182:185], v[58:61]
	v_mfma_f32_16x16x32_bf16 v[50:53], v[158:161], v[190:193], v[50:53]
	v_mfma_f32_16x16x32_bf16 v[46:49], v[166:169], v[190:193], v[46:49]
	v_mfma_f32_16x16x32_bf16 v[38:41], v[166:169], v[206:209], v[38:41]
	v_mfma_f32_16x16x32_bf16 v[42:45], v[158:161], v[206:209], v[42:45]
	v_mfma_f32_16x16x32_bf16 v[66:69], v[162:165], v[178:181], v[66:69]
	v_mfma_f32_16x16x32_bf16 v[62:65], v[170:173], v[178:181], v[62:65]
	v_mfma_f32_16x16x32_bf16 v[54:57], v[170:173], v[186:189], v[54:57]
	v_mfma_f32_16x16x32_bf16 v[58:61], v[162:165], v[186:189], v[58:61]
	v_mfma_f32_16x16x32_bf16 v[50:53], v[162:165], v[202:205], v[50:53]
	v_mfma_f32_16x16x32_bf16 v[46:49], v[170:173], v[202:205], v[46:49]
	v_mfma_f32_16x16x32_bf16 v[42:45], v[162:165], v[210:213], v[42:45]
	s_setprio 2
	s_barrier
	v_mfma_f32_16x16x32_bf16 v[38:41], v[170:173], v[210:213], v[38:41]
	s_setprio 0
	ds_read_b128 v[174:177], v200 offset:16384
	ds_read_b128 v[178:181], v200 offset:17408
	ds_read_b128 v[182:185], v200 offset:18432
	ds_read_b128 v[186:189], v200 offset:19456
	ds_read_b128 v[190:193], v200 offset:20480
	ds_read_b128 v[202:205], v200 offset:21504
	ds_read_b128 v[206:209], v200 offset:22528
	ds_read_b128 v[252:255], v200 offset:23552
	s_mov_b32 m0, s63
	s_nop 0
	global_load_lds_dwordx4 v194, s[46:47]
	s_add_u32 s42, s46, 0x100000
	s_mov_b32 m0, s64
	s_nop 0
	global_load_lds_dwordx4 v196, s[46:47]
	s_addc_u32 s43, s47, 0
	s_mov_b32 m0, s65
	s_nop 0
	global_load_lds_dwordx4 v194, s[42:43]
	s_nop 0
	s_mov_b32 m0, s66
	s_nop 0
	global_load_lds_dwordx4 v196, s[42:43]
	s_nop 0
	s_mov_b32 m0, s62
	s_nop 0
	global_load_lds_dwordx4 v1, s[56:57]
	s_nop 0
	s_mov_b32 m0, s67
	s_nop 0
	global_load_lds_dwordx4 v195, s[56:57]
	s_waitcnt vmcnt(8)
	s_waitcnt lgkmcnt(0)
	s_barrier
; #define PG8_STAGE(bufoff, gbase, voff) do { _Pragma("unroll") for (int _i = 0; _i < 2; ++_i) \
;         asm volatile("s_mov_b32 m0, %2\n\ts_nop 0\n\tglobal_load_lds_dwordx4 %0, %1" :: "v"((voff)[_i]), "s"((const char*)(gbase)), "s"(ldsbase + (unsigned)(bufoff) + ldsw + (unsigned)_i * 8192u) : "memory", "m0"); } while (0)
; #define PG8_LDA(dst, b, h) do { _Pragma("unroll") for (int m = 0; m < 4; ++m) _Pragma("unroll") for (int k = 0; k < 2; ++k) dst[m][k] = *(const PG8_LAS bf16x8*)(lds + PG8_SA(b, h) + aoff + m * 2048 + k * 1024); } while (0)
; #define PG8_LDB(dst, b, h) do { _Pragma("unroll") for (int n = 0; n < 2; ++n) _Pragma("unroll") for (int k = 0; k < 2; ++k) dst[n][k] = *(const PG8_LAS bf16x8*)(lds + PG8_SB(b, h) + boff + n * 2048 + k * 1024); } while (0)
; #define PG8_MMA(ai, bj, At, Bt) do { __builtin_amdgcn_s_setprio(1); _Pragma("unroll") for (int m = 0; m < 4; ++m) _Pragma("unroll") for (int n = 0; n < 2; ++n) _Pragma("unroll") for (int k = 0; k < 2; ++k) \
;         acc[ai][bj][m][n] = __builtin_amdgcn_mfma_f32_16x16x32_bf16(Bt[n][k], At[m][k], acc[ai][bj][m][n], 0, 0, 0); __builtin_amdgcn_s_setprio(0); } while (0)
; #define PG8_WAIT_V(n) asm volatile("s_waitcnt vmcnt(" #n ")" ::: "memory")
; #define PG8_WAIT_L(n) asm volatile("s_waitcnt lgkmcnt(" #n ")" ::: "memory")
; #define PG8_BAR __builtin_amdgcn_s_barrier()
; #define PG8_SCHED __builtin_amdgcn_sched_barrier(0)
; template <class Epi, class Sched, bool ALIGN_EPI = false, bool SP2 = false>
; __device__ __forceinline__ void gemm_phase(PG8_LAS unsigned char* lds, const Gemm g, const Sched& S, const Epi& E) {
;     ...
;             PG8_WAIT_V(8); PG8_WAIT_L(0); PG8_BAR; PG8_MMA(1, 0, At, B0); PG8_MMA(1, 1, At, B1); PG8_BAR; PG8_SCHED;
;             PG8_LDB(B0, 1, 0); PG8_LDB(B1, 1, 1); PG8_SCHED; PG8_LDA(At, 1, 0); PG8_STAGE(PG8_SA(0, 1), a2 + hstep, voffA);
;             PG8_WAIT_V(8); PG8_WAIT_L(0); PG8_BAR; PG8_MMA(0, 0, At, B0); PG8_MMA(0, 1, At, B1); PG8_BAR; PG8_SCHED;
	s_setprio 1
	s_waitcnt lgkmcnt(7)
	v_mfma_f32_16x16x32_bf16 v[98:101], v[134:137], v[174:177], v[98:101]
	v_mfma_f32_16x16x32_bf16 v[94:97], v[142:145], v[174:177], v[94:97]
	s_waitcnt lgkmcnt(5)
	v_mfma_f32_16x16x32_bf16 v[86:89], v[142:145], v[182:185], v[86:89]
	v_mfma_f32_16x16x32_bf16 v[90:93], v[134:137], v[182:185], v[90:93]
	s_waitcnt lgkmcnt(3)
	v_mfma_f32_16x16x32_bf16 v[82:85], v[134:137], v[190:193], v[82:85]
	v_mfma_f32_16x16x32_bf16 v[78:81], v[142:145], v[190:193], v[78:81]
	s_waitcnt lgkmcnt(1)
	v_mfma_f32_16x16x32_bf16 v[70:73], v[142:145], v[206:209], v[70:73]
	v_mfma_f32_16x16x32_bf16 v[74:77], v[134:137], v[206:209], v[74:77]
	v_mfma_f32_16x16x32_bf16 v[98:101], v[138:141], v[178:181], v[98:101]
	v_mfma_f32_16x16x32_bf16 v[94:97], v[146:149], v[178:181], v[94:97]
	v_mfma_f32_16x16x32_bf16 v[86:89], v[146:149], v[186:189], v[86:89]
	v_mfma_f32_16x16x32_bf16 v[90:93], v[138:141], v[186:189], v[90:93]
	v_mfma_f32_16x16x32_bf16 v[82:85], v[138:141], v[202:205], v[82:85]
	v_mfma_f32_16x16x32_bf16 v[78:81], v[146:149], v[202:205], v[78:81]
	s_waitcnt lgkmcnt(0)
	v_mfma_f32_16x16x32_bf16 v[70:73], v[146:149], v[252:255], v[70:73]
	v_mfma_f32_16x16x32_bf16 v[74:77], v[138:141], v[252:255], v[74:77]
	s_setprio 0
	s_setprio 1
	v_mfma_f32_16x16x32_bf16 v[34:37], v[158:161], v[174:177], v[34:37]
	v_mfma_f32_16x16x32_bf16 v[30:33], v[166:169], v[174:177], v[30:33]
	v_mfma_f32_16x16x32_bf16 v[22:25], v[166:169], v[182:185], v[22:25]
	v_mfma_f32_16x16x32_bf16 v[26:29], v[158:161], v[182:185], v[26:29]
	v_mfma_f32_16x16x32_bf16 v[18:21], v[158:161], v[190:193], v[18:21]
	v_mfma_f32_16x16x32_bf16 v[14:17], v[166:169], v[190:193], v[14:17]
	v_mfma_f32_16x16x32_bf16 v[4:7], v[166:169], v[206:209], v[6:9]
	v_mfma_f32_16x16x32_bf16 v[10:13], v[158:161], v[206:209], v[10:13]
	v_mfma_f32_16x16x32_bf16 v[34:37], v[162:165], v[178:181], v[34:37]
	v_mfma_f32_16x16x32_bf16 v[30:33], v[170:173], v[178:181], v[30:33]
	v_mfma_f32_16x16x32_bf16 v[22:25], v[170:173], v[186:189], v[22:25]
	v_mfma_f32_16x16x32_bf16 v[26:29], v[162:165], v[186:189], v[26:29]
	v_mfma_f32_16x16x32_bf16 v[18:21], v[162:165], v[202:205], v[18:21]
	v_mfma_f32_16x16x32_bf16 v[14:17], v[170:173], v[202:205], v[14:17]
	v_mfma_f32_16x16x32_bf16 v[10:13], v[162:165], v[252:255], v[10:13]
	s_setprio 2
	s_barrier
	v_mfma_f32_16x16x32_bf16 v[4:7], v[170:173], v[252:255], v[4:7]
	s_setprio 0
	v_add_u32_e32 v3, 0x18000, v199
	ds_read_b128 v[134:137], v3
	ds_read_b128 v[138:141], v3 offset:1024
	ds_read_b128 v[142:145], v3 offset:2048
	ds_read_b128 v[146:149], v3 offset:3072
	v_add_u32_e32 v3, 0x1c000, v199
	ds_read_b128 v[158:161], v3
	ds_read_b128 v[162:165], v3 offset:1024
	ds_read_b128 v[166:169], v3 offset:2048
	ds_read_b128 v[248:251], v3 offset:3072
	ds_read_b128 v[174:177], v200 offset:32768
	ds_read_b128 v[178:181], v200 offset:33792
	ds_read_b128 v[182:185], v200 offset:34816
	ds_read_b128 v[186:189], v200 offset:35840
	ds_read_b128 v[190:193], v200 offset:36864
	ds_read_b128 v[202:205], v200 offset:37888
	ds_read_b128 v[206:209], v200 offset:38912
	ds_read_b128 v[210:213], v200 offset:39936
	s_add_u32 s42, s56, 0x100000
	s_addc_u32 s43, s57, 0
	s_mov_b32 m0, s76
	s_nop 0
	global_load_lds_dwordx4 v1, s[42:43]
	s_nop 0
	s_mov_b32 m0, s77
	s_nop 0
	global_load_lds_dwordx4 v195, s[42:43]
	s_waitcnt vmcnt(8)
	s_waitcnt lgkmcnt(0)
	s_barrier
	s_setprio 1
	s_waitcnt lgkmcnt(7)
	v_mfma_f32_16x16x32_bf16 v[130:133], v[134:137], v[174:177], v[130:133]
	v_mfma_f32_16x16x32_bf16 v[126:129], v[142:145], v[174:177], v[126:129]
	s_waitcnt lgkmcnt(5)
	v_mfma_f32_16x16x32_bf16 v[118:121], v[142:145], v[182:185], v[118:121]
	v_mfma_f32_16x16x32_bf16 v[122:125], v[134:137], v[182:185], v[122:125]
	s_waitcnt lgkmcnt(3)
	v_mfma_f32_16x16x32_bf16 v[114:117], v[134:137], v[190:193], v[114:117]
	v_mfma_f32_16x16x32_bf16 v[110:113], v[142:145], v[190:193], v[110:113]
	s_waitcnt lgkmcnt(1)
	v_mfma_f32_16x16x32_bf16 v[102:105], v[142:145], v[206:209], v[102:105]
	v_mfma_f32_16x16x32_bf16 v[106:109], v[134:137], v[206:209], v[106:109]
	v_mfma_f32_16x16x32_bf16 v[130:133], v[138:141], v[178:181], v[130:133]
	v_mfma_f32_16x16x32_bf16 v[126:129], v[146:149], v[178:181], v[126:129]
	v_mfma_f32_16x16x32_bf16 v[118:121], v[146:149], v[186:189], v[118:121]
	v_mfma_f32_16x16x32_bf16 v[122:125], v[138:141], v[186:189], v[122:125]
	v_mfma_f32_16x16x32_bf16 v[114:117], v[138:141], v[202:205], v[114:117]
	v_mfma_f32_16x16x32_bf16 v[110:113], v[146:149], v[202:205], v[110:113]
	s_waitcnt lgkmcnt(0)
	v_mfma_f32_16x16x32_bf16 v[102:105], v[146:149], v[210:213], v[102:105]
	v_mfma_f32_16x16x32_bf16 v[106:109], v[138:141], v[210:213], v[106:109]
	s_setprio 0
	s_setprio 1
	v_mfma_f32_16x16x32_bf16 v[66:69], v[158:161], v[174:177], v[66:69]
	v_mfma_f32_16x16x32_bf16 v[62:65], v[166:169], v[174:177], v[62:65]
	v_mfma_f32_16x16x32_bf16 v[54:57], v[166:169], v[182:185], v[54:57]
	v_mfma_f32_16x16x32_bf16 v[58:61], v[158:161], v[182:185], v[58:61]
	v_mfma_f32_16x16x32_bf16 v[50:53], v[158:161], v[190:193], v[50:53]
	v_mfma_f32_16x16x32_bf16 v[46:49], v[166:169], v[190:193], v[46:49]
	v_mfma_f32_16x16x32_bf16 v[38:41], v[166:169], v[206:209], v[38:41]
	v_mfma_f32_16x16x32_bf16 v[42:45], v[158:161], v[206:209], v[42:45]
	v_mfma_f32_16x16x32_bf16 v[66:69], v[162:165], v[178:181], v[66:69]
	v_mfma_f32_16x16x32_bf16 v[62:65], v[248:251], v[178:181], v[62:65]
	v_mfma_f32_16x16x32_bf16 v[54:57], v[248:251], v[186:189], v[54:57]
	v_mfma_f32_16x16x32_bf16 v[58:61], v[162:165], v[186:189], v[58:61]
	v_mfma_f32_16x16x32_bf16 v[50:53], v[162:165], v[202:205], v[50:53]
	v_mfma_f32_16x16x32_bf16 v[46:49], v[248:251], v[202:205], v[46:49]
	v_mfma_f32_16x16x32_bf16 v[42:45], v[162:165], v[210:213], v[42:45]
	s_setprio 2
	s_barrier
; #define PG8_STAGE(bufoff, gbase, voff) do { _Pragma("unroll") for (int _i = 0; _i < 2; ++_i) \
;         asm volatile("s_mov_b32 m0, %2\n\ts_nop 0\n\tglobal_load_lds_dwordx4 %0, %1" :: "v"((voff)[_i]), "s"((const char*)(gbase)), "s"(ldsbase + (unsigned)(bufoff) + ldsw + (unsigned)_i * 8192u) : "memory", "m0"); } while (0)
; #define PG8_LDA(dst, b, h) do { _Pragma("unroll") for (int m = 0; m < 4; ++m) _Pragma("unroll") for (int k = 0; k < 2; ++k) dst[m][k] = *(const PG8_LAS bf16x8*)(lds + PG8_SA(b, h) + aoff + m * 2048 + k * 1024); } while (0)
; #define PG8_MMA(ai, bj, At, Bt) do { __builtin_amdgcn_s_setprio(1); _Pragma("unroll") for (int m = 0; m < 4; ++m) _Pragma("unroll") for (int n = 0; n < 2; ++n) _Pragma("unroll") for (int k = 0; k < 2; ++k) \
;         acc[ai][bj][m][n] = __builtin_amdgcn_mfma_f32_16x16x32_bf16(Bt[n][k], At[m][k], acc[ai][bj][m][n], 0, 0, 0); __builtin_amdgcn_s_setprio(0); } while (0)
; #define PG8_WAIT_V(n) asm volatile("s_waitcnt vmcnt(" #n ")" ::: "memory")
; #define PG8_WAIT_L(n) asm volatile("s_waitcnt lgkmcnt(" #n ")" ::: "memory")
; #define PG8_BAR __builtin_amdgcn_s_barrier()
; #define PG8_SCHED __builtin_amdgcn_sched_barrier(0)
; template <class Epi, class Sched, bool ALIGN_EPI = false, bool SP2 = false>
; __device__ __forceinline__ void gemm_phase(PG8_LAS unsigned char* lds, const Gemm g, const Sched& S, const Epi& E) {
;     ...
;             PG8_LDA(At, 1, 1); PG8_STAGE(PG8_SB(1, 0), b3, voffB); PG8_STAGE(PG8_SB(1, 1), b3 + hstep, voffB); PG8_STAGE(PG8_SA(1, 0), a3, voffA);
;             PG8_WAIT_V(8); PG8_WAIT_L(0); PG8_BAR; PG8_MMA(1, 0, At, B0); PG8_MMA(1, 1, At, B1); PG8_BAR; PG8_SCHED;
	v_mfma_f32_16x16x32_bf16 v[38:41], v[248:251], v[210:213], v[38:41]
	s_setprio 0
	ds_read_b128 v[174:177], v200 offset:49152
	ds_read_b128 v[178:181], v200 offset:50176
	ds_read_b128 v[182:185], v200 offset:51200
	ds_read_b128 v[186:189], v200 offset:52224
	ds_read_b128 v[190:193], v200 offset:53248
	ds_read_b128 v[202:205], v200 offset:54272
	ds_read_b128 v[206:209], v200 offset:55296
	ds_read_b128 v[252:255], v200 offset:56320
	s_mov_b32 m0, s78
	s_nop 0
	global_load_lds_dwordx4 v194, s[54:55]
	s_add_u32 s42, s46, 0x100080
	s_mov_b32 m0, s79
	s_nop 0
	global_load_lds_dwordx4 v196, s[54:55]
	s_addc_u32 s43, s47, 0
	s_mov_b32 m0, s83
	s_nop 0
	global_load_lds_dwordx4 v194, s[42:43]
	s_nop 0
	s_mov_b32 m0, s84
	s_nop 0
	global_load_lds_dwordx4 v196, s[42:43]
	s_nop 0
	s_mov_b32 m0, s80
	s_nop 0
	global_load_lds_dwordx4 v1, s[50:51]
	s_nop 0
	s_mov_b32 m0, s82
	s_nop 0
	global_load_lds_dwordx4 v195, s[50:51]
	s_waitcnt vmcnt(8)
	s_waitcnt lgkmcnt(0)
	s_barrier
	s_setprio 1
	s_waitcnt lgkmcnt(7)
	v_mfma_f32_16x16x32_bf16 v[98:101], v[134:137], v[174:177], v[98:101]
	v_mfma_f32_16x16x32_bf16 v[94:97], v[142:145], v[174:177], v[94:97]
	s_waitcnt lgkmcnt(5)
	v_mfma_f32_16x16x32_bf16 v[86:89], v[142:145], v[182:185], v[86:89]
	v_mfma_f32_16x16x32_bf16 v[90:93], v[134:137], v[182:185], v[90:93]
	s_waitcnt lgkmcnt(3)
	v_mfma_f32_16x16x32_bf16 v[82:85], v[134:137], v[190:193], v[82:85]
	v_mfma_f32_16x16x32_bf16 v[78:81], v[142:145], v[190:193], v[78:81]
	s_waitcnt lgkmcnt(1)
	v_mfma_f32_16x16x32_bf16 v[70:73], v[142:145], v[206:209], v[70:73]
	v_mfma_f32_16x16x32_bf16 v[74:77], v[134:137], v[206:209], v[74:77]
	v_mfma_f32_16x16x32_bf16 v[98:101], v[138:141], v[178:181], v[98:101]
	v_mfma_f32_16x16x32_bf16 v[94:97], v[146:149], v[178:181], v[94:97]
	v_mfma_f32_16x16x32_bf16 v[86:89], v[146:149], v[186:189], v[86:89]
	v_mfma_f32_16x16x32_bf16 v[90:93], v[138:141], v[186:189], v[90:93]
	v_mfma_f32_16x16x32_bf16 v[82:85], v[138:141], v[202:205], v[82:85]
	v_mfma_f32_16x16x32_bf16 v[78:81], v[146:149], v[202:205], v[78:81]
	s_waitcnt lgkmcnt(0)
	v_mfma_f32_16x16x32_bf16 v[70:73], v[146:149], v[252:255], v[70:73]
	v_mfma_f32_16x16x32_bf16 v[74:77], v[138:141], v[252:255], v[74:77]
	s_setprio 0
	s_setprio 1
	v_mfma_f32_16x16x32_bf16 v[34:37], v[158:161], v[174:177], v[34:37]
	v_mfma_f32_16x16x32_bf16 v[30:33], v[166:169], v[174:177], v[30:33]
	v_mfma_f32_16x16x32_bf16 v[22:25], v[166:169], v[182:185], v[22:25]
	v_mfma_f32_16x16x32_bf16 v[26:29], v[158:161], v[182:185], v[26:29]
	v_mfma_f32_16x16x32_bf16 v[18:21], v[158:161], v[190:193], v[18:21]
	v_mfma_f32_16x16x32_bf16 v[14:17], v[166:169], v[190:193], v[14:17]
	v_mfma_f32_16x16x32_bf16 v[4:7], v[166:169], v[206:209], v[4:7]
	v_mfma_f32_16x16x32_bf16 v[8:11], v[158:161], v[206:209], v[10:13]
	v_mfma_f32_16x16x32_bf16 v[34:37], v[162:165], v[178:181], v[34:37]
	v_mfma_f32_16x16x32_bf16 v[30:33], v[248:251], v[178:181], v[30:33]
	v_mfma_f32_16x16x32_bf16 v[22:25], v[248:251], v[186:189], v[22:25]
	v_mfma_f32_16x16x32_bf16 v[26:29], v[162:165], v[186:189], v[26:29]
	v_mfma_f32_16x16x32_bf16 v[18:21], v[162:165], v[202:205], v[18:21]
	v_mfma_f32_16x16x32_bf16 v[14:17], v[248:251], v[202:205], v[14:17]
	v_mfma_f32_16x16x32_bf16 v[10:13], v[162:165], v[252:255], v[8:11]
	s_setprio 2
	s_barrier
	v_mfma_f32_16x16x32_bf16 v[6:9], v[248:251], v[252:255], v[4:7]
	s_setprio 0
	s_add_i32 s92, s92, 2
	s_add_u32 s90, s90, 0x100
	s_addc_u32 s91, s91, 0
	s_cmp_gt_u32 s92, 61
	s_cbranch_scc1 .LBB0_622
	s_mov_b64 s[42:43], s[44:45]
	s_cmp_lg_u32 s92, 30
	s_cbranch_scc0 .LBB0_619
	s_branch .LBB0_620

; #define PG8_STAGE(bufoff, gbase, voff) do { _Pragma("unroll") for (int _i = 0; _i < 2; ++_i) \
;         asm volatile("s_mov_b32 m0, %2\n\ts_nop 0\n\tglobal_load_lds_dwordx4 %0, %1" :: "v"((voff)[_i]), "s"((const char*)(gbase)), "s"(ldsbase + (unsigned)(bufoff) + ldsw + (unsigned)_i * 8192u) : "memory", "m0"); } while (0)
; #define PG8_LDA(dst, b, h) do { _Pragma("unroll") for (int m = 0; m < 4; ++m) _Pragma("unroll") for (int k = 0; k < 2; ++k) dst[m][k] = *(const PG8_LAS bf16x8*)(lds + PG8_SA(b, h) + aoff + m * 2048 + k * 1024); } while (0)
; #define PG8_LDB(dst, b, h) do { _Pragma("unroll") for (int n = 0; n < 2; ++n) _Pragma("unroll") for (int k = 0; k < 2; ++k) dst[n][k] = *(const PG8_LAS bf16x8*)(lds + PG8_SB(b, h) + boff + n * 2048 + k * 1024); } while (0)
; #define PG8_MMA(ai, bj, At, Bt) do { __builtin_amdgcn_s_setprio(1); _Pragma("unroll") for (int m = 0; m < 4; ++m) _Pragma("unroll") for (int n = 0; n < 2; ++n) _Pragma("unroll") for (int k = 0; k < 2; ++k) \
;         acc[ai][bj][m][n] = __builtin_amdgcn_mfma_f32_16x16x32_bf16(Bt[n][k], At[m][k], acc[ai][bj][m][n], 0, 0, 0); __builtin_amdgcn_s_setprio(0); } while (0)
; template <class Epi, class Sched, bool ALIGN_EPI = false, bool SP2 = false>
; __device__ __forceinline__ void gemm_phase(PG8_LAS unsigned char* lds, const Gemm g, const Sched& S, const Epi& E) {
;     ...
;             const bool last = (t == nt - 2);
;             const char* a1 = cA + (size_t)(t + 1) * kstep;
;             const char* a2 = last ? nA : cA + (size_t)(t + 2) * kstep; const char* b2 = last ? nB : cB + (size_t)(t + 2) * kstep;
;             const char* a3 = a2 + kstep; const char* b3 = b2 + kstep;
;             if (last && has_next) S.a_ready(nxt);
;             if constexpr (epi_has_mid<Epi>::value) { if (t == Epi::MID_T) E.mid(acc, cur, wr, wc, fr, fq); }
;             if constexpr (SP2) {
;             PG8_LDB(B0, 0, 0); PG8_LDB(B1, 0, 1); PG8_SCHED; PG8_LDA(At, 0, 0); PG8_STAGE(PG8_SA(1, 1), a1 + hstep, voffA);
;             PG8_WAIT_V(8); PG8_WAIT_L(0); PG8_BAR; PG8_MMA(0, 0, At, B0); PG8_MMA(0, 1, At, B1); PG8_BAR; PG8_SCHED;
;             PG8_LDA(At, 0, 1); PG8_STAGE(PG8_SB(0, 0), b2, voffB); PG8_STAGE(PG8_SB(0, 1), b2 + hstep, voffB); PG8_STAGE(PG8_SA(0, 0), a2, voffA);
;             PG8_WAIT_V(8); PG8_WAIT_L(0); PG8_BAR; PG8_MMA(1, 0, At, B0); PG8_MMA(1, 1, At, B1); PG8_BAR; PG8_SCHED;
.LBB0_698:
	ds_read_b128 v[134:137], v145
	ds_read_b128 v[152:155], v145 offset:1024
	ds_read_b128 v[156:159], v145 offset:2048
	ds_read_b128 v[160:163], v145 offset:3072
	ds_read_b128 v[164:167], v146
	ds_read_b128 v[168:171], v146 offset:1024
	ds_read_b128 v[172:175], v146 offset:2048
	ds_read_b128 v[176:179], v146 offset:3072
	s_cmp_eq_u32 s69, 60
	s_cselect_b32 s48, s41, s53
	s_cselect_b32 s49, s19, s58
	s_cselect_b32 s46, s52, s59
	s_cselect_b32 s47, s17, s68
	s_add_u32 s44, s48, 0x80
	s_addc_u32 s45, s49, 0
	ds_read_b128 v[180:183], v147
	ds_read_b128 v[184:187], v147 offset:1024
	ds_read_b128 v[188:191], v147 offset:2048
	ds_read_b128 v[192:195], v147 offset:3072
	ds_read_b128 v[196:199], v147 offset:4096
	ds_read_b128 v[200:203], v147 offset:5120
	ds_read_b128 v[204:207], v147 offset:6144
	ds_read_b128 v[208:211], v147 offset:7168
	s_mov_b32 m0, s67
	s_nop 0
	global_load_lds_dwordx4 v1, s[42:43]
	s_nop 0
	s_mov_b32 m0, s74
	s_nop 0
	global_load_lds_dwordx4 v141, s[42:43]
	s_waitcnt vmcnt(8)
	s_waitcnt lgkmcnt(0)
	s_barrier
	s_setprio 1
	s_waitcnt lgkmcnt(7)
	v_mfma_f32_16x16x32_bf16 v[126:129], v[134:137], v[180:183], v[126:129]
	v_mfma_f32_16x16x32_bf16 v[122:125], v[156:159], v[180:183], v[122:125]
	s_waitcnt lgkmcnt(5)
	v_mfma_f32_16x16x32_bf16 v[106:109], v[156:159], v[188:191], v[106:109]
	v_mfma_f32_16x16x32_bf16 v[110:113], v[134:137], v[188:191], v[110:113]
	s_waitcnt lgkmcnt(3)
	v_mfma_f32_16x16x32_bf16 v[94:97], v[134:137], v[196:199], v[94:97]
	v_mfma_f32_16x16x32_bf16 v[90:93], v[156:159], v[196:199], v[90:93]
	s_waitcnt lgkmcnt(1)
	v_mfma_f32_16x16x32_bf16 v[74:77], v[156:159], v[204:207], v[74:77]
	v_mfma_f32_16x16x32_bf16 v[78:81], v[134:137], v[204:207], v[78:81]
	v_mfma_f32_16x16x32_bf16 v[126:129], v[152:155], v[184:187], v[126:129]
	v_mfma_f32_16x16x32_bf16 v[122:125], v[160:163], v[184:187], v[122:125]
	v_mfma_f32_16x16x32_bf16 v[106:109], v[160:163], v[192:195], v[106:109]
	v_mfma_f32_16x16x32_bf16 v[110:113], v[152:155], v[192:195], v[110:113]
	v_mfma_f32_16x16x32_bf16 v[94:97], v[152:155], v[200:203], v[94:97]
	v_mfma_f32_16x16x32_bf16 v[90:93], v[160:163], v[200:203], v[90:93]
	s_waitcnt lgkmcnt(0)
	v_mfma_f32_16x16x32_bf16 v[74:77], v[160:163], v[208:211], v[74:77]
	v_mfma_f32_16x16x32_bf16 v[78:81], v[152:155], v[208:211], v[78:81]
	s_setprio 0
	s_setprio 1
	v_mfma_f32_16x16x32_bf16 v[118:121], v[164:167], v[180:183], v[118:121]
	v_mfma_f32_16x16x32_bf16 v[114:117], v[172:175], v[180:183], v[114:117]
	v_mfma_f32_16x16x32_bf16 v[98:101], v[172:175], v[188:191], v[98:101]
	v_mfma_f32_16x16x32_bf16 v[102:105], v[164:167], v[188:191], v[102:105]
	v_mfma_f32_16x16x32_bf16 v[86:89], v[164:167], v[196:199], v[86:89]
	v_mfma_f32_16x16x32_bf16 v[82:85], v[172:175], v[196:199], v[82:85]
	v_mfma_f32_16x16x32_bf16 v[66:69], v[172:175], v[204:207], v[66:69]
	v_mfma_f32_16x16x32_bf16 v[70:73], v[164:167], v[204:207], v[70:73]
	v_mfma_f32_16x16x32_bf16 v[118:121], v[168:171], v[184:187], v[118:121]
	v_mfma_f32_16x16x32_bf16 v[114:117], v[176:179], v[184:187], v[114:117]
	v_mfma_f32_16x16x32_bf16 v[98:101], v[176:179], v[192:195], v[98:101]
	v_mfma_f32_16x16x32_bf16 v[102:105], v[168:171], v[192:195], v[102:105]
	v_mfma_f32_16x16x32_bf16 v[86:89], v[168:171], v[200:203], v[86:89]
	v_mfma_f32_16x16x32_bf16 v[82:85], v[176:179], v[200:203], v[82:85]
	v_mfma_f32_16x16x32_bf16 v[70:73], v[168:171], v[208:211], v[70:73]
	s_setprio 2
	s_barrier
	v_mfma_f32_16x16x32_bf16 v[66:69], v[176:179], v[208:211], v[66:69]
	s_setprio 0
	ds_read_b128 v[180:183], v147 offset:16384
	ds_read_b128 v[184:187], v147 offset:17408
	ds_read_b128 v[188:191], v147 offset:18432
	ds_read_b128 v[192:195], v147 offset:19456
	ds_read_b128 v[196:199], v147 offset:20480
	ds_read_b128 v[200:203], v147 offset:21504
	ds_read_b128 v[204:207], v147 offset:22528
	ds_read_b128 v[252:255], v147 offset:23552
	s_mov_b32 m0, s35
	s_nop 0
	global_load_lds_dwordx4 v140, s[46:47]
	s_add_u32 s70, s46, 0x100000
	s_mov_b32 m0, s50
	s_nop 0
	global_load_lds_dwordx4 v142, s[46:47]
	s_addc_u32 s71, s47, 0
	s_mov_b32 m0, s51
	s_nop 0
	global_load_lds_dwordx4 v140, s[70:71]
	s_nop 0
	s_mov_b32 m0, s54
	s_nop 0
	global_load_lds_dwordx4 v142, s[70:71]
	s_nop 0
	s_mov_b32 m0, s3
	s_nop 0
	global_load_lds_dwordx4 v1, s[48:49]
	s_nop 0
	s_mov_b32 m0, s55
	s_nop 0
	global_load_lds_dwordx4 v141, s[48:49]
	s_waitcnt vmcnt(8)
	s_waitcnt lgkmcnt(0)
	s_barrier
	s_setprio 1
	s_waitcnt lgkmcnt(7)
	v_mfma_f32_16x16x32_bf16 v[62:65], v[134:137], v[180:183], v[62:65]
	v_mfma_f32_16x16x32_bf16 v[58:61], v[156:159], v[180:183], v[58:61]
	s_waitcnt lgkmcnt(5)
	v_mfma_f32_16x16x32_bf16 v[42:45], v[156:159], v[188:191], v[42:45]
	v_mfma_f32_16x16x32_bf16 v[46:49], v[134:137], v[188:191], v[46:49]
	s_waitcnt lgkmcnt(3)
	v_mfma_f32_16x16x32_bf16 v[30:33], v[134:137], v[196:199], v[30:33]
	v_mfma_f32_16x16x32_bf16 v[26:29], v[156:159], v[196:199], v[26:29]
	s_waitcnt lgkmcnt(1)
	v_mfma_f32_16x16x32_bf16 v[10:13], v[156:159], v[204:207], v[10:13]
	v_mfma_f32_16x16x32_bf16 v[14:17], v[134:137], v[204:207], v[14:17]
	v_mfma_f32_16x16x32_bf16 v[62:65], v[152:155], v[184:187], v[62:65]
	v_mfma_f32_16x16x32_bf16 v[58:61], v[160:163], v[184:187], v[58:61]
	v_mfma_f32_16x16x32_bf16 v[42:45], v[160:163], v[192:195], v[42:45]
	v_mfma_f32_16x16x32_bf16 v[46:49], v[152:155], v[192:195], v[46:49]
	v_mfma_f32_16x16x32_bf16 v[30:33], v[152:155], v[200:203], v[30:33]
	v_mfma_f32_16x16x32_bf16 v[26:29], v[160:163], v[200:203], v[26:29]
	s_waitcnt lgkmcnt(0)
	v_mfma_f32_16x16x32_bf16 v[10:13], v[160:163], v[252:255], v[10:13]
	v_mfma_f32_16x16x32_bf16 v[14:17], v[152:155], v[252:255], v[14:17]
	s_setprio 0
	s_setprio 1
	v_mfma_f32_16x16x32_bf16 v[54:57], v[164:167], v[180:183], v[54:57]
	v_mfma_f32_16x16x32_bf16 v[50:53], v[172:175], v[180:183], v[50:53]
	v_mfma_f32_16x16x32_bf16 v[34:37], v[172:175], v[188:191], v[34:37]
	v_mfma_f32_16x16x32_bf16 v[38:41], v[164:167], v[188:191], v[38:41]
	v_mfma_f32_16x16x32_bf16 v[22:25], v[164:167], v[196:199], v[22:25]
	v_mfma_f32_16x16x32_bf16 v[18:21], v[172:175], v[196:199], v[18:21]
	v_mfma_f32_16x16x32_bf16 v[2:5], v[172:175], v[204:207], v[2:5]
	v_mfma_f32_16x16x32_bf16 v[6:9], v[164:167], v[204:207], v[6:9]
	v_mfma_f32_16x16x32_bf16 v[54:57], v[168:171], v[184:187], v[54:57]
	v_mfma_f32_16x16x32_bf16 v[50:53], v[176:179], v[184:187], v[50:53]
	v_mfma_f32_16x16x32_bf16 v[34:37], v[176:179], v[192:195], v[34:37]
	v_mfma_f32_16x16x32_bf16 v[38:41], v[168:171], v[192:195], v[38:41]
	v_mfma_f32_16x16x32_bf16 v[22:25], v[168:171], v[200:203], v[22:25]
	v_mfma_f32_16x16x32_bf16 v[18:21], v[176:179], v[200:203], v[18:21]
	v_mfma_f32_16x16x32_bf16 v[6:9], v[168:171], v[252:255], v[6:9]
	s_setprio 2
	s_barrier
; #define PG8_STAGE(bufoff, gbase, voff) do { _Pragma("unroll") for (int _i = 0; _i < 2; ++_i) \
;         asm volatile("s_mov_b32 m0, %2\n\ts_nop 0\n\tglobal_load_lds_dwordx4 %0, %1" :: "v"((voff)[_i]), "s"((const char*)(gbase)), "s"(ldsbase + (unsigned)(bufoff) + ldsw + (unsigned)_i * 8192u) : "memory", "m0"); } while (0)
; #define PG8_LDA(dst, b, h) do { _Pragma("unroll") for (int m = 0; m < 4; ++m) _Pragma("unroll") for (int k = 0; k < 2; ++k) dst[m][k] = *(const PG8_LAS bf16x8*)(lds + PG8_SA(b, h) + aoff + m * 2048 + k * 1024); } while (0)
; #define PG8_LDB(dst, b, h) do { _Pragma("unroll") for (int n = 0; n < 2; ++n) _Pragma("unroll") for (int k = 0; k < 2; ++k) dst[n][k] = *(const PG8_LAS bf16x8*)(lds + PG8_SB(b, h) + boff + n * 2048 + k * 1024); } while (0)
; #define PG8_MMA(ai, bj, At, Bt) do { __builtin_amdgcn_s_setprio(1); _Pragma("unroll") for (int m = 0; m < 4; ++m) _Pragma("unroll") for (int n = 0; n < 2; ++n) _Pragma("unroll") for (int k = 0; k < 2; ++k) \
;         acc[ai][bj][m][n] = __builtin_amdgcn_mfma_f32_16x16x32_bf16(Bt[n][k], At[m][k], acc[ai][bj][m][n], 0, 0, 0); __builtin_amdgcn_s_setprio(0); } while (0)
; #define PG8_WAIT_V(n) asm volatile("s_waitcnt vmcnt(" #n ")" ::: "memory")
; #define PG8_WAIT_L(n) asm volatile("s_waitcnt lgkmcnt(" #n ")" ::: "memory")
; #define PG8_BAR __builtin_amdgcn_s_barrier()
; #define PG8_SCHED __builtin_amdgcn_sched_barrier(0)
; template <class Epi, class Sched, bool ALIGN_EPI = false, bool SP2 = false>
; __device__ __forceinline__ void gemm_phase(PG8_LAS unsigned char* lds, const Gemm g, const Sched& S, const Epi& E) {
;     ...
;             PG8_WAIT_V(8); PG8_WAIT_L(0); PG8_BAR; PG8_MMA(1, 0, At, B0); PG8_MMA(1, 1, At, B1); PG8_BAR; PG8_SCHED;
;             PG8_LDB(B0, 1, 0); PG8_LDB(B1, 1, 1); PG8_SCHED; PG8_LDA(At, 1, 0); PG8_STAGE(PG8_SA(0, 1), a2 + hstep, voffA);
;             PG8_WAIT_V(8); PG8_WAIT_L(0); PG8_BAR; PG8_MMA(0, 0, At, B0); PG8_MMA(0, 1, At, B1); PG8_BAR; PG8_SCHED;
	v_mfma_f32_16x16x32_bf16 v[2:5], v[176:179], v[252:255], v[2:5]
	s_setprio 0
	ds_read_b128 v[134:137], v148
	ds_read_b128 v[152:155], v148 offset:1024
	ds_read_b128 v[156:159], v148 offset:2048
	ds_read_b128 v[160:163], v148 offset:3072
	ds_read_b128 v[164:167], v149
	ds_read_b128 v[168:171], v149 offset:1024
	ds_read_b128 v[172:175], v149 offset:2048
	ds_read_b128 v[248:251], v149 offset:3072
	ds_read_b128 v[180:183], v147 offset:32768
	ds_read_b128 v[184:187], v147 offset:33792
	ds_read_b128 v[188:191], v147 offset:34816
	ds_read_b128 v[192:195], v147 offset:35840
	ds_read_b128 v[196:199], v147 offset:36864
	ds_read_b128 v[200:203], v147 offset:37888
	ds_read_b128 v[204:207], v147 offset:38912
	ds_read_b128 v[208:211], v147 offset:39936
	s_add_u32 s48, s48, 0x100000
	s_addc_u32 s49, s49, 0
	s_mov_b32 m0, s56
	s_nop 0
	global_load_lds_dwordx4 v1, s[48:49]
	s_nop 0
	s_mov_b32 m0, s57
	s_nop 0
	global_load_lds_dwordx4 v141, s[48:49]
	s_waitcnt vmcnt(8)
	s_waitcnt lgkmcnt(0)
	s_barrier
	s_setprio 1
	s_waitcnt lgkmcnt(7)
	v_mfma_f32_16x16x32_bf16 v[126:129], v[134:137], v[180:183], v[126:129]
	v_mfma_f32_16x16x32_bf16 v[122:125], v[156:159], v[180:183], v[122:125]
	s_waitcnt lgkmcnt(5)
	v_mfma_f32_16x16x32_bf16 v[106:109], v[156:159], v[188:191], v[106:109]
	v_mfma_f32_16x16x32_bf16 v[110:113], v[134:137], v[188:191], v[110:113]
	s_waitcnt lgkmcnt(3)
	v_mfma_f32_16x16x32_bf16 v[94:97], v[134:137], v[196:199], v[94:97]
	v_mfma_f32_16x16x32_bf16 v[90:93], v[156:159], v[196:199], v[90:93]
	s_waitcnt lgkmcnt(1)
	v_mfma_f32_16x16x32_bf16 v[74:77], v[156:159], v[204:207], v[74:77]
	v_mfma_f32_16x16x32_bf16 v[78:81], v[134:137], v[204:207], v[78:81]
	v_mfma_f32_16x16x32_bf16 v[126:129], v[152:155], v[184:187], v[126:129]
	v_mfma_f32_16x16x32_bf16 v[122:125], v[160:163], v[184:187], v[122:125]
	v_mfma_f32_16x16x32_bf16 v[106:109], v[160:163], v[192:195], v[106:109]
	v_mfma_f32_16x16x32_bf16 v[110:113], v[152:155], v[192:195], v[110:113]
	v_mfma_f32_16x16x32_bf16 v[94:97], v[152:155], v[200:203], v[94:97]
	v_mfma_f32_16x16x32_bf16 v[90:93], v[160:163], v[200:203], v[90:93]
	s_waitcnt lgkmcnt(0)
	v_mfma_f32_16x16x32_bf16 v[74:77], v[160:163], v[208:211], v[74:77]
	v_mfma_f32_16x16x32_bf16 v[78:81], v[152:155], v[208:211], v[78:81]
	s_setprio 0
	s_setprio 1
	v_mfma_f32_16x16x32_bf16 v[118:121], v[164:167], v[180:183], v[118:121]
	v_mfma_f32_16x16x32_bf16 v[114:117], v[172:175], v[180:183], v[114:117]
	v_mfma_f32_16x16x32_bf16 v[98:101], v[172:175], v[188:191], v[98:101]
	v_mfma_f32_16x16x32_bf16 v[102:105], v[164:167], v[188:191], v[102:105]
	v_mfma_f32_16x16x32_bf16 v[86:89], v[164:167], v[196:199], v[86:89]
	v_mfma_f32_16x16x32_bf16 v[82:85], v[172:175], v[196:199], v[82:85]
	v_mfma_f32_16x16x32_bf16 v[66:69], v[172:175], v[204:207], v[66:69]
	v_mfma_f32_16x16x32_bf16 v[70:73], v[164:167], v[204:207], v[70:73]
	v_mfma_f32_16x16x32_bf16 v[118:121], v[168:171], v[184:187], v[118:121]
	v_mfma_f32_16x16x32_bf16 v[114:117], v[248:251], v[184:187], v[114:117]
	v_mfma_f32_16x16x32_bf16 v[98:101], v[248:251], v[192:195], v[98:101]
	v_mfma_f32_16x16x32_bf16 v[102:105], v[168:171], v[192:195], v[102:105]
	v_mfma_f32_16x16x32_bf16 v[86:89], v[168:171], v[200:203], v[86:89]
	v_mfma_f32_16x16x32_bf16 v[82:85], v[248:251], v[200:203], v[82:85]
	v_mfma_f32_16x16x32_bf16 v[70:73], v[168:171], v[208:211], v[70:73]
	s_setprio 2
	s_barrier
; #define PG8_STAGE(bufoff, gbase, voff) do { _Pragma("unroll") for (int _i = 0; _i < 2; ++_i) \
;         asm volatile("s_mov_b32 m0, %2\n\ts_nop 0\n\tglobal_load_lds_dwordx4 %0, %1" :: "v"((voff)[_i]), "s"((const char*)(gbase)), "s"(ldsbase + (unsigned)(bufoff) + ldsw + (unsigned)_i * 8192u) : "memory", "m0"); } while (0)
; #define PG8_LDA(dst, b, h) do { _Pragma("unroll") for (int m = 0; m < 4; ++m) _Pragma("unroll") for (int k = 0; k < 2; ++k) dst[m][k] = *(const PG8_LAS bf16x8*)(lds + PG8_SA(b, h) + aoff + m * 2048 + k * 1024); } while (0)
; #define PG8_MMA(ai, bj, At, Bt) do { __builtin_amdgcn_s_setprio(1); _Pragma("unroll") for (int m = 0; m < 4; ++m) _Pragma("unroll") for (int n = 0; n < 2; ++n) _Pragma("unroll") for (int k = 0; k < 2; ++k) \
;         acc[ai][bj][m][n] = __builtin_amdgcn_mfma_f32_16x16x32_bf16(Bt[n][k], At[m][k], acc[ai][bj][m][n], 0, 0, 0); __builtin_amdgcn_s_setprio(0); } while (0)
; #define PG8_WAIT_V(n) asm volatile("s_waitcnt vmcnt(" #n ")" ::: "memory")
; #define PG8_WAIT_L(n) asm volatile("s_waitcnt lgkmcnt(" #n ")" ::: "memory")
; #define PG8_BAR __builtin_amdgcn_s_barrier()
; #define PG8_SCHED __builtin_amdgcn_sched_barrier(0)
; template <class Epi, class Sched, bool ALIGN_EPI = false, bool SP2 = false>
; __device__ __forceinline__ void gemm_phase(PG8_LAS unsigned char* lds, const Gemm g, const Sched& S, const Epi& E) {
;     ...
;             PG8_LDA(At, 1, 1); PG8_STAGE(PG8_SB(1, 0), b3, voffB); PG8_STAGE(PG8_SB(1, 1), b3 + hstep, voffB); PG8_STAGE(PG8_SA(1, 0), a3, voffA);
;             PG8_WAIT_V(8); PG8_WAIT_L(0); PG8_BAR; PG8_MMA(1, 0, At, B0); PG8_MMA(1, 1, At, B1); PG8_BAR; PG8_SCHED;
;     ...
;         if constexpr (ALIGN_EPI) { if (wr == 0) PG8_BAR; }
	v_mfma_f32_16x16x32_bf16 v[66:69], v[248:251], v[208:211], v[66:69]
	s_setprio 0
	ds_read_b128 v[180:183], v147 offset:49152
	ds_read_b128 v[184:187], v147 offset:50176
	ds_read_b128 v[188:191], v147 offset:51200
	ds_read_b128 v[192:195], v147 offset:52224
	ds_read_b128 v[196:199], v147 offset:53248
	ds_read_b128 v[200:203], v147 offset:54272
	ds_read_b128 v[204:207], v147 offset:55296
	ds_read_b128 v[252:255], v147 offset:56320
	s_add_u32 s48, s46, 0x80
	s_addc_u32 s49, s47, 0
	s_mov_b32 m0, s61
	s_nop 0
	global_load_lds_dwordx4 v140, s[48:49]
	s_add_u32 s46, s46, 0x100080
	s_mov_b32 m0, s62
	s_nop 0
	global_load_lds_dwordx4 v142, s[48:49]
	s_addc_u32 s47, s47, 0
	s_mov_b32 m0, s65
	s_nop 0
	global_load_lds_dwordx4 v140, s[46:47]
	s_nop 0
	s_mov_b32 m0, s66
	s_nop 0
	global_load_lds_dwordx4 v142, s[46:47]
	s_nop 0
	s_mov_b32 m0, s63
	s_nop 0
	global_load_lds_dwordx4 v1, s[44:45]
	s_nop 0
	s_mov_b32 m0, s64
	s_nop 0
	global_load_lds_dwordx4 v141, s[44:45]
	s_waitcnt vmcnt(8)
	s_waitcnt lgkmcnt(0)
	s_barrier
	s_setprio 1
	s_waitcnt lgkmcnt(7)
	v_mfma_f32_16x16x32_bf16 v[62:65], v[134:137], v[180:183], v[62:65]
	v_mfma_f32_16x16x32_bf16 v[58:61], v[156:159], v[180:183], v[58:61]
	s_waitcnt lgkmcnt(5)
	v_mfma_f32_16x16x32_bf16 v[42:45], v[156:159], v[188:191], v[42:45]
	v_mfma_f32_16x16x32_bf16 v[46:49], v[134:137], v[188:191], v[46:49]
	s_waitcnt lgkmcnt(3)
	v_mfma_f32_16x16x32_bf16 v[30:33], v[134:137], v[196:199], v[30:33]
	v_mfma_f32_16x16x32_bf16 v[26:29], v[156:159], v[196:199], v[26:29]
	s_waitcnt lgkmcnt(1)
	v_mfma_f32_16x16x32_bf16 v[10:13], v[156:159], v[204:207], v[10:13]
	v_mfma_f32_16x16x32_bf16 v[14:17], v[134:137], v[204:207], v[14:17]
	v_mfma_f32_16x16x32_bf16 v[62:65], v[152:155], v[184:187], v[62:65]
	v_mfma_f32_16x16x32_bf16 v[58:61], v[160:163], v[184:187], v[58:61]
	v_mfma_f32_16x16x32_bf16 v[42:45], v[160:163], v[192:195], v[42:45]
	v_mfma_f32_16x16x32_bf16 v[46:49], v[152:155], v[192:195], v[46:49]
	v_mfma_f32_16x16x32_bf16 v[30:33], v[152:155], v[200:203], v[30:33]
	v_mfma_f32_16x16x32_bf16 v[26:29], v[160:163], v[200:203], v[26:29]
	s_waitcnt lgkmcnt(0)
	v_mfma_f32_16x16x32_bf16 v[10:13], v[160:163], v[252:255], v[10:13]
	v_mfma_f32_16x16x32_bf16 v[14:17], v[152:155], v[252:255], v[14:17]
	s_setprio 0
	s_setprio 1
	v_mfma_f32_16x16x32_bf16 v[54:57], v[164:167], v[180:183], v[54:57]
	v_mfma_f32_16x16x32_bf16 v[50:53], v[172:175], v[180:183], v[50:53]
	v_mfma_f32_16x16x32_bf16 v[34:37], v[172:175], v[188:191], v[34:37]
	v_mfma_f32_16x16x32_bf16 v[38:41], v[164:167], v[188:191], v[38:41]
	v_mfma_f32_16x16x32_bf16 v[22:25], v[164:167], v[196:199], v[22:25]
	v_mfma_f32_16x16x32_bf16 v[18:21], v[172:175], v[196:199], v[18:21]
	v_mfma_f32_16x16x32_bf16 v[2:5], v[172:175], v[204:207], v[2:5]
	v_mfma_f32_16x16x32_bf16 v[6:9], v[164:167], v[204:207], v[6:9]
	v_mfma_f32_16x16x32_bf16 v[54:57], v[168:171], v[184:187], v[54:57]
	v_mfma_f32_16x16x32_bf16 v[50:53], v[248:251], v[184:187], v[50:53]
	v_mfma_f32_16x16x32_bf16 v[34:37], v[248:251], v[192:195], v[34:37]
	v_mfma_f32_16x16x32_bf16 v[38:41], v[168:171], v[192:195], v[38:41]
	v_mfma_f32_16x16x32_bf16 v[22:25], v[168:171], v[200:203], v[22:25]
	v_mfma_f32_16x16x32_bf16 v[18:21], v[248:251], v[200:203], v[18:21]
	v_mfma_f32_16x16x32_bf16 v[6:9], v[168:171], v[252:255], v[6:9]
	s_setprio 2
	s_barrier
	v_mfma_f32_16x16x32_bf16 v[2:5], v[248:251], v[252:255], v[2:5]
	s_setprio 0
	s_add_i32 s69, s69, 2
	s_add_u32 s53, s53, 0x100
	s_addc_u32 s58, s58, 0
	s_add_u32 s59, s59, 0x100
	s_addc_u32 s68, s68, 0
	s_add_u32 s42, s42, 0x100
	s_addc_u32 s43, s43, 0
	s_cmp_gt_u32 s69, 61
	s_cbranch_scc0 .LBB0_698
	s_and_b64 vcc, exec, s[14:15]
	s_cbranch_vccz .LBB0_701
	s_barrier

; #define PG8_STAGE(bufoff, gbase, voff) do { _Pragma("unroll") for (int _i = 0; _i < 2; ++_i) \
;         asm volatile("s_mov_b32 m0, %2\n\ts_nop 0\n\tglobal_load_lds_dwordx4 %0, %1" :: "v"((voff)[_i]), "s"((const char*)(gbase)), "s"(ldsbase + (unsigned)(bufoff) + ldsw + (unsigned)_i * 8192u) : "memory", "m0"); } while (0)
; #define PG8_LDA(dst, b, h) do { _Pragma("unroll") for (int m = 0; m < 4; ++m) _Pragma("unroll") for (int k = 0; k < 2; ++k) dst[m][k] = *(const PG8_LAS bf16x8*)(lds + PG8_SA(b, h) + aoff + m * 2048 + k * 1024); } while (0)
; #define PG8_LDB(dst, b, h) do { _Pragma("unroll") for (int n = 0; n < 2; ++n) _Pragma("unroll") for (int k = 0; k < 2; ++k) dst[n][k] = *(const PG8_LAS bf16x8*)(lds + PG8_SB(b, h) + boff + n * 2048 + k * 1024); } while (0)
; #define PG8_MMA(ai, bj, At, Bt) do { __builtin_amdgcn_s_setprio(1); _Pragma("unroll") for (int m = 0; m < 4; ++m) _Pragma("unroll") for (int n = 0; n < 2; ++n) _Pragma("unroll") for (int k = 0; k < 2; ++k) \
;         acc[ai][bj][m][n] = __builtin_amdgcn_mfma_f32_16x16x32_bf16(Bt[n][k], At[m][k], acc[ai][bj][m][n], 0, 0, 0); __builtin_amdgcn_s_setprio(0); } while (0)
; template <class Epi, class Sched, bool ALIGN_EPI = false, bool SP2 = false>
; __device__ __forceinline__ void gemm_phase(PG8_LAS unsigned char* lds, const Gemm g, const Sched& S, const Epi& E) {
;     ...
;             const bool last = (t == nt - 2);
;             const char* a1 = cA + (size_t)(t + 1) * kstep;
;             const char* a2 = last ? nA : cA + (size_t)(t + 2) * kstep; const char* b2 = last ? nB : cB + (size_t)(t + 2) * kstep;
;             const char* a3 = a2 + kstep; const char* b3 = b2 + kstep;
;             if (last && has_next) S.a_ready(nxt);
;             if constexpr (epi_has_mid<Epi>::value) { if (t == Epi::MID_T) E.mid(acc, cur, wr, wc, fr, fq); }
;             if constexpr (SP2) {
;             PG8_LDB(B0, 0, 0); PG8_LDB(B1, 0, 1); PG8_SCHED; PG8_LDA(At, 0, 0); PG8_STAGE(PG8_SA(1, 1), a1 + hstep, voffA);
;             PG8_WAIT_V(8); PG8_WAIT_L(0); PG8_BAR; PG8_MMA(0, 0, At, B0); PG8_MMA(0, 1, At, B1); PG8_BAR; PG8_SCHED;
;             PG8_LDA(At, 0, 1); PG8_STAGE(PG8_SB(0, 0), b2, voffB); PG8_STAGE(PG8_SB(0, 1), b2 + hstep, voffB); PG8_STAGE(PG8_SA(0, 0), a2, voffA);
;             PG8_WAIT_V(8); PG8_WAIT_L(0); PG8_BAR; PG8_MMA(1, 0, At, B0); PG8_MMA(1, 1, At, B1); PG8_BAR; PG8_SCHED;
.LBB0_789:
	v_add_u32_e32 v164, 0x10000, v149
	v_add_u32_e32 v180, 0x14000, v149
	s_add_u32 s8, s40, 0x100
	s_waitcnt lgkmcnt(0)
	ds_read_b128 v[152:155], v164
	ds_read_b128 v[156:159], v164 offset:1024
	ds_read_b128 v[160:163], v164 offset:2048
	ds_read_b128 v[164:167], v164 offset:3072
	ds_read_b128 v[168:171], v180
	ds_read_b128 v[172:175], v180 offset:1024
	ds_read_b128 v[176:179], v180 offset:2048
	ds_read_b128 v[180:183], v180 offset:3072
	s_addc_u32 s9, s41, 0
	s_and_b64 s[38:39], s[38:39], exec
	s_cselect_b32 s46, s59, s8
	s_cselect_b32 s47, s17, s9
	s_cselect_b32 s39, s15, s75
	s_cselect_b32 s38, s71, s74
	s_add_u32 s42, s46, 0x80
	s_addc_u32 s43, s47, 0
	s_add_u32 s44, s38, 0x80
	s_addc_u32 s45, s39, 0
	ds_read_b128 v[184:187], v150
	ds_read_b128 v[188:191], v150 offset:1024
	ds_read_b128 v[192:195], v150 offset:2048
	ds_read_b128 v[196:199], v150 offset:3072
	ds_read_b128 v[200:203], v150 offset:4096
	ds_read_b128 v[204:207], v150 offset:5120
	ds_read_b128 v[208:211], v150 offset:6144
	ds_read_b128 v[212:215], v150 offset:7168
	s_add_u32 s40, s40, 0x100080
	s_addc_u32 s41, s41, 0
	s_mov_b32 m0, s64
	s_nop 0
	global_load_lds_dwordx4 v139, s[40:41]
	s_nop 0
	s_mov_b32 m0, s65
	s_nop 0
	global_load_lds_dwordx4 v141, s[40:41]
	s_waitcnt vmcnt(8)
	s_waitcnt lgkmcnt(0)
	s_barrier
	s_setprio 1
	s_waitcnt lgkmcnt(7)
	v_mfma_f32_16x16x32_bf16 v[126:129], v[152:155], v[184:187], v[126:129]
	v_mfma_f32_16x16x32_bf16 v[122:125], v[160:163], v[184:187], v[122:125]
	s_waitcnt lgkmcnt(5)
	v_mfma_f32_16x16x32_bf16 v[106:109], v[160:163], v[192:195], v[106:109]
	v_mfma_f32_16x16x32_bf16 v[110:113], v[152:155], v[192:195], v[110:113]
	s_waitcnt lgkmcnt(3)
	v_mfma_f32_16x16x32_bf16 v[94:97], v[152:155], v[200:203], v[94:97]
	v_mfma_f32_16x16x32_bf16 v[90:93], v[160:163], v[200:203], v[90:93]
	s_waitcnt lgkmcnt(1)
	v_mfma_f32_16x16x32_bf16 v[74:77], v[160:163], v[208:211], v[74:77]
	v_mfma_f32_16x16x32_bf16 v[78:81], v[152:155], v[208:211], v[78:81]
	v_mfma_f32_16x16x32_bf16 v[126:129], v[156:159], v[188:191], v[126:129]
	v_mfma_f32_16x16x32_bf16 v[122:125], v[164:167], v[188:191], v[122:125]
	v_mfma_f32_16x16x32_bf16 v[106:109], v[164:167], v[196:199], v[106:109]
	v_mfma_f32_16x16x32_bf16 v[110:113], v[156:159], v[196:199], v[110:113]
	v_mfma_f32_16x16x32_bf16 v[94:97], v[156:159], v[204:207], v[94:97]
	v_mfma_f32_16x16x32_bf16 v[90:93], v[164:167], v[204:207], v[90:93]
	s_waitcnt lgkmcnt(0)
	v_mfma_f32_16x16x32_bf16 v[74:77], v[164:167], v[212:215], v[74:77]
	v_mfma_f32_16x16x32_bf16 v[78:81], v[156:159], v[212:215], v[78:81]
	s_setprio 0
	s_setprio 1
	v_mfma_f32_16x16x32_bf16 v[118:121], v[168:171], v[184:187], v[118:121]
	v_mfma_f32_16x16x32_bf16 v[114:117], v[176:179], v[184:187], v[114:117]
	v_mfma_f32_16x16x32_bf16 v[98:101], v[176:179], v[192:195], v[98:101]
	v_mfma_f32_16x16x32_bf16 v[102:105], v[168:171], v[192:195], v[102:105]
	v_mfma_f32_16x16x32_bf16 v[86:89], v[168:171], v[200:203], v[86:89]
	v_mfma_f32_16x16x32_bf16 v[82:85], v[176:179], v[200:203], v[82:85]
	v_mfma_f32_16x16x32_bf16 v[66:69], v[176:179], v[208:211], v[66:69]
	v_mfma_f32_16x16x32_bf16 v[70:73], v[168:171], v[208:211], v[70:73]
	v_mfma_f32_16x16x32_bf16 v[118:121], v[172:175], v[188:191], v[118:121]
	v_mfma_f32_16x16x32_bf16 v[114:117], v[180:183], v[188:191], v[114:117]
	v_mfma_f32_16x16x32_bf16 v[98:101], v[180:183], v[196:199], v[98:101]
	v_mfma_f32_16x16x32_bf16 v[102:105], v[172:175], v[196:199], v[102:105]
	v_mfma_f32_16x16x32_bf16 v[86:89], v[172:175], v[204:207], v[86:89]
	v_mfma_f32_16x16x32_bf16 v[82:85], v[180:183], v[204:207], v[82:85]
	v_mfma_f32_16x16x32_bf16 v[70:73], v[172:175], v[212:215], v[70:73]
	s_setprio 2
	s_barrier
	v_mfma_f32_16x16x32_bf16 v[66:69], v[180:183], v[212:215], v[66:69]
	s_setprio 0
	ds_read_b128 v[184:187], v150 offset:16384
	ds_read_b128 v[188:191], v150 offset:17408
	ds_read_b128 v[192:195], v150 offset:18432
	ds_read_b128 v[196:199], v150 offset:19456
	ds_read_b128 v[200:203], v150 offset:20480
	ds_read_b128 v[204:207], v150 offset:21504
	ds_read_b128 v[208:211], v150 offset:22528
	ds_read_b128 v[252:255], v150 offset:23552
	s_mov_b32 m0, s49
	s_nop 0
	global_load_lds_dwordx4 v140, s[38:39]
	s_add_u32 s40, s38, 0x100000
	s_mov_b32 m0, s50
	s_nop 0
	global_load_lds_dwordx4 v142, s[38:39]
	s_addc_u32 s41, s39, 0
	s_mov_b32 m0, s51
	s_nop 0
	global_load_lds_dwordx4 v140, s[40:41]
	s_nop 0
	s_mov_b32 m0, s52
	s_nop 0
	global_load_lds_dwordx4 v142, s[40:41]
	s_nop 0
	s_mov_b32 m0, s37
	s_nop 0
	global_load_lds_dwordx4 v139, s[46:47]
	s_nop 0
	s_mov_b32 m0, s53
	s_nop 0
	global_load_lds_dwordx4 v141, s[46:47]
	s_waitcnt vmcnt(8)
	s_waitcnt lgkmcnt(0)
	s_barrier
; #define PG8_STAGE(bufoff, gbase, voff) do { _Pragma("unroll") for (int _i = 0; _i < 2; ++_i) \
;         asm volatile("s_mov_b32 m0, %2\n\ts_nop 0\n\tglobal_load_lds_dwordx4 %0, %1" :: "v"((voff)[_i]), "s"((const char*)(gbase)), "s"(ldsbase + (unsigned)(bufoff) + ldsw + (unsigned)_i * 8192u) : "memory", "m0"); } while (0)
; #define PG8_LDA(dst, b, h) do { _Pragma("unroll") for (int m = 0; m < 4; ++m) _Pragma("unroll") for (int k = 0; k < 2; ++k) dst[m][k] = *(const PG8_LAS bf16x8*)(lds + PG8_SA(b, h) + aoff + m * 2048 + k * 1024); } while (0)
; #define PG8_LDB(dst, b, h) do { _Pragma("unroll") for (int n = 0; n < 2; ++n) _Pragma("unroll") for (int k = 0; k < 2; ++k) dst[n][k] = *(const PG8_LAS bf16x8*)(lds + PG8_SB(b, h) + boff + n * 2048 + k * 1024); } while (0)
; #define PG8_MMA(ai, bj, At, Bt) do { __builtin_amdgcn_s_setprio(1); _Pragma("unroll") for (int m = 0; m < 4; ++m) _Pragma("unroll") for (int n = 0; n < 2; ++n) _Pragma("unroll") for (int k = 0; k < 2; ++k) \
;         acc[ai][bj][m][n] = __builtin_amdgcn_mfma_f32_16x16x32_bf16(Bt[n][k], At[m][k], acc[ai][bj][m][n], 0, 0, 0); __builtin_amdgcn_s_setprio(0); } while (0)
; #define PG8_WAIT_V(n) asm volatile("s_waitcnt vmcnt(" #n ")" ::: "memory")
; #define PG8_WAIT_L(n) asm volatile("s_waitcnt lgkmcnt(" #n ")" ::: "memory")
; #define PG8_BAR __builtin_amdgcn_s_barrier()
; #define PG8_SCHED __builtin_amdgcn_sched_barrier(0)
; template <class Epi, class Sched, bool ALIGN_EPI = false, bool SP2 = false>
; __device__ __forceinline__ void gemm_phase(PG8_LAS unsigned char* lds, const Gemm g, const Sched& S, const Epi& E) {
;     ...
;             PG8_WAIT_V(8); PG8_WAIT_L(0); PG8_BAR; PG8_MMA(1, 0, At, B0); PG8_MMA(1, 1, At, B1); PG8_BAR; PG8_SCHED;
;             PG8_LDB(B0, 1, 0); PG8_LDB(B1, 1, 1); PG8_SCHED; PG8_LDA(At, 1, 0); PG8_STAGE(PG8_SA(0, 1), a2 + hstep, voffA);
;             PG8_WAIT_V(8); PG8_WAIT_L(0); PG8_BAR; PG8_MMA(0, 0, At, B0); PG8_MMA(0, 1, At, B1); PG8_BAR; PG8_SCHED;
	s_setprio 1
	s_waitcnt lgkmcnt(7)
	v_mfma_f32_16x16x32_bf16 v[62:65], v[152:155], v[184:187], v[62:65]
	v_mfma_f32_16x16x32_bf16 v[58:61], v[160:163], v[184:187], v[58:61]
	s_waitcnt lgkmcnt(5)
	v_mfma_f32_16x16x32_bf16 v[42:45], v[160:163], v[192:195], v[42:45]
	v_mfma_f32_16x16x32_bf16 v[46:49], v[152:155], v[192:195], v[46:49]
	s_waitcnt lgkmcnt(3)
	v_mfma_f32_16x16x32_bf16 v[30:33], v[152:155], v[200:203], v[30:33]
	v_mfma_f32_16x16x32_bf16 v[26:29], v[160:163], v[200:203], v[26:29]
	s_waitcnt lgkmcnt(1)
	v_mfma_f32_16x16x32_bf16 v[10:13], v[160:163], v[208:211], v[10:13]
	v_mfma_f32_16x16x32_bf16 v[14:17], v[152:155], v[208:211], v[14:17]
	v_mfma_f32_16x16x32_bf16 v[62:65], v[156:159], v[188:191], v[62:65]
	v_mfma_f32_16x16x32_bf16 v[58:61], v[164:167], v[188:191], v[58:61]
	v_mfma_f32_16x16x32_bf16 v[42:45], v[164:167], v[196:199], v[42:45]
	v_mfma_f32_16x16x32_bf16 v[46:49], v[156:159], v[196:199], v[46:49]
	v_mfma_f32_16x16x32_bf16 v[30:33], v[156:159], v[204:207], v[30:33]
	v_mfma_f32_16x16x32_bf16 v[26:29], v[164:167], v[204:207], v[26:29]
	s_waitcnt lgkmcnt(0)
	v_mfma_f32_16x16x32_bf16 v[10:13], v[164:167], v[252:255], v[10:13]
	v_mfma_f32_16x16x32_bf16 v[14:17], v[156:159], v[252:255], v[14:17]
	s_setprio 0
	s_setprio 1
	v_mfma_f32_16x16x32_bf16 v[54:57], v[168:171], v[184:187], v[54:57]
	v_mfma_f32_16x16x32_bf16 v[50:53], v[176:179], v[184:187], v[50:53]
	v_mfma_f32_16x16x32_bf16 v[34:37], v[176:179], v[192:195], v[34:37]
	v_mfma_f32_16x16x32_bf16 v[38:41], v[168:171], v[192:195], v[38:41]
	v_mfma_f32_16x16x32_bf16 v[22:25], v[168:171], v[200:203], v[22:25]
	v_mfma_f32_16x16x32_bf16 v[18:21], v[176:179], v[200:203], v[18:21]
	v_mfma_f32_16x16x32_bf16 v[2:5], v[176:179], v[208:211], v[2:5]
	v_mfma_f32_16x16x32_bf16 v[6:9], v[168:171], v[208:211], v[6:9]
	v_mfma_f32_16x16x32_bf16 v[54:57], v[172:175], v[188:191], v[54:57]
	v_mfma_f32_16x16x32_bf16 v[50:53], v[180:183], v[188:191], v[50:53]
	v_mfma_f32_16x16x32_bf16 v[34:37], v[180:183], v[196:199], v[34:37]
	v_mfma_f32_16x16x32_bf16 v[38:41], v[172:175], v[196:199], v[38:41]
	v_mfma_f32_16x16x32_bf16 v[22:25], v[172:175], v[204:207], v[22:25]
	v_mfma_f32_16x16x32_bf16 v[18:21], v[180:183], v[204:207], v[18:21]
	v_mfma_f32_16x16x32_bf16 v[6:9], v[172:175], v[252:255], v[6:9]
	s_setprio 2
	s_barrier
	v_mfma_f32_16x16x32_bf16 v[2:5], v[180:183], v[252:255], v[2:5]
	s_setprio 0
	v_add_u32_e32 v164, 0x18000, v149
	v_add_u32_e32 v180, 0x1c000, v149
	ds_read_b128 v[152:155], v164
	ds_read_b128 v[156:159], v164 offset:1024
	ds_read_b128 v[160:163], v164 offset:2048
	ds_read_b128 v[164:167], v164 offset:3072
	ds_read_b128 v[168:171], v180
	ds_read_b128 v[172:175], v180 offset:1024
	ds_read_b128 v[176:179], v180 offset:2048
	ds_read_b128 v[248:251], v180 offset:3072
	ds_read_b128 v[184:187], v150 offset:32768
	ds_read_b128 v[188:191], v150 offset:33792
	ds_read_b128 v[192:195], v150 offset:34816
	ds_read_b128 v[196:199], v150 offset:35840
	ds_read_b128 v[200:203], v150 offset:36864
	ds_read_b128 v[204:207], v150 offset:37888
	ds_read_b128 v[208:211], v150 offset:38912
	ds_read_b128 v[212:215], v150 offset:39936
	s_add_u32 s40, s46, 0x100000
	s_addc_u32 s41, s47, 0
	s_mov_b32 m0, s54
	s_nop 0
	global_load_lds_dwordx4 v139, s[40:41]
	s_nop 0
	s_mov_b32 m0, s55
	s_nop 0
	global_load_lds_dwordx4 v141, s[40:41]
	s_waitcnt vmcnt(8)
	s_waitcnt lgkmcnt(0)
	s_barrier
	s_setprio 1
	s_waitcnt lgkmcnt(7)
	v_mfma_f32_16x16x32_bf16 v[126:129], v[152:155], v[184:187], v[126:129]
	v_mfma_f32_16x16x32_bf16 v[122:125], v[160:163], v[184:187], v[122:125]
	s_waitcnt lgkmcnt(5)
	v_mfma_f32_16x16x32_bf16 v[106:109], v[160:163], v[192:195], v[106:109]
	v_mfma_f32_16x16x32_bf16 v[110:113], v[152:155], v[192:195], v[110:113]
	s_waitcnt lgkmcnt(3)
	v_mfma_f32_16x16x32_bf16 v[94:97], v[152:155], v[200:203], v[94:97]
	v_mfma_f32_16x16x32_bf16 v[90:93], v[160:163], v[200:203], v[90:93]
	s_waitcnt lgkmcnt(1)
	v_mfma_f32_16x16x32_bf16 v[74:77], v[160:163], v[208:211], v[74:77]
	v_mfma_f32_16x16x32_bf16 v[78:81], v[152:155], v[208:211], v[78:81]
	v_mfma_f32_16x16x32_bf16 v[126:129], v[156:159], v[188:191], v[126:129]
	v_mfma_f32_16x16x32_bf16 v[122:125], v[164:167], v[188:191], v[122:125]
	v_mfma_f32_16x16x32_bf16 v[106:109], v[164:167], v[196:199], v[106:109]
	v_mfma_f32_16x16x32_bf16 v[110:113], v[156:159], v[196:199], v[110:113]
	v_mfma_f32_16x16x32_bf16 v[94:97], v[156:159], v[204:207], v[94:97]
	v_mfma_f32_16x16x32_bf16 v[90:93], v[164:167], v[204:207], v[90:93]
	s_waitcnt lgkmcnt(0)
	v_mfma_f32_16x16x32_bf16 v[74:77], v[164:167], v[212:215], v[74:77]
	v_mfma_f32_16x16x32_bf16 v[78:81], v[156:159], v[212:215], v[78:81]
	s_setprio 0
	s_setprio 1
	v_mfma_f32_16x16x32_bf16 v[118:121], v[168:171], v[184:187], v[118:121]
	v_mfma_f32_16x16x32_bf16 v[114:117], v[176:179], v[184:187], v[114:117]
	v_mfma_f32_16x16x32_bf16 v[98:101], v[176:179], v[192:195], v[98:101]
	v_mfma_f32_16x16x32_bf16 v[102:105], v[168:171], v[192:195], v[102:105]
	v_mfma_f32_16x16x32_bf16 v[86:89], v[168:171], v[200:203], v[86:89]
	v_mfma_f32_16x16x32_bf16 v[82:85], v[176:179], v[200:203], v[82:85]
	v_mfma_f32_16x16x32_bf16 v[66:69], v[176:179], v[208:211], v[66:69]
	v_mfma_f32_16x16x32_bf16 v[70:73], v[168:171], v[208:211], v[70:73]
	v_mfma_f32_16x16x32_bf16 v[118:121], v[172:175], v[188:191], v[118:121]
	v_mfma_f32_16x16x32_bf16 v[114:117], v[248:251], v[188:191], v[114:117]
	v_mfma_f32_16x16x32_bf16 v[98:101], v[248:251], v[196:199], v[98:101]
	v_mfma_f32_16x16x32_bf16 v[102:105], v[172:175], v[196:199], v[102:105]
	v_mfma_f32_16x16x32_bf16 v[86:89], v[172:175], v[204:207], v[86:89]
	v_mfma_f32_16x16x32_bf16 v[82:85], v[248:251], v[204:207], v[82:85]
	v_mfma_f32_16x16x32_bf16 v[70:73], v[172:175], v[212:215], v[70:73]
	s_setprio 2
	s_barrier
; #define PG8_STAGE(bufoff, gbase, voff) do { _Pragma("unroll") for (int _i = 0; _i < 2; ++_i) \
;         asm volatile("s_mov_b32 m0, %2\n\ts_nop 0\n\tglobal_load_lds_dwordx4 %0, %1" :: "v"((voff)[_i]), "s"((const char*)(gbase)), "s"(ldsbase + (unsigned)(bufoff) + ldsw + (unsigned)_i * 8192u) : "memory", "m0"); } while (0)
; #define PG8_LDA(dst, b, h) do { _Pragma("unroll") for (int m = 0; m < 4; ++m) _Pragma("unroll") for (int k = 0; k < 2; ++k) dst[m][k] = *(const PG8_LAS bf16x8*)(lds + PG8_SA(b, h) + aoff + m * 2048 + k * 1024); } while (0)
; #define PG8_MMA(ai, bj, At, Bt) do { __builtin_amdgcn_s_setprio(1); _Pragma("unroll") for (int m = 0; m < 4; ++m) _Pragma("unroll") for (int n = 0; n < 2; ++n) _Pragma("unroll") for (int k = 0; k < 2; ++k) \
;         acc[ai][bj][m][n] = __builtin_amdgcn_mfma_f32_16x16x32_bf16(Bt[n][k], At[m][k], acc[ai][bj][m][n], 0, 0, 0); __builtin_amdgcn_s_setprio(0); } while (0)
; #define PG8_WAIT_V(n) asm volatile("s_waitcnt vmcnt(" #n ")" ::: "memory")
; #define PG8_WAIT_L(n) asm volatile("s_waitcnt lgkmcnt(" #n ")" ::: "memory")
; #define PG8_BAR __builtin_amdgcn_s_barrier()
; #define PG8_SCHED __builtin_amdgcn_sched_barrier(0)
; template <class Epi, class Sched, bool ALIGN_EPI = false, bool SP2 = false>
; __device__ __forceinline__ void gemm_phase(PG8_LAS unsigned char* lds, const Gemm g, const Sched& S, const Epi& E) {
;     ...
;             PG8_LDA(At, 1, 1); PG8_STAGE(PG8_SB(1, 0), b3, voffB); PG8_STAGE(PG8_SB(1, 1), b3 + hstep, voffB); PG8_STAGE(PG8_SA(1, 0), a3, voffA);
;             PG8_WAIT_V(8); PG8_WAIT_L(0); PG8_BAR; PG8_MMA(1, 0, At, B0); PG8_MMA(1, 1, At, B1); PG8_BAR; PG8_SCHED;
	v_mfma_f32_16x16x32_bf16 v[66:69], v[248:251], v[212:215], v[66:69]
	s_setprio 0
	ds_read_b128 v[184:187], v150 offset:49152
	ds_read_b128 v[188:191], v150 offset:50176
	ds_read_b128 v[192:195], v150 offset:51200
	ds_read_b128 v[196:199], v150 offset:52224
	ds_read_b128 v[200:203], v150 offset:53248
	ds_read_b128 v[204:207], v150 offset:54272
	ds_read_b128 v[208:211], v150 offset:55296
	ds_read_b128 v[252:255], v150 offset:56320
	s_mov_b32 m0, s56
	s_nop 0
	global_load_lds_dwordx4 v140, s[44:45]
	s_add_u32 s38, s38, 0x100080
	s_mov_b32 m0, s57
	s_nop 0
	global_load_lds_dwordx4 v142, s[44:45]
	s_addc_u32 s39, s39, 0
	s_mov_b32 m0, s62
	s_nop 0
	global_load_lds_dwordx4 v140, s[38:39]
	s_nop 0
	s_mov_b32 m0, s63
	s_nop 0
	global_load_lds_dwordx4 v142, s[38:39]
	s_nop 0
	s_mov_b32 m0, s60
	s_nop 0
	global_load_lds_dwordx4 v139, s[42:43]
	s_nop 0
	s_mov_b32 m0, s61
	s_nop 0
	global_load_lds_dwordx4 v141, s[42:43]
	s_waitcnt vmcnt(8)
	s_waitcnt lgkmcnt(0)
	s_barrier
	s_setprio 1
	s_waitcnt lgkmcnt(7)
	v_mfma_f32_16x16x32_bf16 v[62:65], v[152:155], v[184:187], v[62:65]
	v_mfma_f32_16x16x32_bf16 v[58:61], v[160:163], v[184:187], v[58:61]
	s_waitcnt lgkmcnt(5)
	v_mfma_f32_16x16x32_bf16 v[42:45], v[160:163], v[192:195], v[42:45]
	v_mfma_f32_16x16x32_bf16 v[46:49], v[152:155], v[192:195], v[46:49]
	s_waitcnt lgkmcnt(3)
	v_mfma_f32_16x16x32_bf16 v[30:33], v[152:155], v[200:203], v[30:33]
	v_mfma_f32_16x16x32_bf16 v[26:29], v[160:163], v[200:203], v[26:29]
	s_waitcnt lgkmcnt(1)
	v_mfma_f32_16x16x32_bf16 v[10:13], v[160:163], v[208:211], v[10:13]
	v_mfma_f32_16x16x32_bf16 v[14:17], v[152:155], v[208:211], v[14:17]
	v_mfma_f32_16x16x32_bf16 v[62:65], v[156:159], v[188:191], v[62:65]
	v_mfma_f32_16x16x32_bf16 v[58:61], v[164:167], v[188:191], v[58:61]
	v_mfma_f32_16x16x32_bf16 v[42:45], v[164:167], v[196:199], v[42:45]
	v_mfma_f32_16x16x32_bf16 v[46:49], v[156:159], v[196:199], v[46:49]
	v_mfma_f32_16x16x32_bf16 v[30:33], v[156:159], v[204:207], v[30:33]
	v_mfma_f32_16x16x32_bf16 v[26:29], v[164:167], v[204:207], v[26:29]
	s_waitcnt lgkmcnt(0)
	v_mfma_f32_16x16x32_bf16 v[10:13], v[164:167], v[252:255], v[10:13]
	v_mfma_f32_16x16x32_bf16 v[14:17], v[156:159], v[252:255], v[14:17]
	s_setprio 0
	s_setprio 1
	v_mfma_f32_16x16x32_bf16 v[54:57], v[168:171], v[184:187], v[54:57]
	v_mfma_f32_16x16x32_bf16 v[50:53], v[176:179], v[184:187], v[50:53]
	v_mfma_f32_16x16x32_bf16 v[34:37], v[176:179], v[192:195], v[34:37]
	v_mfma_f32_16x16x32_bf16 v[38:41], v[168:171], v[192:195], v[38:41]
	v_mfma_f32_16x16x32_bf16 v[22:25], v[168:171], v[200:203], v[22:25]
	v_mfma_f32_16x16x32_bf16 v[18:21], v[176:179], v[200:203], v[18:21]
	v_mfma_f32_16x16x32_bf16 v[2:5], v[176:179], v[208:211], v[2:5]
	v_mfma_f32_16x16x32_bf16 v[6:9], v[168:171], v[208:211], v[6:9]
	v_mfma_f32_16x16x32_bf16 v[54:57], v[172:175], v[188:191], v[54:57]
	v_mfma_f32_16x16x32_bf16 v[50:53], v[248:251], v[188:191], v[50:53]
	v_mfma_f32_16x16x32_bf16 v[34:37], v[248:251], v[196:199], v[34:37]
	v_mfma_f32_16x16x32_bf16 v[38:41], v[172:175], v[196:199], v[38:41]
	v_mfma_f32_16x16x32_bf16 v[22:25], v[172:175], v[204:207], v[22:25]
	v_mfma_f32_16x16x32_bf16 v[18:21], v[248:251], v[204:207], v[18:21]
	v_mfma_f32_16x16x32_bf16 v[6:9], v[172:175], v[252:255], v[6:9]
	s_setprio 2
	s_barrier
	v_mfma_f32_16x16x32_bf16 v[2:5], v[248:251], v[252:255], v[2:5]
	s_setprio 0
	s_add_i32 s76, s76, 2
	s_add_u32 s74, s74, 0x100
	s_addc_u32 s75, s75, 0
	s_cmp_gt_u32 s76, 61
	s_cbranch_scc1 .LBB0_780
	s_mov_b64 s[40:41], s[8:9]
	s_branch .LBB0_784

; #define PG8_STAGE(bufoff, gbase, voff) do { _Pragma("unroll") for (int _i = 0; _i < 2; ++_i) \
;         asm volatile("s_mov_b32 m0, %2\n\ts_nop 0\n\tglobal_load_lds_dwordx4 %0, %1" :: "v"((voff)[_i]), "s"((const char*)(gbase)), "s"(ldsbase + (unsigned)(bufoff) + ldsw + (unsigned)_i * 8192u) : "memory", "m0"); } while (0)
; #define PG8_LDA(dst, b, h) do { _Pragma("unroll") for (int m = 0; m < 4; ++m) _Pragma("unroll") for (int k = 0; k < 2; ++k) dst[m][k] = *(const PG8_LAS bf16x8*)(lds + PG8_SA(b, h) + aoff + m * 2048 + k * 1024); } while (0)
; #define PG8_LDB(dst, b, h) do { _Pragma("unroll") for (int n = 0; n < 2; ++n) _Pragma("unroll") for (int k = 0; k < 2; ++k) dst[n][k] = *(const PG8_LAS bf16x8*)(lds + PG8_SB(b, h) + boff + n * 2048 + k * 1024); } while (0)
; #define PG8_MMA(ai, bj, At, Bt) do { __builtin_amdgcn_s_setprio(1); _Pragma("unroll") for (int m = 0; m < 4; ++m) _Pragma("unroll") for (int n = 0; n < 2; ++n) _Pragma("unroll") for (int k = 0; k < 2; ++k) \
;         acc[ai][bj][m][n] = __builtin_amdgcn_mfma_f32_16x16x32_bf16(Bt[n][k], At[m][k], acc[ai][bj][m][n], 0, 0, 0); __builtin_amdgcn_s_setprio(0); } while (0)
; template <class Epi, class Sched, bool ALIGN_EPI = false, bool SP2 = false>
; __device__ __forceinline__ void gemm_phase(PG8_LAS unsigned char* lds, const Gemm g, const Sched& S, const Epi& E) {
;     ...
;             const bool last = (t == nt - 2);
;             const char* a1 = cA + (size_t)(t + 1) * kstep;
;             const char* a2 = last ? nA : cA + (size_t)(t + 2) * kstep; const char* b2 = last ? nB : cB + (size_t)(t + 2) * kstep;
;             const char* a3 = a2 + kstep; const char* b3 = b2 + kstep;
;             if (last && has_next) S.a_ready(nxt);
;             if constexpr (epi_has_mid<Epi>::value) { if (t == Epi::MID_T) E.mid(acc, cur, wr, wc, fr, fq); }
;             if constexpr (SP2) {
;             PG8_LDB(B0, 0, 0); PG8_LDB(B1, 0, 1); PG8_SCHED; PG8_LDA(At, 0, 0); PG8_STAGE(PG8_SA(1, 1), a1 + hstep, voffA);
;             PG8_WAIT_V(8); PG8_WAIT_L(0); PG8_BAR; PG8_MMA(0, 0, At, B0); PG8_MMA(0, 1, At, B1); PG8_BAR; PG8_SCHED;
;             PG8_LDA(At, 0, 1); PG8_STAGE(PG8_SB(0, 0), b2, voffB); PG8_STAGE(PG8_SB(0, 1), b2 + hstep, voffB); PG8_STAGE(PG8_SA(0, 0), a2, voffA);
;             PG8_WAIT_V(8); PG8_WAIT_L(0); PG8_BAR; PG8_MMA(1, 0, At, B0); PG8_MMA(1, 1, At, B1); PG8_BAR; PG8_SCHED;
.LBB0_873:
	ds_read_b128 v[134:137], v145
	ds_read_b128 v[150:153], v145 offset:1024
	ds_read_b128 v[154:157], v145 offset:2048
	ds_read_b128 v[158:161], v145 offset:3072
	ds_read_b128 v[162:165], v146
	ds_read_b128 v[166:169], v146 offset:1024
	ds_read_b128 v[170:173], v146 offset:2048
	ds_read_b128 v[174:177], v146 offset:3072
	s_add_u32 s38, s36, 0x100
	s_addc_u32 s39, s37, 0
	s_cmpk_eq_i32 s69, 0xa8
	s_cselect_b32 s44, s4, s38
	s_cselect_b32 s45, s5, s39
	s_cselect_b32 s42, s22, s67
	s_cselect_b32 s43, s23, s68
	s_add_u32 s40, s44, 0x80
	s_addc_u32 s41, s45, 0
	ds_read_b128 v[178:181], v147
	ds_read_b128 v[182:185], v147 offset:1024
	ds_read_b128 v[186:189], v147 offset:2048
	ds_read_b128 v[190:193], v147 offset:3072
	ds_read_b128 v[194:197], v147 offset:4096
	ds_read_b128 v[198:201], v147 offset:5120
	ds_read_b128 v[202:205], v147 offset:6144
	ds_read_b128 v[206:209], v147 offset:7168
	s_add_u32 s36, s36, 0x2b0080
	s_addc_u32 s37, s37, 0
	s_mov_b32 m0, s60
	s_nop 0
	global_load_lds_dwordx4 v1, s[36:37]
	s_nop 0
	s_mov_b32 m0, s61
	s_nop 0
	global_load_lds_dwordx4 v141, s[36:37]
	s_waitcnt vmcnt(8)
	s_waitcnt lgkmcnt(0)
	s_barrier
	s_setprio 1
	s_waitcnt lgkmcnt(7)
	v_mfma_f32_16x16x32_bf16 v[126:129], v[134:137], v[178:181], v[126:129]
	v_mfma_f32_16x16x32_bf16 v[122:125], v[154:157], v[178:181], v[122:125]
	s_waitcnt lgkmcnt(5)
	v_mfma_f32_16x16x32_bf16 v[106:109], v[154:157], v[186:189], v[106:109]
	v_mfma_f32_16x16x32_bf16 v[110:113], v[134:137], v[186:189], v[110:113]
	s_waitcnt lgkmcnt(3)
	v_mfma_f32_16x16x32_bf16 v[94:97], v[134:137], v[194:197], v[94:97]
	v_mfma_f32_16x16x32_bf16 v[90:93], v[154:157], v[194:197], v[90:93]
	s_waitcnt lgkmcnt(1)
	v_mfma_f32_16x16x32_bf16 v[74:77], v[154:157], v[202:205], v[74:77]
	v_mfma_f32_16x16x32_bf16 v[78:81], v[134:137], v[202:205], v[78:81]
	v_mfma_f32_16x16x32_bf16 v[126:129], v[150:153], v[182:185], v[126:129]
	v_mfma_f32_16x16x32_bf16 v[122:125], v[158:161], v[182:185], v[122:125]
	v_mfma_f32_16x16x32_bf16 v[106:109], v[158:161], v[190:193], v[106:109]
	v_mfma_f32_16x16x32_bf16 v[110:113], v[150:153], v[190:193], v[110:113]
	v_mfma_f32_16x16x32_bf16 v[94:97], v[150:153], v[198:201], v[94:97]
	v_mfma_f32_16x16x32_bf16 v[90:93], v[158:161], v[198:201], v[90:93]
	s_waitcnt lgkmcnt(0)
	v_mfma_f32_16x16x32_bf16 v[74:77], v[158:161], v[206:209], v[74:77]
	v_mfma_f32_16x16x32_bf16 v[78:81], v[150:153], v[206:209], v[78:81]
	s_setprio 0
	s_setprio 1
	v_mfma_f32_16x16x32_bf16 v[118:121], v[162:165], v[178:181], v[118:121]
	v_mfma_f32_16x16x32_bf16 v[114:117], v[170:173], v[178:181], v[114:117]
	v_mfma_f32_16x16x32_bf16 v[98:101], v[170:173], v[186:189], v[98:101]
	v_mfma_f32_16x16x32_bf16 v[102:105], v[162:165], v[186:189], v[102:105]
	v_mfma_f32_16x16x32_bf16 v[86:89], v[162:165], v[194:197], v[86:89]
	v_mfma_f32_16x16x32_bf16 v[82:85], v[170:173], v[194:197], v[82:85]
	v_mfma_f32_16x16x32_bf16 v[66:69], v[170:173], v[202:205], v[66:69]
	v_mfma_f32_16x16x32_bf16 v[70:73], v[162:165], v[202:205], v[70:73]
	v_mfma_f32_16x16x32_bf16 v[118:121], v[166:169], v[182:185], v[118:121]
	v_mfma_f32_16x16x32_bf16 v[114:117], v[174:177], v[182:185], v[114:117]
	v_mfma_f32_16x16x32_bf16 v[98:101], v[174:177], v[190:193], v[98:101]
	v_mfma_f32_16x16x32_bf16 v[102:105], v[166:169], v[190:193], v[102:105]
	v_mfma_f32_16x16x32_bf16 v[86:89], v[166:169], v[198:201], v[86:89]
	v_mfma_f32_16x16x32_bf16 v[82:85], v[174:177], v[198:201], v[82:85]
	v_mfma_f32_16x16x32_bf16 v[70:73], v[166:169], v[206:209], v[70:73]
	s_setprio 2
	s_barrier
	v_mfma_f32_16x16x32_bf16 v[66:69], v[174:177], v[206:209], v[66:69]
	s_setprio 0
	ds_read_b128 v[178:181], v147 offset:16384
	ds_read_b128 v[182:185], v147 offset:17408
	ds_read_b128 v[186:189], v147 offset:18432
	ds_read_b128 v[190:193], v147 offset:19456
	ds_read_b128 v[194:197], v147 offset:20480
	ds_read_b128 v[198:201], v147 offset:21504
	ds_read_b128 v[202:205], v147 offset:22528
	ds_read_b128 v[252:255], v147 offset:23552
	s_mov_b32 m0, s47
	s_nop 0
	global_load_lds_dwordx4 v140, s[42:43]
	s_add_u32 s36, s42, 0x2b0000
	s_mov_b32 m0, s48
	s_nop 0
	global_load_lds_dwordx4 v142, s[42:43]
	s_addc_u32 s37, s43, 0
	s_mov_b32 m0, s49
	s_nop 0
	global_load_lds_dwordx4 v140, s[36:37]
	s_nop 0
	s_mov_b32 m0, s50
	s_nop 0
	global_load_lds_dwordx4 v142, s[36:37]
	s_nop 0
	s_mov_b32 m0, s46
	s_nop 0
	global_load_lds_dwordx4 v1, s[44:45]
	s_nop 0
	s_mov_b32 m0, s51
	s_nop 0
	global_load_lds_dwordx4 v141, s[44:45]
	s_waitcnt vmcnt(8)
	s_waitcnt lgkmcnt(0)
	s_barrier
; #define PG8_STAGE(bufoff, gbase, voff) do { _Pragma("unroll") for (int _i = 0; _i < 2; ++_i) \
;         asm volatile("s_mov_b32 m0, %2\n\ts_nop 0\n\tglobal_load_lds_dwordx4 %0, %1" :: "v"((voff)[_i]), "s"((const char*)(gbase)), "s"(ldsbase + (unsigned)(bufoff) + ldsw + (unsigned)_i * 8192u) : "memory", "m0"); } while (0)
; #define PG8_LDA(dst, b, h) do { _Pragma("unroll") for (int m = 0; m < 4; ++m) _Pragma("unroll") for (int k = 0; k < 2; ++k) dst[m][k] = *(const PG8_LAS bf16x8*)(lds + PG8_SA(b, h) + aoff + m * 2048 + k * 1024); } while (0)
; #define PG8_LDB(dst, b, h) do { _Pragma("unroll") for (int n = 0; n < 2; ++n) _Pragma("unroll") for (int k = 0; k < 2; ++k) dst[n][k] = *(const PG8_LAS bf16x8*)(lds + PG8_SB(b, h) + boff + n * 2048 + k * 1024); } while (0)
; #define PG8_MMA(ai, bj, At, Bt) do { __builtin_amdgcn_s_setprio(1); _Pragma("unroll") for (int m = 0; m < 4; ++m) _Pragma("unroll") for (int n = 0; n < 2; ++n) _Pragma("unroll") for (int k = 0; k < 2; ++k) \
;         acc[ai][bj][m][n] = __builtin_amdgcn_mfma_f32_16x16x32_bf16(Bt[n][k], At[m][k], acc[ai][bj][m][n], 0, 0, 0); __builtin_amdgcn_s_setprio(0); } while (0)
; #define PG8_WAIT_V(n) asm volatile("s_waitcnt vmcnt(" #n ")" ::: "memory")
; #define PG8_WAIT_L(n) asm volatile("s_waitcnt lgkmcnt(" #n ")" ::: "memory")
; #define PG8_BAR __builtin_amdgcn_s_barrier()
; #define PG8_SCHED __builtin_amdgcn_sched_barrier(0)
; template <class Epi, class Sched, bool ALIGN_EPI = false, bool SP2 = false>
; __device__ __forceinline__ void gemm_phase(PG8_LAS unsigned char* lds, const Gemm g, const Sched& S, const Epi& E) {
;     ...
;             PG8_WAIT_V(8); PG8_WAIT_L(0); PG8_BAR; PG8_MMA(1, 0, At, B0); PG8_MMA(1, 1, At, B1); PG8_BAR; PG8_SCHED;
;             PG8_LDB(B0, 1, 0); PG8_LDB(B1, 1, 1); PG8_SCHED; PG8_LDA(At, 1, 0); PG8_STAGE(PG8_SA(0, 1), a2 + hstep, voffA);
;             PG8_WAIT_V(8); PG8_WAIT_L(0); PG8_BAR; PG8_MMA(0, 0, At, B0); PG8_MMA(0, 1, At, B1); PG8_BAR; PG8_SCHED;
	s_setprio 1
	s_waitcnt lgkmcnt(7)
	v_mfma_f32_16x16x32_bf16 v[62:65], v[134:137], v[178:181], v[62:65]
	v_mfma_f32_16x16x32_bf16 v[58:61], v[154:157], v[178:181], v[58:61]
	s_waitcnt lgkmcnt(5)
	v_mfma_f32_16x16x32_bf16 v[42:45], v[154:157], v[186:189], v[42:45]
	v_mfma_f32_16x16x32_bf16 v[46:49], v[134:137], v[186:189], v[46:49]
	s_waitcnt lgkmcnt(3)
	v_mfma_f32_16x16x32_bf16 v[30:33], v[134:137], v[194:197], v[30:33]
	v_mfma_f32_16x16x32_bf16 v[26:29], v[154:157], v[194:197], v[26:29]
	s_waitcnt lgkmcnt(1)
	v_mfma_f32_16x16x32_bf16 v[10:13], v[154:157], v[202:205], v[10:13]
	v_mfma_f32_16x16x32_bf16 v[14:17], v[134:137], v[202:205], v[14:17]
	v_mfma_f32_16x16x32_bf16 v[62:65], v[150:153], v[182:185], v[62:65]
	v_mfma_f32_16x16x32_bf16 v[58:61], v[158:161], v[182:185], v[58:61]
	v_mfma_f32_16x16x32_bf16 v[42:45], v[158:161], v[190:193], v[42:45]
	v_mfma_f32_16x16x32_bf16 v[46:49], v[150:153], v[190:193], v[46:49]
	v_mfma_f32_16x16x32_bf16 v[30:33], v[150:153], v[198:201], v[30:33]
	v_mfma_f32_16x16x32_bf16 v[26:29], v[158:161], v[198:201], v[26:29]
	s_waitcnt lgkmcnt(0)
	v_mfma_f32_16x16x32_bf16 v[10:13], v[158:161], v[252:255], v[10:13]
	v_mfma_f32_16x16x32_bf16 v[14:17], v[150:153], v[252:255], v[14:17]
	s_setprio 0
	s_setprio 1
	v_mfma_f32_16x16x32_bf16 v[54:57], v[162:165], v[178:181], v[54:57]
	v_mfma_f32_16x16x32_bf16 v[50:53], v[170:173], v[178:181], v[50:53]
	v_mfma_f32_16x16x32_bf16 v[34:37], v[170:173], v[186:189], v[34:37]
	v_mfma_f32_16x16x32_bf16 v[38:41], v[162:165], v[186:189], v[38:41]
	v_mfma_f32_16x16x32_bf16 v[22:25], v[162:165], v[194:197], v[22:25]
	v_mfma_f32_16x16x32_bf16 v[18:21], v[170:173], v[194:197], v[18:21]
	v_mfma_f32_16x16x32_bf16 v[2:5], v[170:173], v[202:205], v[2:5]
	v_mfma_f32_16x16x32_bf16 v[6:9], v[162:165], v[202:205], v[6:9]
	v_mfma_f32_16x16x32_bf16 v[54:57], v[166:169], v[182:185], v[54:57]
	v_mfma_f32_16x16x32_bf16 v[50:53], v[174:177], v[182:185], v[50:53]
	v_mfma_f32_16x16x32_bf16 v[34:37], v[174:177], v[190:193], v[34:37]
	v_mfma_f32_16x16x32_bf16 v[38:41], v[166:169], v[190:193], v[38:41]
	v_mfma_f32_16x16x32_bf16 v[22:25], v[166:169], v[198:201], v[22:25]
	v_mfma_f32_16x16x32_bf16 v[18:21], v[174:177], v[198:201], v[18:21]
	v_mfma_f32_16x16x32_bf16 v[6:9], v[166:169], v[252:255], v[6:9]
	s_setprio 2
	s_barrier
	v_mfma_f32_16x16x32_bf16 v[2:5], v[174:177], v[252:255], v[2:5]
	s_setprio 0
	ds_read_b128 v[134:137], v148
	ds_read_b128 v[150:153], v148 offset:1024
	ds_read_b128 v[154:157], v148 offset:2048
	ds_read_b128 v[158:161], v148 offset:3072
	ds_read_b128 v[162:165], v149
	ds_read_b128 v[166:169], v149 offset:1024
	ds_read_b128 v[170:173], v149 offset:2048
	ds_read_b128 v[248:251], v149 offset:3072
	ds_read_b128 v[178:181], v147 offset:32768
	ds_read_b128 v[182:185], v147 offset:33792
	ds_read_b128 v[186:189], v147 offset:34816
	ds_read_b128 v[190:193], v147 offset:35840
	ds_read_b128 v[194:197], v147 offset:36864
	ds_read_b128 v[198:201], v147 offset:37888
	ds_read_b128 v[202:205], v147 offset:38912
	ds_read_b128 v[206:209], v147 offset:39936
	s_add_u32 s36, s44, 0x2b0000
	s_addc_u32 s37, s45, 0
	s_mov_b32 m0, s52
	s_nop 0
	global_load_lds_dwordx4 v1, s[36:37]
	s_nop 0
	s_mov_b32 m0, s53
	s_nop 0
	global_load_lds_dwordx4 v141, s[36:37]
	s_waitcnt vmcnt(8)
	s_waitcnt lgkmcnt(0)
	s_barrier
	s_setprio 1
	s_waitcnt lgkmcnt(7)
	v_mfma_f32_16x16x32_bf16 v[126:129], v[134:137], v[178:181], v[126:129]
	v_mfma_f32_16x16x32_bf16 v[122:125], v[154:157], v[178:181], v[122:125]
	s_waitcnt lgkmcnt(5)
	v_mfma_f32_16x16x32_bf16 v[106:109], v[154:157], v[186:189], v[106:109]
	v_mfma_f32_16x16x32_bf16 v[110:113], v[134:137], v[186:189], v[110:113]
	s_waitcnt lgkmcnt(3)
	v_mfma_f32_16x16x32_bf16 v[94:97], v[134:137], v[194:197], v[94:97]
	v_mfma_f32_16x16x32_bf16 v[90:93], v[154:157], v[194:197], v[90:93]
	s_waitcnt lgkmcnt(1)
	v_mfma_f32_16x16x32_bf16 v[74:77], v[154:157], v[202:205], v[74:77]
	v_mfma_f32_16x16x32_bf16 v[78:81], v[134:137], v[202:205], v[78:81]
	v_mfma_f32_16x16x32_bf16 v[126:129], v[150:153], v[182:185], v[126:129]
	v_mfma_f32_16x16x32_bf16 v[122:125], v[158:161], v[182:185], v[122:125]
	v_mfma_f32_16x16x32_bf16 v[106:109], v[158:161], v[190:193], v[106:109]
	v_mfma_f32_16x16x32_bf16 v[110:113], v[150:153], v[190:193], v[110:113]
	v_mfma_f32_16x16x32_bf16 v[94:97], v[150:153], v[198:201], v[94:97]
	v_mfma_f32_16x16x32_bf16 v[90:93], v[158:161], v[198:201], v[90:93]
	s_waitcnt lgkmcnt(0)
	v_mfma_f32_16x16x32_bf16 v[74:77], v[158:161], v[206:209], v[74:77]
	v_mfma_f32_16x16x32_bf16 v[78:81], v[150:153], v[206:209], v[78:81]
	s_setprio 0
	s_setprio 1
	v_mfma_f32_16x16x32_bf16 v[118:121], v[162:165], v[178:181], v[118:121]
	v_mfma_f32_16x16x32_bf16 v[114:117], v[170:173], v[178:181], v[114:117]
	v_mfma_f32_16x16x32_bf16 v[98:101], v[170:173], v[186:189], v[98:101]
	v_mfma_f32_16x16x32_bf16 v[102:105], v[162:165], v[186:189], v[102:105]
	v_mfma_f32_16x16x32_bf16 v[86:89], v[162:165], v[194:197], v[86:89]
	v_mfma_f32_16x16x32_bf16 v[82:85], v[170:173], v[194:197], v[82:85]
	v_mfma_f32_16x16x32_bf16 v[66:69], v[170:173], v[202:205], v[66:69]
	v_mfma_f32_16x16x32_bf16 v[70:73], v[162:165], v[202:205], v[70:73]
	v_mfma_f32_16x16x32_bf16 v[118:121], v[166:169], v[182:185], v[118:121]
	v_mfma_f32_16x16x32_bf16 v[114:117], v[248:251], v[182:185], v[114:117]
	v_mfma_f32_16x16x32_bf16 v[98:101], v[248:251], v[190:193], v[98:101]
	v_mfma_f32_16x16x32_bf16 v[102:105], v[166:169], v[190:193], v[102:105]
	v_mfma_f32_16x16x32_bf16 v[86:89], v[166:169], v[198:201], v[86:89]
	v_mfma_f32_16x16x32_bf16 v[82:85], v[248:251], v[198:201], v[82:85]
	v_mfma_f32_16x16x32_bf16 v[70:73], v[166:169], v[206:209], v[70:73]
	s_setprio 2
	s_barrier
; #define PG8_STAGE(bufoff, gbase, voff) do { _Pragma("unroll") for (int _i = 0; _i < 2; ++_i) \
;         asm volatile("s_mov_b32 m0, %2\n\ts_nop 0\n\tglobal_load_lds_dwordx4 %0, %1" :: "v"((voff)[_i]), "s"((const char*)(gbase)), "s"(ldsbase + (unsigned)(bufoff) + ldsw + (unsigned)_i * 8192u) : "memory", "m0"); } while (0)
; #define PG8_LDA(dst, b, h) do { _Pragma("unroll") for (int m = 0; m < 4; ++m) _Pragma("unroll") for (int k = 0; k < 2; ++k) dst[m][k] = *(const PG8_LAS bf16x8*)(lds + PG8_SA(b, h) + aoff + m * 2048 + k * 1024); } while (0)
; #define PG8_MMA(ai, bj, At, Bt) do { __builtin_amdgcn_s_setprio(1); _Pragma("unroll") for (int m = 0; m < 4; ++m) _Pragma("unroll") for (int n = 0; n < 2; ++n) _Pragma("unroll") for (int k = 0; k < 2; ++k) \
;         acc[ai][bj][m][n] = __builtin_amdgcn_mfma_f32_16x16x32_bf16(Bt[n][k], At[m][k], acc[ai][bj][m][n], 0, 0, 0); __builtin_amdgcn_s_setprio(0); } while (0)
; #define PG8_WAIT_V(n) asm volatile("s_waitcnt vmcnt(" #n ")" ::: "memory")
; #define PG8_WAIT_L(n) asm volatile("s_waitcnt lgkmcnt(" #n ")" ::: "memory")
; #define PG8_BAR __builtin_amdgcn_s_barrier()
; #define PG8_SCHED __builtin_amdgcn_sched_barrier(0)
; template <class Epi, class Sched, bool ALIGN_EPI = false, bool SP2 = false>
; __device__ __forceinline__ void gemm_phase(PG8_LAS unsigned char* lds, const Gemm g, const Sched& S, const Epi& E) {
;     ...
;             PG8_LDA(At, 1, 1); PG8_STAGE(PG8_SB(1, 0), b3, voffB); PG8_STAGE(PG8_SB(1, 1), b3 + hstep, voffB); PG8_STAGE(PG8_SA(1, 0), a3, voffA);
;             PG8_WAIT_V(8); PG8_WAIT_L(0); PG8_BAR; PG8_MMA(1, 0, At, B0); PG8_MMA(1, 1, At, B1); PG8_BAR; PG8_SCHED;
;     ...
;         if constexpr (ALIGN_EPI) { if (wr == 0) PG8_BAR; }
	v_mfma_f32_16x16x32_bf16 v[66:69], v[248:251], v[206:209], v[66:69]
	s_setprio 0
	ds_read_b128 v[178:181], v147 offset:49152
	ds_read_b128 v[182:185], v147 offset:50176
	ds_read_b128 v[186:189], v147 offset:51200
	ds_read_b128 v[190:193], v147 offset:52224
	ds_read_b128 v[194:197], v147 offset:53248
	ds_read_b128 v[198:201], v147 offset:54272
	ds_read_b128 v[202:205], v147 offset:55296
	ds_read_b128 v[252:255], v147 offset:56320
	s_add_u32 s36, s42, 0x80
	s_addc_u32 s37, s43, 0
	s_mov_b32 m0, s54
	s_nop 0
	global_load_lds_dwordx4 v140, s[36:37]
	s_nop 0
	s_mov_b32 m0, s55
	s_nop 0
	global_load_lds_dwordx4 v142, s[36:37]
	s_add_u32 s36, s42, 0x2b0080
	s_addc_u32 s37, s43, 0
	s_mov_b32 m0, s58
	s_nop 0
	global_load_lds_dwordx4 v140, s[36:37]
	s_nop 0
	s_mov_b32 m0, s59
	s_nop 0
	global_load_lds_dwordx4 v142, s[36:37]
	s_nop 0
	s_mov_b32 m0, s56
	s_nop 0
	global_load_lds_dwordx4 v1, s[40:41]
	s_nop 0
	s_mov_b32 m0, s57
	s_nop 0
	global_load_lds_dwordx4 v141, s[40:41]
	s_waitcnt vmcnt(8)
	s_waitcnt lgkmcnt(0)
	s_barrier
	s_setprio 1
	s_waitcnt lgkmcnt(7)
	v_mfma_f32_16x16x32_bf16 v[62:65], v[134:137], v[178:181], v[62:65]
	v_mfma_f32_16x16x32_bf16 v[58:61], v[154:157], v[178:181], v[58:61]
	s_waitcnt lgkmcnt(5)
	v_mfma_f32_16x16x32_bf16 v[42:45], v[154:157], v[186:189], v[42:45]
	v_mfma_f32_16x16x32_bf16 v[46:49], v[134:137], v[186:189], v[46:49]
	s_waitcnt lgkmcnt(3)
	v_mfma_f32_16x16x32_bf16 v[30:33], v[134:137], v[194:197], v[30:33]
	v_mfma_f32_16x16x32_bf16 v[26:29], v[154:157], v[194:197], v[26:29]
	s_waitcnt lgkmcnt(1)
	v_mfma_f32_16x16x32_bf16 v[10:13], v[154:157], v[202:205], v[10:13]
	v_mfma_f32_16x16x32_bf16 v[14:17], v[134:137], v[202:205], v[14:17]
	v_mfma_f32_16x16x32_bf16 v[62:65], v[150:153], v[182:185], v[62:65]
	v_mfma_f32_16x16x32_bf16 v[58:61], v[158:161], v[182:185], v[58:61]
	v_mfma_f32_16x16x32_bf16 v[42:45], v[158:161], v[190:193], v[42:45]
	v_mfma_f32_16x16x32_bf16 v[46:49], v[150:153], v[190:193], v[46:49]
	v_mfma_f32_16x16x32_bf16 v[30:33], v[150:153], v[198:201], v[30:33]
	v_mfma_f32_16x16x32_bf16 v[26:29], v[158:161], v[198:201], v[26:29]
	s_waitcnt lgkmcnt(0)
	v_mfma_f32_16x16x32_bf16 v[10:13], v[158:161], v[252:255], v[10:13]
	v_mfma_f32_16x16x32_bf16 v[14:17], v[150:153], v[252:255], v[14:17]
	s_setprio 0
	s_setprio 1
	v_mfma_f32_16x16x32_bf16 v[54:57], v[162:165], v[178:181], v[54:57]
	v_mfma_f32_16x16x32_bf16 v[50:53], v[170:173], v[178:181], v[50:53]
	v_mfma_f32_16x16x32_bf16 v[34:37], v[170:173], v[186:189], v[34:37]
	v_mfma_f32_16x16x32_bf16 v[38:41], v[162:165], v[186:189], v[38:41]
	v_mfma_f32_16x16x32_bf16 v[22:25], v[162:165], v[194:197], v[22:25]
	v_mfma_f32_16x16x32_bf16 v[18:21], v[170:173], v[194:197], v[18:21]
	v_mfma_f32_16x16x32_bf16 v[2:5], v[170:173], v[202:205], v[2:5]
	v_mfma_f32_16x16x32_bf16 v[6:9], v[162:165], v[202:205], v[6:9]
	v_mfma_f32_16x16x32_bf16 v[54:57], v[166:169], v[182:185], v[54:57]
	v_mfma_f32_16x16x32_bf16 v[50:53], v[248:251], v[182:185], v[50:53]
	v_mfma_f32_16x16x32_bf16 v[34:37], v[248:251], v[190:193], v[34:37]
	v_mfma_f32_16x16x32_bf16 v[38:41], v[166:169], v[190:193], v[38:41]
	v_mfma_f32_16x16x32_bf16 v[22:25], v[166:169], v[198:201], v[22:25]
	v_mfma_f32_16x16x32_bf16 v[18:21], v[248:251], v[198:201], v[18:21]
	v_mfma_f32_16x16x32_bf16 v[6:9], v[166:169], v[252:255], v[6:9]
	s_setprio 2
	s_barrier
	v_mfma_f32_16x16x32_bf16 v[2:5], v[248:251], v[252:255], v[2:5]
	s_setprio 0
	s_add_i32 s69, s69, 2
	s_add_u32 s67, s67, 0x100
	s_addc_u32 s68, s68, 0
	s_cmpk_gt_u32 s69, 0xa9
	s_mov_b64 s[36:37], s[38:39]
	s_cbranch_scc0 .LBB0_873
	s_and_b64 vcc, exec, s[10:11]
	s_cbranch_vccz .LBB0_876
	s_barrier
